# all GEMM K-loops: per-block s_setprio toggles removed; one static s_setprio 1 for waves 4-7 at kernel entry
# speedup vs baseline: 1.0027x; 1.0023x over previous
_Z3fwd4Args:
	s_load_dwordx2 s[92:93], s[0:1], 0x100
	s_load_dword s28, s[0:1], 0x110
	s_mov_b32 s86, s2
	v_readfirstlane_b32 s2, v0
	s_mov_b32 s60, s86
	s_nop 0
	v_writelane_b32 v254, s2, 0
	s_cmpk_lt_u32 s2, 0x100
	s_cbranch_scc1 .Lprio_skip
	s_setprio 1
.Lprio_skip:
	s_add_u32 s2, s0, 0x110
	s_addc_u32 s3, s1, 0
	v_writelane_b32 v254, s2, 1
	s_nop 1
	v_writelane_b32 v254, s3, 2
	s_waitcnt lgkmcnt(0)
	s_and_b32 s2, s28, 7
	s_cmp_lg_u32 s2, 0
	v_writelane_b32 v254, s60, 3
	s_cbranch_scc1 .LBB0_2
	s_ashr_i32 s3, s86, 31
	s_lshr_b32 s3, s3, 29
	s_add_i32 s3, s86, s3
	s_and_b32 s4, s3, -8
	s_ashr_i32 s2, s28, 3
	s_sub_i32 s4, s86, s4
	s_mul_i32 s2, s2, s4
	s_ashr_i32 s3, s3, 3
	s_add_i32 s60, s2, s3

.LBB0_117:
	ds_read_b128 v[130:133], v161
	ds_read_b128 v[134:137], v161 offset:1024
	ds_read_b128 v[170:173], v161 offset:2048
	ds_read_b128 v[174:177], v161 offset:3072
	ds_read_b128 v[178:181], v163
	ds_read_b128 v[182:185], v163 offset:1024
	ds_read_b128 v[186:189], v163 offset:2048
	ds_read_b128 v[190:193], v163 offset:3072
	s_add_u32 s50, s48, 0xfff80080
	s_addc_u32 s51, s49, -1
	s_cmp_eq_u32 s74, 28
	s_cselect_b32 s53, s9, s51
	s_cselect_b32 s52, s43, s50
	s_cselect_b32 s51, s41, s73
	s_cselect_b32 s50, s71, s72
	v_lshl_add_u64 v[154:155], s[48:49], 0, v[146:147]
	s_add_i32 m0, s56, 0xc000
	ds_read_b128 v[194:197], v165
	ds_read_b128 v[198:201], v165 offset:1024
	ds_read_b128 v[202:205], v165 offset:2048
	ds_read_b128 v[206:209], v165 offset:3072
	ds_read_b128 v[210:213], v165 offset:4096
	ds_read_b128 v[214:217], v165 offset:5120
	ds_read_b128 v[218:221], v165 offset:6144
	ds_read_b128 v[222:225], v165 offset:7168
	global_load_lds_dwordx4 v[154:155], off
	v_lshl_add_u64 v[154:155], s[48:49], 0, v[148:149]
	s_add_i32 m0, s56, 0xe000
	s_nop 0
	global_load_lds_dwordx4 v[154:155], off
	s_waitcnt vmcnt(8)
	s_waitcnt lgkmcnt(0)
	s_barrier
	s_waitcnt lgkmcnt(0)
	v_mfma_f32_16x16x32_bf16 v[126:129], v[130:133], v[194:197], v[126:129]
	v_mfma_f32_16x16x32_bf16 v[122:125], v[170:173], v[194:197], v[122:125]
	v_mfma_f32_16x16x32_bf16 v[118:121], v[130:133], v[202:205], v[118:121]
	v_mfma_f32_16x16x32_bf16 v[110:113], v[170:173], v[202:205], v[110:113]
	v_mfma_f32_16x16x32_bf16 v[102:105], v[130:133], v[210:213], v[102:105]
	v_mfma_f32_16x16x32_bf16 v[94:97], v[170:173], v[210:213], v[94:97]
	v_mfma_f32_16x16x32_bf16 v[86:89], v[130:133], v[218:221], v[86:89]
	v_mfma_f32_16x16x32_bf16 v[78:81], v[170:173], v[218:221], v[78:81]
	v_mfma_f32_16x16x32_bf16 v[126:129], v[134:137], v[198:201], v[126:129]
	v_mfma_f32_16x16x32_bf16 v[122:125], v[174:177], v[198:201], v[122:125]
	v_mfma_f32_16x16x32_bf16 v[118:121], v[134:137], v[206:209], v[118:121]
	v_mfma_f32_16x16x32_bf16 v[110:113], v[174:177], v[206:209], v[110:113]
	v_mfma_f32_16x16x32_bf16 v[102:105], v[134:137], v[214:217], v[102:105]
	v_mfma_f32_16x16x32_bf16 v[94:97], v[174:177], v[214:217], v[94:97]
	v_mfma_f32_16x16x32_bf16 v[86:89], v[134:137], v[222:225], v[86:89]
	v_mfma_f32_16x16x32_bf16 v[78:81], v[174:177], v[222:225], v[78:81]
	v_mfma_f32_16x16x32_bf16 v[114:117], v[178:181], v[194:197], v[114:117]
	v_mfma_f32_16x16x32_bf16 v[106:109], v[186:189], v[194:197], v[106:109]
	v_mfma_f32_16x16x32_bf16 v[98:101], v[178:181], v[202:205], v[98:101]
	v_mfma_f32_16x16x32_bf16 v[90:93], v[186:189], v[202:205], v[90:93]
	v_mfma_f32_16x16x32_bf16 v[82:85], v[178:181], v[210:213], v[82:85]
	v_mfma_f32_16x16x32_bf16 v[74:77], v[186:189], v[210:213], v[74:77]
	v_mfma_f32_16x16x32_bf16 v[70:73], v[178:181], v[218:221], v[70:73]
	v_mfma_f32_16x16x32_bf16 v[66:69], v[186:189], v[218:221], v[66:69]
	v_mfma_f32_16x16x32_bf16 v[114:117], v[182:185], v[198:201], v[114:117]
	v_mfma_f32_16x16x32_bf16 v[106:109], v[190:193], v[198:201], v[106:109]
	v_mfma_f32_16x16x32_bf16 v[98:101], v[182:185], v[206:209], v[98:101]
	v_mfma_f32_16x16x32_bf16 v[90:93], v[190:193], v[206:209], v[90:93]
	v_mfma_f32_16x16x32_bf16 v[82:85], v[182:185], v[214:217], v[82:85]
	v_mfma_f32_16x16x32_bf16 v[74:77], v[190:193], v[214:217], v[74:77]
	v_mfma_f32_16x16x32_bf16 v[70:73], v[182:185], v[222:225], v[70:73]
	v_mfma_f32_16x16x32_bf16 v[66:69], v[190:193], v[222:225], v[66:69]
	s_barrier
	s_add_i32 s75, s67, s55
	v_lshl_add_u64 v[154:155], s[50:51], 0, v[140:141]
	s_mov_b32 m0, s75
	ds_read_b128 v[194:197], v165 offset:16384
	ds_read_b128 v[198:201], v165 offset:17408
	ds_read_b128 v[202:205], v165 offset:18432
	ds_read_b128 v[206:209], v165 offset:19456
	ds_read_b128 v[210:213], v165 offset:20480
	ds_read_b128 v[214:217], v165 offset:21504
	ds_read_b128 v[218:221], v165 offset:22528
	ds_read_b128 v[222:225], v165 offset:23552
	global_load_lds_dwordx4 v[154:155], off
	s_add_i32 m0, s75, 0x2000
	s_add_u32 s76, s50, 0x80000
	v_lshl_add_u64 v[166:167], s[50:51], 0, v[144:145]
	s_addc_u32 s77, s51, 0
	s_add_i32 s75, s68, s55
	global_load_lds_dwordx4 v[166:167], off
	v_lshl_add_u64 v[226:227], s[76:77], 0, v[140:141]
	s_mov_b32 m0, s75
	v_lshl_add_u64 v[228:229], s[52:53], 0, v[142:143]
	global_load_lds_dwordx4 v[226:227], off
	v_lshl_add_u64 v[226:227], s[76:77], 0, v[144:145]
	s_add_i32 m0, s75, 0x2000
	s_nop 0
	global_load_lds_dwordx4 v[226:227], off
	v_lshl_add_u64 v[226:227], s[52:53], 0, v[138:139]
	s_mov_b32 m0, s56
	s_nop 0
	global_load_lds_dwordx4 v[226:227], off
	s_mov_b32 m0, s57
	s_nop 0
	global_load_lds_dwordx4 v[228:229], off
	s_waitcnt vmcnt(8)
	s_waitcnt lgkmcnt(0)
	s_barrier
	s_waitcnt lgkmcnt(0)
	v_mfma_f32_16x16x32_bf16 v[62:65], v[130:133], v[194:197], v[62:65]
	v_mfma_f32_16x16x32_bf16 v[58:61], v[170:173], v[194:197], v[58:61]
	v_mfma_f32_16x16x32_bf16 v[54:57], v[130:133], v[202:205], v[54:57]
	v_mfma_f32_16x16x32_bf16 v[46:49], v[170:173], v[202:205], v[46:49]
	v_mfma_f32_16x16x32_bf16 v[38:41], v[130:133], v[210:213], v[38:41]
	v_mfma_f32_16x16x32_bf16 v[30:33], v[170:173], v[210:213], v[30:33]
	v_mfma_f32_16x16x32_bf16 v[22:25], v[130:133], v[218:221], v[22:25]
	v_mfma_f32_16x16x32_bf16 v[14:17], v[170:173], v[218:221], v[14:17]
	v_mfma_f32_16x16x32_bf16 v[62:65], v[134:137], v[198:201], v[62:65]
	v_mfma_f32_16x16x32_bf16 v[58:61], v[174:177], v[198:201], v[58:61]
	v_mfma_f32_16x16x32_bf16 v[54:57], v[134:137], v[206:209], v[54:57]
	v_mfma_f32_16x16x32_bf16 v[46:49], v[174:177], v[206:209], v[46:49]
	v_mfma_f32_16x16x32_bf16 v[38:41], v[134:137], v[214:217], v[38:41]
	v_mfma_f32_16x16x32_bf16 v[30:33], v[174:177], v[214:217], v[30:33]
	v_mfma_f32_16x16x32_bf16 v[22:25], v[134:137], v[222:225], v[22:25]
	v_mfma_f32_16x16x32_bf16 v[14:17], v[174:177], v[222:225], v[14:17]
	v_mfma_f32_16x16x32_bf16 v[50:53], v[178:181], v[194:197], v[50:53]
	v_mfma_f32_16x16x32_bf16 v[42:45], v[186:189], v[194:197], v[42:45]
	v_mfma_f32_16x16x32_bf16 v[34:37], v[178:181], v[202:205], v[34:37]
	v_mfma_f32_16x16x32_bf16 v[26:29], v[186:189], v[202:205], v[26:29]
	v_mfma_f32_16x16x32_bf16 v[18:21], v[178:181], v[210:213], v[18:21]
	v_mfma_f32_16x16x32_bf16 v[10:13], v[186:189], v[210:213], v[10:13]
	v_mfma_f32_16x16x32_bf16 v[6:9], v[178:181], v[218:221], v[6:9]
	v_mfma_f32_16x16x32_bf16 v[2:5], v[186:189], v[218:221], v[2:5]
	v_mfma_f32_16x16x32_bf16 v[50:53], v[182:185], v[198:201], v[50:53]
	v_mfma_f32_16x16x32_bf16 v[42:45], v[190:193], v[198:201], v[42:45]
	v_mfma_f32_16x16x32_bf16 v[34:37], v[182:185], v[206:209], v[34:37]
	v_mfma_f32_16x16x32_bf16 v[26:29], v[190:193], v[206:209], v[26:29]
	v_mfma_f32_16x16x32_bf16 v[18:21], v[182:185], v[214:217], v[18:21]
	v_mfma_f32_16x16x32_bf16 v[10:13], v[190:193], v[214:217], v[10:13]
	v_mfma_f32_16x16x32_bf16 v[6:9], v[182:185], v[222:225], v[6:9]
	v_mfma_f32_16x16x32_bf16 v[2:5], v[190:193], v[222:225], v[2:5]
	s_barrier
	s_add_i32 s75, 0, 0x18000
	v_add_u32_e32 v156, s75, v159
	s_add_i32 s76, 0, 0x1c000
	ds_read_b128 v[130:133], v156
	ds_read_b128 v[134:137], v156 offset:1024
	ds_read_b128 v[170:173], v156 offset:2048
	ds_read_b128 v[174:177], v156 offset:3072
	v_add_u32_e32 v156, s76, v159
	ds_read_b128 v[178:181], v156
	ds_read_b128 v[182:185], v156 offset:1024
	ds_read_b128 v[186:189], v156 offset:2048
	ds_read_b128 v[190:193], v156 offset:3072
	s_add_u32 s52, s52, 0x80000
	s_addc_u32 s53, s53, 0
	s_mov_b32 m0, s58
	v_lshl_add_u64 v[230:231], s[52:53], 0, v[138:139]
	ds_read_b128 v[194:197], v165 offset:32768
	ds_read_b128 v[198:201], v165 offset:33792
	ds_read_b128 v[202:205], v165 offset:34816
	ds_read_b128 v[206:209], v165 offset:35840
	ds_read_b128 v[210:213], v165 offset:36864
	ds_read_b128 v[214:217], v165 offset:37888
	ds_read_b128 v[218:221], v165 offset:38912
	ds_read_b128 v[222:225], v165 offset:39936
	global_load_lds_dwordx4 v[230:231], off
	v_lshl_add_u64 v[230:231], s[52:53], 0, v[142:143]
	s_mov_b32 m0, s59
	s_nop 0
	global_load_lds_dwordx4 v[230:231], off
	s_waitcnt vmcnt(8)
	s_waitcnt lgkmcnt(0)
	s_barrier
	s_waitcnt lgkmcnt(0)
	v_mfma_f32_16x16x32_bf16 v[126:129], v[130:133], v[194:197], v[126:129]
	v_mfma_f32_16x16x32_bf16 v[122:125], v[170:173], v[194:197], v[122:125]
	v_mfma_f32_16x16x32_bf16 v[118:121], v[130:133], v[202:205], v[118:121]
	v_mfma_f32_16x16x32_bf16 v[110:113], v[170:173], v[202:205], v[110:113]
	v_mfma_f32_16x16x32_bf16 v[102:105], v[130:133], v[210:213], v[102:105]
	v_mfma_f32_16x16x32_bf16 v[94:97], v[170:173], v[210:213], v[94:97]
	v_mfma_f32_16x16x32_bf16 v[86:89], v[130:133], v[218:221], v[86:89]
	v_mfma_f32_16x16x32_bf16 v[78:81], v[170:173], v[218:221], v[78:81]
	v_mfma_f32_16x16x32_bf16 v[126:129], v[134:137], v[198:201], v[126:129]
	v_mfma_f32_16x16x32_bf16 v[122:125], v[174:177], v[198:201], v[122:125]
	v_mfma_f32_16x16x32_bf16 v[118:121], v[134:137], v[206:209], v[118:121]
	v_mfma_f32_16x16x32_bf16 v[110:113], v[174:177], v[206:209], v[110:113]
	v_mfma_f32_16x16x32_bf16 v[102:105], v[134:137], v[214:217], v[102:105]
	v_mfma_f32_16x16x32_bf16 v[94:97], v[174:177], v[214:217], v[94:97]
	v_mfma_f32_16x16x32_bf16 v[86:89], v[134:137], v[222:225], v[86:89]
	v_mfma_f32_16x16x32_bf16 v[78:81], v[174:177], v[222:225], v[78:81]
	v_mfma_f32_16x16x32_bf16 v[114:117], v[178:181], v[194:197], v[114:117]
	v_mfma_f32_16x16x32_bf16 v[106:109], v[186:189], v[194:197], v[106:109]
	v_mfma_f32_16x16x32_bf16 v[98:101], v[178:181], v[202:205], v[98:101]
	v_mfma_f32_16x16x32_bf16 v[90:93], v[186:189], v[202:205], v[90:93]
	v_mfma_f32_16x16x32_bf16 v[82:85], v[178:181], v[210:213], v[82:85]
	v_mfma_f32_16x16x32_bf16 v[74:77], v[186:189], v[210:213], v[74:77]
	v_mfma_f32_16x16x32_bf16 v[70:73], v[178:181], v[218:221], v[70:73]
	v_mfma_f32_16x16x32_bf16 v[66:69], v[186:189], v[218:221], v[66:69]
	v_mfma_f32_16x16x32_bf16 v[114:117], v[182:185], v[198:201], v[114:117]
	v_mfma_f32_16x16x32_bf16 v[106:109], v[190:193], v[198:201], v[106:109]
	v_mfma_f32_16x16x32_bf16 v[98:101], v[182:185], v[206:209], v[98:101]
	v_mfma_f32_16x16x32_bf16 v[90:93], v[190:193], v[206:209], v[90:93]
	v_mfma_f32_16x16x32_bf16 v[82:85], v[182:185], v[214:217], v[82:85]
	v_mfma_f32_16x16x32_bf16 v[74:77], v[190:193], v[214:217], v[74:77]
	v_mfma_f32_16x16x32_bf16 v[70:73], v[182:185], v[222:225], v[70:73]
	v_mfma_f32_16x16x32_bf16 v[66:69], v[190:193], v[222:225], v[66:69]
	s_barrier
	s_add_i32 s52, s75, s55
	v_lshl_add_u64 v[154:155], v[154:155], 0, s[12:13]
	s_mov_b32 m0, s52
	ds_read_b128 v[194:197], v165 offset:49152
	ds_read_b128 v[198:201], v165 offset:50176
	ds_read_b128 v[202:205], v165 offset:51200
	ds_read_b128 v[206:209], v165 offset:52224
	ds_read_b128 v[210:213], v165 offset:53248
	ds_read_b128 v[214:217], v165 offset:54272
	ds_read_b128 v[218:221], v165 offset:55296
	ds_read_b128 v[222:225], v165 offset:56320
	global_load_lds_dwordx4 v[154:155], off
	s_add_i32 m0, s52, 0x2000
	s_add_u32 s50, s50, 0x80080
	v_lshl_add_u64 v[154:155], v[166:167], 0, s[12:13]
	s_addc_u32 s51, s51, 0
	s_add_i32 s52, s76, s55
	global_load_lds_dwordx4 v[154:155], off
	v_lshl_add_u64 v[154:155], s[50:51], 0, v[140:141]
	s_mov_b32 m0, s52
	s_nop 0
	global_load_lds_dwordx4 v[154:155], off
	v_lshl_add_u64 v[154:155], s[50:51], 0, v[144:145]
	s_add_i32 m0, s52, 0x2000
	s_nop 0
	global_load_lds_dwordx4 v[154:155], off
	v_lshl_add_u64 v[154:155], v[226:227], 0, s[12:13]
	s_mov_b32 m0, s64
	s_nop 0
	global_load_lds_dwordx4 v[154:155], off
	v_lshl_add_u64 v[154:155], v[228:229], 0, s[12:13]
	s_mov_b32 m0, s65
	s_nop 0
	global_load_lds_dwordx4 v[154:155], off
	s_waitcnt vmcnt(8)
	s_waitcnt lgkmcnt(0)
	s_barrier
	s_waitcnt lgkmcnt(0)
	v_mfma_f32_16x16x32_bf16 v[62:65], v[130:133], v[194:197], v[62:65]
	v_mfma_f32_16x16x32_bf16 v[58:61], v[170:173], v[194:197], v[58:61]
	v_mfma_f32_16x16x32_bf16 v[54:57], v[130:133], v[202:205], v[54:57]
	v_mfma_f32_16x16x32_bf16 v[46:49], v[170:173], v[202:205], v[46:49]
	v_mfma_f32_16x16x32_bf16 v[38:41], v[130:133], v[210:213], v[38:41]
	v_mfma_f32_16x16x32_bf16 v[30:33], v[170:173], v[210:213], v[30:33]
	v_mfma_f32_16x16x32_bf16 v[22:25], v[130:133], v[218:221], v[22:25]
	v_mfma_f32_16x16x32_bf16 v[14:17], v[170:173], v[218:221], v[14:17]
	v_mfma_f32_16x16x32_bf16 v[62:65], v[134:137], v[198:201], v[62:65]
	v_mfma_f32_16x16x32_bf16 v[58:61], v[174:177], v[198:201], v[58:61]
	v_mfma_f32_16x16x32_bf16 v[54:57], v[134:137], v[206:209], v[54:57]
	v_mfma_f32_16x16x32_bf16 v[46:49], v[174:177], v[206:209], v[46:49]
	v_mfma_f32_16x16x32_bf16 v[38:41], v[134:137], v[214:217], v[38:41]
	v_mfma_f32_16x16x32_bf16 v[30:33], v[174:177], v[214:217], v[30:33]
	v_mfma_f32_16x16x32_bf16 v[22:25], v[134:137], v[222:225], v[22:25]
	v_mfma_f32_16x16x32_bf16 v[14:17], v[174:177], v[222:225], v[14:17]
	v_mfma_f32_16x16x32_bf16 v[50:53], v[178:181], v[194:197], v[50:53]
	v_mfma_f32_16x16x32_bf16 v[42:45], v[186:189], v[194:197], v[42:45]
	v_mfma_f32_16x16x32_bf16 v[34:37], v[178:181], v[202:205], v[34:37]
	v_mfma_f32_16x16x32_bf16 v[26:29], v[186:189], v[202:205], v[26:29]
	v_mfma_f32_16x16x32_bf16 v[18:21], v[178:181], v[210:213], v[18:21]
	v_mfma_f32_16x16x32_bf16 v[10:13], v[186:189], v[210:213], v[10:13]
	v_mfma_f32_16x16x32_bf16 v[6:9], v[178:181], v[218:221], v[6:9]
	v_mfma_f32_16x16x32_bf16 v[2:5], v[186:189], v[218:221], v[2:5]
	v_mfma_f32_16x16x32_bf16 v[50:53], v[182:185], v[198:201], v[50:53]
	v_mfma_f32_16x16x32_bf16 v[42:45], v[190:193], v[198:201], v[42:45]
	v_mfma_f32_16x16x32_bf16 v[34:37], v[182:185], v[206:209], v[34:37]
	v_mfma_f32_16x16x32_bf16 v[26:29], v[190:193], v[206:209], v[26:29]
	v_mfma_f32_16x16x32_bf16 v[18:21], v[182:185], v[214:217], v[18:21]
	v_mfma_f32_16x16x32_bf16 v[10:13], v[190:193], v[214:217], v[10:13]
	v_mfma_f32_16x16x32_bf16 v[6:9], v[182:185], v[222:225], v[6:9]
	v_mfma_f32_16x16x32_bf16 v[2:5], v[190:193], v[222:225], v[2:5]
	s_barrier
	s_add_i32 s74, s74, 2
	s_add_u32 s48, s48, 0x100
	s_addc_u32 s49, s49, 0
	s_add_u32 s72, s72, 0x100
	s_addc_u32 s73, s73, 0
	s_cmp_gt_u32 s74, 29
	s_cbranch_scc0 .LBB0_117
	s_and_b64 vcc, exec, s[28:29]
	s_cbranch_vccz .LBB0_120
	s_barrier

.LBB0_806:
	ds_read_b128 v[138:141], v144
	ds_read_b128 v[148:151], v144 offset:1024
	ds_read_b128 v[152:155], v144 offset:2048
	ds_read_b128 v[156:159], v144 offset:3072
	ds_read_b128 v[160:163], v145
	ds_read_b128 v[164:167], v145 offset:1024
	ds_read_b128 v[168:171], v145 offset:2048
	ds_read_b128 v[172:175], v145 offset:3072
	s_add_u32 s30, s28, 0x100
	s_addc_u32 s31, s29, 0
	s_add_u32 s34, s54, s28
	s_addc_u32 s35, s55, s29
	s_cmp_eq_u32 s56, 60
	s_cselect_b32 s36, 0, s30
	s_cselect_b32 s37, 0, s31
	s_cselect_b32 s34, s21, s34
	s_cselect_b32 s35, s8, s35
	s_add_u32 s36, s2, s36
	s_addc_u32 s37, s3, s37
	s_mov_b32 m0, s50
	v_lshl_add_u64 v[208:209], v[134:135], 0, s[28:29]
	ds_read_b128 v[176:179], v146
	ds_read_b128 v[180:183], v146 offset:1024
	ds_read_b128 v[184:187], v146 offset:2048
	ds_read_b128 v[188:191], v146 offset:3072
	ds_read_b128 v[192:195], v146 offset:4096
	ds_read_b128 v[196:199], v146 offset:5120
	ds_read_b128 v[200:203], v146 offset:6144
	ds_read_b128 v[204:207], v146 offset:7168
	global_load_lds_dwordx4 v[208:209], off
	v_lshl_add_u64 v[208:209], v[136:137], 0, s[28:29]
	s_mov_b32 m0, s51
	s_nop 0
	global_load_lds_dwordx4 v[208:209], off
	s_waitcnt vmcnt(8)
	s_waitcnt lgkmcnt(0)
	s_barrier
	s_waitcnt lgkmcnt(0)
	v_mfma_f32_16x16x32_bf16 v[126:129], v[138:141], v[176:179], v[126:129]
	v_mfma_f32_16x16x32_bf16 v[122:125], v[152:155], v[176:179], v[122:125]
	v_mfma_f32_16x16x32_bf16 v[110:113], v[138:141], v[184:187], v[110:113]
	v_mfma_f32_16x16x32_bf16 v[106:109], v[152:155], v[184:187], v[106:109]
	v_mfma_f32_16x16x32_bf16 v[94:97], v[138:141], v[192:195], v[94:97]
	v_mfma_f32_16x16x32_bf16 v[90:93], v[152:155], v[192:195], v[90:93]
	v_mfma_f32_16x16x32_bf16 v[78:81], v[138:141], v[200:203], v[78:81]
	v_mfma_f32_16x16x32_bf16 v[74:77], v[152:155], v[200:203], v[74:77]
	v_mfma_f32_16x16x32_bf16 v[126:129], v[148:151], v[180:183], v[126:129]
	v_mfma_f32_16x16x32_bf16 v[122:125], v[156:159], v[180:183], v[122:125]
	v_mfma_f32_16x16x32_bf16 v[110:113], v[148:151], v[188:191], v[110:113]
	v_mfma_f32_16x16x32_bf16 v[106:109], v[156:159], v[188:191], v[106:109]
	v_mfma_f32_16x16x32_bf16 v[94:97], v[148:151], v[196:199], v[94:97]
	v_mfma_f32_16x16x32_bf16 v[90:93], v[156:159], v[196:199], v[90:93]
	v_mfma_f32_16x16x32_bf16 v[78:81], v[148:151], v[204:207], v[78:81]
	v_mfma_f32_16x16x32_bf16 v[74:77], v[156:159], v[204:207], v[74:77]
	v_mfma_f32_16x16x32_bf16 v[118:121], v[160:163], v[176:179], v[118:121]
	v_mfma_f32_16x16x32_bf16 v[114:117], v[168:171], v[176:179], v[114:117]
	v_mfma_f32_16x16x32_bf16 v[102:105], v[160:163], v[184:187], v[102:105]
	v_mfma_f32_16x16x32_bf16 v[98:101], v[168:171], v[184:187], v[98:101]
	v_mfma_f32_16x16x32_bf16 v[86:89], v[160:163], v[192:195], v[86:89]
	v_mfma_f32_16x16x32_bf16 v[82:85], v[168:171], v[192:195], v[82:85]
	v_mfma_f32_16x16x32_bf16 v[70:73], v[160:163], v[200:203], v[70:73]
	v_mfma_f32_16x16x32_bf16 v[66:69], v[168:171], v[200:203], v[66:69]
	v_mfma_f32_16x16x32_bf16 v[118:121], v[164:167], v[180:183], v[118:121]
	v_mfma_f32_16x16x32_bf16 v[114:117], v[172:175], v[180:183], v[114:117]
	v_mfma_f32_16x16x32_bf16 v[102:105], v[164:167], v[188:191], v[102:105]
	v_mfma_f32_16x16x32_bf16 v[98:101], v[172:175], v[188:191], v[98:101]
	v_mfma_f32_16x16x32_bf16 v[86:89], v[164:167], v[196:199], v[86:89]
	v_mfma_f32_16x16x32_bf16 v[82:85], v[172:175], v[196:199], v[82:85]
	v_mfma_f32_16x16x32_bf16 v[70:73], v[164:167], v[204:207], v[70:73]
	v_mfma_f32_16x16x32_bf16 v[66:69], v[172:175], v[204:207], v[66:69]
	s_barrier
	s_add_i32 s28, s48, s33
	v_lshl_add_u64 v[208:209], s[34:35], 0, v[132:133]
	s_mov_b32 m0, s28
	ds_read_b128 v[176:179], v146 offset:16384
	ds_read_b128 v[180:183], v146 offset:17408
	ds_read_b128 v[184:187], v146 offset:18432
	ds_read_b128 v[188:191], v146 offset:19456
	ds_read_b128 v[192:195], v146 offset:20480
	ds_read_b128 v[196:199], v146 offset:21504
	ds_read_b128 v[200:203], v146 offset:22528
	ds_read_b128 v[204:207], v146 offset:23552
	global_load_lds_dwordx4 v[208:209], off
	s_add_i32 m0, s28, 0x2000
	s_add_u32 s28, s34, 0x100000
	v_lshl_add_u64 v[210:211], s[34:35], 0, v[130:131]
	s_addc_u32 s29, s35, 0
	s_add_i32 s57, s49, s33
	global_load_lds_dwordx4 v[210:211], off
	v_lshl_add_u64 v[212:213], s[28:29], 0, v[132:133]
	s_mov_b32 m0, s57
	v_lshl_add_u64 v[214:215], s[36:37], 0, v[130:131]
	global_load_lds_dwordx4 v[212:213], off
	v_lshl_add_u64 v[212:213], s[28:29], 0, v[130:131]
	s_add_i32 m0, s57, 0x2000
	s_nop 0
	global_load_lds_dwordx4 v[212:213], off
	v_lshl_add_u64 v[212:213], s[36:37], 0, v[132:133]
	s_mov_b32 m0, s39
	s_nop 0
	global_load_lds_dwordx4 v[212:213], off
	s_mov_b32 m0, s40
	s_nop 0
	global_load_lds_dwordx4 v[214:215], off
	s_waitcnt vmcnt(8)
	s_waitcnt lgkmcnt(0)
	s_barrier
	s_waitcnt lgkmcnt(0)
	v_mfma_f32_16x16x32_bf16 v[62:65], v[138:141], v[176:179], v[62:65]
	v_mfma_f32_16x16x32_bf16 v[58:61], v[152:155], v[176:179], v[58:61]
	v_mfma_f32_16x16x32_bf16 v[46:49], v[138:141], v[184:187], v[46:49]
	v_mfma_f32_16x16x32_bf16 v[42:45], v[152:155], v[184:187], v[42:45]
	v_mfma_f32_16x16x32_bf16 v[30:33], v[138:141], v[192:195], v[30:33]
	v_mfma_f32_16x16x32_bf16 v[26:29], v[152:155], v[192:195], v[26:29]
	v_mfma_f32_16x16x32_bf16 v[14:17], v[138:141], v[200:203], v[14:17]
	v_mfma_f32_16x16x32_bf16 v[10:13], v[152:155], v[200:203], v[10:13]
	v_mfma_f32_16x16x32_bf16 v[62:65], v[148:151], v[180:183], v[62:65]
	v_mfma_f32_16x16x32_bf16 v[58:61], v[156:159], v[180:183], v[58:61]
	v_mfma_f32_16x16x32_bf16 v[46:49], v[148:151], v[188:191], v[46:49]
	v_mfma_f32_16x16x32_bf16 v[42:45], v[156:159], v[188:191], v[42:45]
	v_mfma_f32_16x16x32_bf16 v[30:33], v[148:151], v[196:199], v[30:33]
	v_mfma_f32_16x16x32_bf16 v[26:29], v[156:159], v[196:199], v[26:29]
	v_mfma_f32_16x16x32_bf16 v[14:17], v[148:151], v[204:207], v[14:17]
	v_mfma_f32_16x16x32_bf16 v[10:13], v[156:159], v[204:207], v[10:13]
	v_mfma_f32_16x16x32_bf16 v[54:57], v[160:163], v[176:179], v[54:57]
	v_mfma_f32_16x16x32_bf16 v[50:53], v[168:171], v[176:179], v[50:53]
	v_mfma_f32_16x16x32_bf16 v[38:41], v[160:163], v[184:187], v[38:41]
	v_mfma_f32_16x16x32_bf16 v[34:37], v[168:171], v[184:187], v[34:37]
	v_mfma_f32_16x16x32_bf16 v[22:25], v[160:163], v[192:195], v[22:25]
	v_mfma_f32_16x16x32_bf16 v[18:21], v[168:171], v[192:195], v[18:21]
	v_mfma_f32_16x16x32_bf16 v[6:9], v[160:163], v[200:203], v[6:9]
	v_mfma_f32_16x16x32_bf16 v[2:5], v[168:171], v[200:203], v[2:5]
	v_mfma_f32_16x16x32_bf16 v[54:57], v[164:167], v[180:183], v[54:57]
	v_mfma_f32_16x16x32_bf16 v[50:53], v[172:175], v[180:183], v[50:53]
	v_mfma_f32_16x16x32_bf16 v[38:41], v[164:167], v[188:191], v[38:41]
	v_mfma_f32_16x16x32_bf16 v[34:37], v[172:175], v[188:191], v[34:37]
	v_mfma_f32_16x16x32_bf16 v[22:25], v[164:167], v[196:199], v[22:25]
	v_mfma_f32_16x16x32_bf16 v[18:21], v[172:175], v[196:199], v[18:21]
	v_mfma_f32_16x16x32_bf16 v[6:9], v[164:167], v[204:207], v[6:9]
	v_mfma_f32_16x16x32_bf16 v[2:5], v[172:175], v[204:207], v[2:5]
	s_barrier
	s_add_i32 s57, 0, 0x18000
	s_add_i32 s58, 0, 0x1c000
	v_add_u32_e32 v156, s57, v143
	v_add_u32_e32 v172, s58, v143
	ds_read_b128 v[138:141], v156
	ds_read_b128 v[148:151], v156 offset:1024
	ds_read_b128 v[152:155], v156 offset:2048
	ds_read_b128 v[156:159], v156 offset:3072
	ds_read_b128 v[160:163], v172
	ds_read_b128 v[164:167], v172 offset:1024
	ds_read_b128 v[168:171], v172 offset:2048
	ds_read_b128 v[172:175], v172 offset:3072
	s_add_u32 s28, s36, 0x100000
	s_addc_u32 s29, s37, 0
	s_mov_b32 m0, s41
	v_lshl_add_u64 v[216:217], s[28:29], 0, v[132:133]
	ds_read_b128 v[176:179], v146 offset:32768
	ds_read_b128 v[180:183], v146 offset:33792
	ds_read_b128 v[184:187], v146 offset:34816
	ds_read_b128 v[188:191], v146 offset:35840
	ds_read_b128 v[192:195], v146 offset:36864
	ds_read_b128 v[196:199], v146 offset:37888
	ds_read_b128 v[200:203], v146 offset:38912
	ds_read_b128 v[204:207], v146 offset:39936
	global_load_lds_dwordx4 v[216:217], off
	v_lshl_add_u64 v[216:217], s[28:29], 0, v[130:131]
	s_mov_b32 m0, s42
	s_nop 0
	global_load_lds_dwordx4 v[216:217], off
	s_waitcnt vmcnt(8)
	s_waitcnt lgkmcnt(0)
	s_barrier
	s_waitcnt lgkmcnt(0)
	v_mfma_f32_16x16x32_bf16 v[126:129], v[138:141], v[176:179], v[126:129]
	v_mfma_f32_16x16x32_bf16 v[122:125], v[152:155], v[176:179], v[122:125]
	v_mfma_f32_16x16x32_bf16 v[110:113], v[138:141], v[184:187], v[110:113]
	v_mfma_f32_16x16x32_bf16 v[106:109], v[152:155], v[184:187], v[106:109]
	v_mfma_f32_16x16x32_bf16 v[94:97], v[138:141], v[192:195], v[94:97]
	v_mfma_f32_16x16x32_bf16 v[90:93], v[152:155], v[192:195], v[90:93]
	v_mfma_f32_16x16x32_bf16 v[78:81], v[138:141], v[200:203], v[78:81]
	v_mfma_f32_16x16x32_bf16 v[74:77], v[152:155], v[200:203], v[74:77]
	v_mfma_f32_16x16x32_bf16 v[126:129], v[148:151], v[180:183], v[126:129]
	v_mfma_f32_16x16x32_bf16 v[122:125], v[156:159], v[180:183], v[122:125]
	v_mfma_f32_16x16x32_bf16 v[110:113], v[148:151], v[188:191], v[110:113]
	v_mfma_f32_16x16x32_bf16 v[106:109], v[156:159], v[188:191], v[106:109]
	v_mfma_f32_16x16x32_bf16 v[94:97], v[148:151], v[196:199], v[94:97]
	v_mfma_f32_16x16x32_bf16 v[90:93], v[156:159], v[196:199], v[90:93]
	v_mfma_f32_16x16x32_bf16 v[78:81], v[148:151], v[204:207], v[78:81]
	v_mfma_f32_16x16x32_bf16 v[74:77], v[156:159], v[204:207], v[74:77]
	v_mfma_f32_16x16x32_bf16 v[118:121], v[160:163], v[176:179], v[118:121]
	v_mfma_f32_16x16x32_bf16 v[114:117], v[168:171], v[176:179], v[114:117]
	v_mfma_f32_16x16x32_bf16 v[102:105], v[160:163], v[184:187], v[102:105]
	v_mfma_f32_16x16x32_bf16 v[98:101], v[168:171], v[184:187], v[98:101]
	v_mfma_f32_16x16x32_bf16 v[86:89], v[160:163], v[192:195], v[86:89]
	v_mfma_f32_16x16x32_bf16 v[82:85], v[168:171], v[192:195], v[82:85]
	v_mfma_f32_16x16x32_bf16 v[70:73], v[160:163], v[200:203], v[70:73]
	v_mfma_f32_16x16x32_bf16 v[66:69], v[168:171], v[200:203], v[66:69]
	v_mfma_f32_16x16x32_bf16 v[118:121], v[164:167], v[180:183], v[118:121]
	v_mfma_f32_16x16x32_bf16 v[114:117], v[172:175], v[180:183], v[114:117]
	v_mfma_f32_16x16x32_bf16 v[102:105], v[164:167], v[188:191], v[102:105]
	v_mfma_f32_16x16x32_bf16 v[98:101], v[172:175], v[188:191], v[98:101]
	v_mfma_f32_16x16x32_bf16 v[86:89], v[164:167], v[196:199], v[86:89]
	v_mfma_f32_16x16x32_bf16 v[82:85], v[172:175], v[196:199], v[82:85]
	v_mfma_f32_16x16x32_bf16 v[70:73], v[164:167], v[204:207], v[70:73]
	v_mfma_f32_16x16x32_bf16 v[66:69], v[172:175], v[204:207], v[66:69]
	s_barrier
	s_add_i32 s28, s57, s33
	v_lshl_add_u64 v[208:209], v[208:209], 0, s[16:17]
	s_mov_b32 m0, s28
	ds_read_b128 v[176:179], v146 offset:49152
	ds_read_b128 v[180:183], v146 offset:50176
	ds_read_b128 v[184:187], v146 offset:51200
	ds_read_b128 v[188:191], v146 offset:52224
	ds_read_b128 v[192:195], v146 offset:53248
	ds_read_b128 v[196:199], v146 offset:54272
	ds_read_b128 v[200:203], v146 offset:55296
	ds_read_b128 v[204:207], v146 offset:56320
	global_load_lds_dwordx4 v[208:209], off
	s_add_i32 m0, s28, 0x2000
	s_add_u32 s28, s34, 0x100080
	v_lshl_add_u64 v[208:209], v[210:211], 0, s[16:17]
	s_addc_u32 s29, s35, 0
	s_add_i32 s34, s58, s33
	global_load_lds_dwordx4 v[208:209], off
	v_lshl_add_u64 v[208:209], s[28:29], 0, v[132:133]
	s_mov_b32 m0, s34
	s_nop 0
	global_load_lds_dwordx4 v[208:209], off
	v_lshl_add_u64 v[208:209], s[28:29], 0, v[130:131]
	s_add_i32 m0, s34, 0x2000
	s_nop 0
	global_load_lds_dwordx4 v[208:209], off
	v_lshl_add_u64 v[208:209], v[212:213], 0, s[16:17]
	s_mov_b32 m0, s45
	s_nop 0
	global_load_lds_dwordx4 v[208:209], off
	v_lshl_add_u64 v[208:209], v[214:215], 0, s[16:17]
	s_mov_b32 m0, s46
	s_nop 0
	global_load_lds_dwordx4 v[208:209], off
	s_waitcnt vmcnt(8)
	s_waitcnt lgkmcnt(0)
	s_barrier
	s_waitcnt lgkmcnt(0)
	v_mfma_f32_16x16x32_bf16 v[62:65], v[138:141], v[176:179], v[62:65]
	v_mfma_f32_16x16x32_bf16 v[58:61], v[152:155], v[176:179], v[58:61]
	v_mfma_f32_16x16x32_bf16 v[46:49], v[138:141], v[184:187], v[46:49]
	v_mfma_f32_16x16x32_bf16 v[42:45], v[152:155], v[184:187], v[42:45]
	v_mfma_f32_16x16x32_bf16 v[30:33], v[138:141], v[192:195], v[30:33]
	v_mfma_f32_16x16x32_bf16 v[26:29], v[152:155], v[192:195], v[26:29]
	v_mfma_f32_16x16x32_bf16 v[14:17], v[138:141], v[200:203], v[14:17]
	v_mfma_f32_16x16x32_bf16 v[10:13], v[152:155], v[200:203], v[10:13]
	v_mfma_f32_16x16x32_bf16 v[62:65], v[148:151], v[180:183], v[62:65]
	v_mfma_f32_16x16x32_bf16 v[58:61], v[156:159], v[180:183], v[58:61]
	v_mfma_f32_16x16x32_bf16 v[46:49], v[148:151], v[188:191], v[46:49]
	v_mfma_f32_16x16x32_bf16 v[42:45], v[156:159], v[188:191], v[42:45]
	v_mfma_f32_16x16x32_bf16 v[30:33], v[148:151], v[196:199], v[30:33]
	v_mfma_f32_16x16x32_bf16 v[26:29], v[156:159], v[196:199], v[26:29]
	v_mfma_f32_16x16x32_bf16 v[14:17], v[148:151], v[204:207], v[14:17]
	v_mfma_f32_16x16x32_bf16 v[10:13], v[156:159], v[204:207], v[10:13]
	v_mfma_f32_16x16x32_bf16 v[54:57], v[160:163], v[176:179], v[54:57]
	v_mfma_f32_16x16x32_bf16 v[50:53], v[168:171], v[176:179], v[50:53]
	v_mfma_f32_16x16x32_bf16 v[38:41], v[160:163], v[184:187], v[38:41]
	v_mfma_f32_16x16x32_bf16 v[34:37], v[168:171], v[184:187], v[34:37]
	v_mfma_f32_16x16x32_bf16 v[22:25], v[160:163], v[192:195], v[22:25]
	v_mfma_f32_16x16x32_bf16 v[18:21], v[168:171], v[192:195], v[18:21]
	v_mfma_f32_16x16x32_bf16 v[6:9], v[160:163], v[200:203], v[6:9]
	v_mfma_f32_16x16x32_bf16 v[2:5], v[168:171], v[200:203], v[2:5]
	v_mfma_f32_16x16x32_bf16 v[54:57], v[164:167], v[180:183], v[54:57]
	v_mfma_f32_16x16x32_bf16 v[50:53], v[172:175], v[180:183], v[50:53]
	v_mfma_f32_16x16x32_bf16 v[38:41], v[164:167], v[188:191], v[38:41]
	v_mfma_f32_16x16x32_bf16 v[34:37], v[172:175], v[188:191], v[34:37]
	v_mfma_f32_16x16x32_bf16 v[22:25], v[164:167], v[196:199], v[22:25]
	v_mfma_f32_16x16x32_bf16 v[18:21], v[172:175], v[196:199], v[18:21]
	v_mfma_f32_16x16x32_bf16 v[6:9], v[164:167], v[204:207], v[6:9]
	v_mfma_f32_16x16x32_bf16 v[2:5], v[172:175], v[204:207], v[2:5]
	s_barrier
	s_add_i32 s56, s56, 2
	s_cmp_gt_u32 s56, 61
	s_mov_b64 s[28:29], s[30:31]
	s_cbranch_scc0 .LBB0_806
	s_and_b64 vcc, exec, s[18:19]
	s_cbranch_vccz .LBB0_809
	s_barrier

.LBB0_910:
	ds_read_b128 v[130:133], v157
	ds_read_b128 v[134:137], v157 offset:1024
	ds_read_b128 v[164:167], v157 offset:2048
	ds_read_b128 v[168:171], v157 offset:3072
	ds_read_b128 v[172:175], v159
	ds_read_b128 v[176:179], v159 offset:1024
	ds_read_b128 v[180:183], v159 offset:2048
	ds_read_b128 v[184:187], v159 offset:3072
	s_add_u32 s30, s6, 0xfff80080
	s_addc_u32 s31, s7, -1
	s_cmp_eq_u32 s58, 28
	s_cselect_b32 s35, s13, s31
	s_cselect_b32 s34, s12, s30
	s_cselect_b32 s31, s1, s57
	s_cselect_b32 s30, s55, s56
	s_mov_b32 m0, s49
	v_lshl_add_u64 v[154:155], s[6:7], 0, v[146:147]
	ds_read_b128 v[188:191], v161
	ds_read_b128 v[192:195], v161 offset:1024
	ds_read_b128 v[196:199], v161 offset:2048
	ds_read_b128 v[200:203], v161 offset:3072
	ds_read_b128 v[204:207], v161 offset:4096
	ds_read_b128 v[208:211], v161 offset:5120
	ds_read_b128 v[212:215], v161 offset:6144
	ds_read_b128 v[216:219], v161 offset:7168
	global_load_lds_dwordx4 v[154:155], off
	v_lshl_add_u64 v[154:155], s[6:7], 0, v[148:149]
	s_mov_b32 m0, s50
	s_nop 0
	global_load_lds_dwordx4 v[154:155], off
	s_waitcnt vmcnt(8)
	s_waitcnt lgkmcnt(0)
	s_barrier
	s_waitcnt lgkmcnt(0)
	v_mfma_f32_16x16x32_bf16 v[126:129], v[130:133], v[188:191], v[126:129]
	v_mfma_f32_16x16x32_bf16 v[122:125], v[164:167], v[188:191], v[122:125]
	v_mfma_f32_16x16x32_bf16 v[118:121], v[130:133], v[196:199], v[118:121]
	v_mfma_f32_16x16x32_bf16 v[110:113], v[164:167], v[196:199], v[110:113]
	v_mfma_f32_16x16x32_bf16 v[102:105], v[130:133], v[204:207], v[102:105]
	v_mfma_f32_16x16x32_bf16 v[94:97], v[164:167], v[204:207], v[94:97]
	v_mfma_f32_16x16x32_bf16 v[86:89], v[130:133], v[212:215], v[86:89]
	v_mfma_f32_16x16x32_bf16 v[78:81], v[164:167], v[212:215], v[78:81]
	v_mfma_f32_16x16x32_bf16 v[126:129], v[134:137], v[192:195], v[126:129]
	v_mfma_f32_16x16x32_bf16 v[122:125], v[168:171], v[192:195], v[122:125]
	v_mfma_f32_16x16x32_bf16 v[118:121], v[134:137], v[200:203], v[118:121]
	v_mfma_f32_16x16x32_bf16 v[110:113], v[168:171], v[200:203], v[110:113]
	v_mfma_f32_16x16x32_bf16 v[102:105], v[134:137], v[208:211], v[102:105]
	v_mfma_f32_16x16x32_bf16 v[94:97], v[168:171], v[208:211], v[94:97]
	v_mfma_f32_16x16x32_bf16 v[86:89], v[134:137], v[216:219], v[86:89]
	v_mfma_f32_16x16x32_bf16 v[78:81], v[168:171], v[216:219], v[78:81]
	v_mfma_f32_16x16x32_bf16 v[114:117], v[172:175], v[188:191], v[114:117]
	v_mfma_f32_16x16x32_bf16 v[106:109], v[180:183], v[188:191], v[106:109]
	v_mfma_f32_16x16x32_bf16 v[98:101], v[172:175], v[196:199], v[98:101]
	v_mfma_f32_16x16x32_bf16 v[90:93], v[180:183], v[196:199], v[90:93]
	v_mfma_f32_16x16x32_bf16 v[82:85], v[172:175], v[204:207], v[82:85]
	v_mfma_f32_16x16x32_bf16 v[74:77], v[180:183], v[204:207], v[74:77]
	v_mfma_f32_16x16x32_bf16 v[70:73], v[172:175], v[212:215], v[70:73]
	v_mfma_f32_16x16x32_bf16 v[66:69], v[180:183], v[212:215], v[66:69]
	v_mfma_f32_16x16x32_bf16 v[114:117], v[176:179], v[192:195], v[114:117]
	v_mfma_f32_16x16x32_bf16 v[106:109], v[184:187], v[192:195], v[106:109]
	v_mfma_f32_16x16x32_bf16 v[98:101], v[176:179], v[200:203], v[98:101]
	v_mfma_f32_16x16x32_bf16 v[90:93], v[184:187], v[200:203], v[90:93]
	v_mfma_f32_16x16x32_bf16 v[82:85], v[176:179], v[208:211], v[82:85]
	v_mfma_f32_16x16x32_bf16 v[74:77], v[184:187], v[208:211], v[74:77]
	v_mfma_f32_16x16x32_bf16 v[70:73], v[176:179], v[216:219], v[70:73]
	v_mfma_f32_16x16x32_bf16 v[66:69], v[184:187], v[216:219], v[66:69]
	s_barrier
	s_mov_b32 m0, s51
	v_lshl_add_u64 v[154:155], s[30:31], 0, v[142:143]
	ds_read_b128 v[188:191], v161 offset:16384
	ds_read_b128 v[192:195], v161 offset:17408
	ds_read_b128 v[196:199], v161 offset:18432
	ds_read_b128 v[200:203], v161 offset:19456
	ds_read_b128 v[204:207], v161 offset:20480
	ds_read_b128 v[208:211], v161 offset:21504
	ds_read_b128 v[212:215], v161 offset:22528
	ds_read_b128 v[216:219], v161 offset:23552
	global_load_lds_dwordx4 v[154:155], off
	s_add_i32 m0, s51, 0x2000
	s_add_u32 s60, s30, 0x80000
	v_lshl_add_u64 v[220:221], s[30:31], 0, v[138:139]
	s_addc_u32 s61, s31, 0
	s_add_i32 s59, s48, s36
	global_load_lds_dwordx4 v[220:221], off
	v_lshl_add_u64 v[222:223], s[60:61], 0, v[142:143]
	s_mov_b32 m0, s59
	v_lshl_add_u64 v[224:225], s[34:35], 0, v[140:141]
	global_load_lds_dwordx4 v[222:223], off
	v_lshl_add_u64 v[222:223], s[60:61], 0, v[138:139]
	s_add_i32 m0, s59, 0x2000
	s_nop 0
	global_load_lds_dwordx4 v[222:223], off
	v_lshl_add_u64 v[222:223], s[34:35], 0, v[144:145]
	s_mov_b32 m0, s37
	s_nop 0
	global_load_lds_dwordx4 v[222:223], off
	s_mov_b32 m0, s40
	s_nop 0
	global_load_lds_dwordx4 v[224:225], off
	s_waitcnt vmcnt(8)
	s_waitcnt lgkmcnt(0)
	s_barrier
	s_waitcnt lgkmcnt(0)
	v_mfma_f32_16x16x32_bf16 v[62:65], v[130:133], v[188:191], v[62:65]
	v_mfma_f32_16x16x32_bf16 v[58:61], v[164:167], v[188:191], v[58:61]
	v_mfma_f32_16x16x32_bf16 v[54:57], v[130:133], v[196:199], v[54:57]
	v_mfma_f32_16x16x32_bf16 v[46:49], v[164:167], v[196:199], v[46:49]
	v_mfma_f32_16x16x32_bf16 v[38:41], v[130:133], v[204:207], v[38:41]
	v_mfma_f32_16x16x32_bf16 v[30:33], v[164:167], v[204:207], v[30:33]
	v_mfma_f32_16x16x32_bf16 v[22:25], v[130:133], v[212:215], v[22:25]
	v_mfma_f32_16x16x32_bf16 v[14:17], v[164:167], v[212:215], v[14:17]
	v_mfma_f32_16x16x32_bf16 v[62:65], v[134:137], v[192:195], v[62:65]
	v_mfma_f32_16x16x32_bf16 v[58:61], v[168:171], v[192:195], v[58:61]
	v_mfma_f32_16x16x32_bf16 v[54:57], v[134:137], v[200:203], v[54:57]
	v_mfma_f32_16x16x32_bf16 v[46:49], v[168:171], v[200:203], v[46:49]
	v_mfma_f32_16x16x32_bf16 v[38:41], v[134:137], v[208:211], v[38:41]
	v_mfma_f32_16x16x32_bf16 v[30:33], v[168:171], v[208:211], v[30:33]
	v_mfma_f32_16x16x32_bf16 v[22:25], v[134:137], v[216:219], v[22:25]
	v_mfma_f32_16x16x32_bf16 v[14:17], v[168:171], v[216:219], v[14:17]
	v_mfma_f32_16x16x32_bf16 v[50:53], v[172:175], v[188:191], v[50:53]
	v_mfma_f32_16x16x32_bf16 v[42:45], v[180:183], v[188:191], v[42:45]
	v_mfma_f32_16x16x32_bf16 v[34:37], v[172:175], v[196:199], v[34:37]
	v_mfma_f32_16x16x32_bf16 v[26:29], v[180:183], v[196:199], v[26:29]
	v_mfma_f32_16x16x32_bf16 v[18:21], v[172:175], v[204:207], v[18:21]
	v_mfma_f32_16x16x32_bf16 v[10:13], v[180:183], v[204:207], v[10:13]
	v_mfma_f32_16x16x32_bf16 v[6:9], v[172:175], v[212:215], v[6:9]
	v_mfma_f32_16x16x32_bf16 v[2:5], v[180:183], v[212:215], v[2:5]
	v_mfma_f32_16x16x32_bf16 v[50:53], v[176:179], v[192:195], v[50:53]
	v_mfma_f32_16x16x32_bf16 v[42:45], v[184:187], v[192:195], v[42:45]
	v_mfma_f32_16x16x32_bf16 v[34:37], v[176:179], v[200:203], v[34:37]
	v_mfma_f32_16x16x32_bf16 v[26:29], v[184:187], v[200:203], v[26:29]
	v_mfma_f32_16x16x32_bf16 v[18:21], v[176:179], v[208:211], v[18:21]
	v_mfma_f32_16x16x32_bf16 v[10:13], v[184:187], v[208:211], v[10:13]
	v_mfma_f32_16x16x32_bf16 v[6:9], v[176:179], v[216:219], v[6:9]
	v_mfma_f32_16x16x32_bf16 v[2:5], v[184:187], v[216:219], v[2:5]
	s_barrier
	s_add_i32 s59, 0, 0x18000
	v_add_u32_e32 v150, s59, v153
	s_add_i32 s60, 0, 0x1c000
	ds_read_b128 v[130:133], v150
	ds_read_b128 v[134:137], v150 offset:1024
	ds_read_b128 v[164:167], v150 offset:2048
	ds_read_b128 v[168:171], v150 offset:3072
	v_add_u32_e32 v150, s60, v153
	ds_read_b128 v[172:175], v150
	ds_read_b128 v[176:179], v150 offset:1024
	ds_read_b128 v[180:183], v150 offset:2048
	ds_read_b128 v[184:187], v150 offset:3072
	s_add_u32 s34, s34, 0x80000
	s_addc_u32 s35, s35, 0
	s_mov_b32 m0, s41
	v_lshl_add_u64 v[226:227], s[34:35], 0, v[144:145]
	ds_read_b128 v[188:191], v161 offset:32768
	ds_read_b128 v[192:195], v161 offset:33792
	ds_read_b128 v[196:199], v161 offset:34816
	ds_read_b128 v[200:203], v161 offset:35840
	ds_read_b128 v[204:207], v161 offset:36864
	ds_read_b128 v[208:211], v161 offset:37888
	ds_read_b128 v[212:215], v161 offset:38912
	ds_read_b128 v[216:219], v161 offset:39936
	global_load_lds_dwordx4 v[226:227], off
	v_lshl_add_u64 v[226:227], s[34:35], 0, v[140:141]
	s_mov_b32 m0, s42
	s_nop 0
	global_load_lds_dwordx4 v[226:227], off
	s_waitcnt vmcnt(8)
	s_waitcnt lgkmcnt(0)
	s_barrier
	s_waitcnt lgkmcnt(0)
	v_mfma_f32_16x16x32_bf16 v[126:129], v[130:133], v[188:191], v[126:129]
	v_mfma_f32_16x16x32_bf16 v[122:125], v[164:167], v[188:191], v[122:125]
	v_mfma_f32_16x16x32_bf16 v[118:121], v[130:133], v[196:199], v[118:121]
	v_mfma_f32_16x16x32_bf16 v[110:113], v[164:167], v[196:199], v[110:113]
	v_mfma_f32_16x16x32_bf16 v[102:105], v[130:133], v[204:207], v[102:105]
	v_mfma_f32_16x16x32_bf16 v[94:97], v[164:167], v[204:207], v[94:97]
	v_mfma_f32_16x16x32_bf16 v[86:89], v[130:133], v[212:215], v[86:89]
	v_mfma_f32_16x16x32_bf16 v[78:81], v[164:167], v[212:215], v[78:81]
	v_mfma_f32_16x16x32_bf16 v[126:129], v[134:137], v[192:195], v[126:129]
	v_mfma_f32_16x16x32_bf16 v[122:125], v[168:171], v[192:195], v[122:125]
	v_mfma_f32_16x16x32_bf16 v[118:121], v[134:137], v[200:203], v[118:121]
	v_mfma_f32_16x16x32_bf16 v[110:113], v[168:171], v[200:203], v[110:113]
	v_mfma_f32_16x16x32_bf16 v[102:105], v[134:137], v[208:211], v[102:105]
	v_mfma_f32_16x16x32_bf16 v[94:97], v[168:171], v[208:211], v[94:97]
	v_mfma_f32_16x16x32_bf16 v[86:89], v[134:137], v[216:219], v[86:89]
	v_mfma_f32_16x16x32_bf16 v[78:81], v[168:171], v[216:219], v[78:81]
	v_mfma_f32_16x16x32_bf16 v[114:117], v[172:175], v[188:191], v[114:117]
	v_mfma_f32_16x16x32_bf16 v[106:109], v[180:183], v[188:191], v[106:109]
	v_mfma_f32_16x16x32_bf16 v[98:101], v[172:175], v[196:199], v[98:101]
	v_mfma_f32_16x16x32_bf16 v[90:93], v[180:183], v[196:199], v[90:93]
	v_mfma_f32_16x16x32_bf16 v[82:85], v[172:175], v[204:207], v[82:85]
	v_mfma_f32_16x16x32_bf16 v[74:77], v[180:183], v[204:207], v[74:77]
	v_mfma_f32_16x16x32_bf16 v[70:73], v[172:175], v[212:215], v[70:73]
	v_mfma_f32_16x16x32_bf16 v[66:69], v[180:183], v[212:215], v[66:69]
	v_mfma_f32_16x16x32_bf16 v[114:117], v[176:179], v[192:195], v[114:117]
	v_mfma_f32_16x16x32_bf16 v[106:109], v[184:187], v[192:195], v[106:109]
	v_mfma_f32_16x16x32_bf16 v[98:101], v[176:179], v[200:203], v[98:101]
	v_mfma_f32_16x16x32_bf16 v[90:93], v[184:187], v[200:203], v[90:93]
	v_mfma_f32_16x16x32_bf16 v[82:85], v[176:179], v[208:211], v[82:85]
	v_mfma_f32_16x16x32_bf16 v[74:77], v[184:187], v[208:211], v[74:77]
	v_mfma_f32_16x16x32_bf16 v[70:73], v[176:179], v[216:219], v[70:73]
	v_mfma_f32_16x16x32_bf16 v[66:69], v[184:187], v[216:219], v[66:69]
	s_barrier
	s_add_i32 s34, s59, s36
	v_lshl_add_u64 v[154:155], v[154:155], 0, s[16:17]
	s_mov_b32 m0, s34
	ds_read_b128 v[188:191], v161 offset:49152
	ds_read_b128 v[192:195], v161 offset:50176
	ds_read_b128 v[196:199], v161 offset:51200
	ds_read_b128 v[200:203], v161 offset:52224
	ds_read_b128 v[204:207], v161 offset:53248
	ds_read_b128 v[208:211], v161 offset:54272
	ds_read_b128 v[212:215], v161 offset:55296
	ds_read_b128 v[216:219], v161 offset:56320
	global_load_lds_dwordx4 v[154:155], off
	s_add_i32 m0, s34, 0x2000
	s_add_u32 s30, s30, 0x80080
	v_lshl_add_u64 v[154:155], v[220:221], 0, s[16:17]
	s_addc_u32 s31, s31, 0
	s_add_i32 s34, s60, s36
	global_load_lds_dwordx4 v[154:155], off
	v_lshl_add_u64 v[154:155], s[30:31], 0, v[142:143]
	s_mov_b32 m0, s34
	s_nop 0
	global_load_lds_dwordx4 v[154:155], off
	v_lshl_add_u64 v[154:155], s[30:31], 0, v[138:139]
	s_add_i32 m0, s34, 0x2000
	s_nop 0
	global_load_lds_dwordx4 v[154:155], off
	v_lshl_add_u64 v[154:155], v[222:223], 0, s[16:17]
	s_mov_b32 m0, s45
	s_nop 0
	global_load_lds_dwordx4 v[154:155], off
	v_lshl_add_u64 v[154:155], v[224:225], 0, s[16:17]
	s_mov_b32 m0, s46
	s_nop 0
	global_load_lds_dwordx4 v[154:155], off
	s_waitcnt vmcnt(8)
	s_waitcnt lgkmcnt(0)
	s_barrier
	s_waitcnt lgkmcnt(0)
	v_mfma_f32_16x16x32_bf16 v[62:65], v[130:133], v[188:191], v[62:65]
	v_mfma_f32_16x16x32_bf16 v[58:61], v[164:167], v[188:191], v[58:61]
	v_mfma_f32_16x16x32_bf16 v[54:57], v[130:133], v[196:199], v[54:57]
	v_mfma_f32_16x16x32_bf16 v[46:49], v[164:167], v[196:199], v[46:49]
	v_mfma_f32_16x16x32_bf16 v[38:41], v[130:133], v[204:207], v[38:41]
	v_mfma_f32_16x16x32_bf16 v[30:33], v[164:167], v[204:207], v[30:33]
	v_mfma_f32_16x16x32_bf16 v[22:25], v[130:133], v[212:215], v[22:25]
	v_mfma_f32_16x16x32_bf16 v[14:17], v[164:167], v[212:215], v[14:17]
	v_mfma_f32_16x16x32_bf16 v[62:65], v[134:137], v[192:195], v[62:65]
	v_mfma_f32_16x16x32_bf16 v[58:61], v[168:171], v[192:195], v[58:61]
	v_mfma_f32_16x16x32_bf16 v[54:57], v[134:137], v[200:203], v[54:57]
	v_mfma_f32_16x16x32_bf16 v[46:49], v[168:171], v[200:203], v[46:49]
	v_mfma_f32_16x16x32_bf16 v[38:41], v[134:137], v[208:211], v[38:41]
	v_mfma_f32_16x16x32_bf16 v[30:33], v[168:171], v[208:211], v[30:33]
	v_mfma_f32_16x16x32_bf16 v[22:25], v[134:137], v[216:219], v[22:25]
	v_mfma_f32_16x16x32_bf16 v[14:17], v[168:171], v[216:219], v[14:17]
	v_mfma_f32_16x16x32_bf16 v[50:53], v[172:175], v[188:191], v[50:53]
	v_mfma_f32_16x16x32_bf16 v[42:45], v[180:183], v[188:191], v[42:45]
	v_mfma_f32_16x16x32_bf16 v[34:37], v[172:175], v[196:199], v[34:37]
	v_mfma_f32_16x16x32_bf16 v[26:29], v[180:183], v[196:199], v[26:29]
	v_mfma_f32_16x16x32_bf16 v[18:21], v[172:175], v[204:207], v[18:21]
	v_mfma_f32_16x16x32_bf16 v[10:13], v[180:183], v[204:207], v[10:13]
	v_mfma_f32_16x16x32_bf16 v[6:9], v[172:175], v[212:215], v[6:9]
	v_mfma_f32_16x16x32_bf16 v[2:5], v[180:183], v[212:215], v[2:5]
	v_mfma_f32_16x16x32_bf16 v[50:53], v[176:179], v[192:195], v[50:53]
	v_mfma_f32_16x16x32_bf16 v[42:45], v[184:187], v[192:195], v[42:45]
	v_mfma_f32_16x16x32_bf16 v[34:37], v[176:179], v[200:203], v[34:37]
	v_mfma_f32_16x16x32_bf16 v[26:29], v[184:187], v[200:203], v[26:29]
	v_mfma_f32_16x16x32_bf16 v[18:21], v[176:179], v[208:211], v[18:21]
	v_mfma_f32_16x16x32_bf16 v[10:13], v[184:187], v[208:211], v[10:13]
	v_mfma_f32_16x16x32_bf16 v[6:9], v[176:179], v[216:219], v[6:9]
	v_mfma_f32_16x16x32_bf16 v[2:5], v[184:187], v[216:219], v[2:5]
	s_barrier
	s_add_i32 s58, s58, 2
	s_add_u32 s6, s6, 0x100
	s_addc_u32 s7, s7, 0
	s_add_u32 s56, s56, 0x100
	s_addc_u32 s57, s57, 0
	s_cmp_gt_u32 s58, 29
	s_cbranch_scc0 .LBB0_910
	s_and_b64 vcc, exec, s[18:19]
	s_cbranch_vccz .LBB0_913
	s_barrier

.LBB0_1112:
	ds_read_b128 v[138:141], v143
	ds_read_b128 v[150:153], v143 offset:1024
	ds_read_b128 v[154:157], v143 offset:2048
	ds_read_b128 v[158:161], v143 offset:3072
	ds_read_b128 v[162:165], v144
	ds_read_b128 v[166:169], v144 offset:1024
	ds_read_b128 v[170:173], v144 offset:2048
	ds_read_b128 v[174:177], v144 offset:3072
	s_add_u32 s22, s20, 0x100
	s_addc_u32 s23, s21, 0
	s_add_u32 s24, s0, s20
	s_addc_u32 s25, s1, s21
	s_cmpk_eq_i32 s6, 0x54
	s_cselect_b32 s26, 0, s22
	s_cselect_b32 s27, 0, s23
	s_cselect_b32 s24, s16, s24
	s_cselect_b32 s25, s17, s25
	s_add_u32 s26, s2, s26
	s_addc_u32 s27, s3, s27
	s_mov_b32 m0, s41
	v_lshl_add_u64 v[210:211], v[134:135], 0, s[20:21]
	ds_read_b128 v[178:181], v145
	ds_read_b128 v[182:185], v145 offset:1024
	ds_read_b128 v[186:189], v145 offset:2048
	ds_read_b128 v[190:193], v145 offset:3072
	ds_read_b128 v[194:197], v145 offset:4096
	ds_read_b128 v[198:201], v145 offset:5120
	ds_read_b128 v[202:205], v145 offset:6144
	ds_read_b128 v[206:209], v145 offset:7168
	global_load_lds_dwordx4 v[210:211], off
	v_lshl_add_u64 v[210:211], v[136:137], 0, s[20:21]
	s_mov_b32 m0, s42
	s_nop 0
	global_load_lds_dwordx4 v[210:211], off
	s_waitcnt vmcnt(8)
	s_waitcnt lgkmcnt(0)
	s_barrier
	s_waitcnt lgkmcnt(0)
	v_mfma_f32_16x16x32_bf16 v[126:129], v[138:141], v[178:181], v[126:129]
	v_mfma_f32_16x16x32_bf16 v[122:125], v[154:157], v[178:181], v[122:125]
	v_mfma_f32_16x16x32_bf16 v[110:113], v[138:141], v[186:189], v[110:113]
	v_mfma_f32_16x16x32_bf16 v[106:109], v[154:157], v[186:189], v[106:109]
	v_mfma_f32_16x16x32_bf16 v[94:97], v[138:141], v[194:197], v[94:97]
	v_mfma_f32_16x16x32_bf16 v[90:93], v[154:157], v[194:197], v[90:93]
	v_mfma_f32_16x16x32_bf16 v[78:81], v[138:141], v[202:205], v[78:81]
	v_mfma_f32_16x16x32_bf16 v[74:77], v[154:157], v[202:205], v[74:77]
	v_mfma_f32_16x16x32_bf16 v[126:129], v[150:153], v[182:185], v[126:129]
	v_mfma_f32_16x16x32_bf16 v[122:125], v[158:161], v[182:185], v[122:125]
	v_mfma_f32_16x16x32_bf16 v[110:113], v[150:153], v[190:193], v[110:113]
	v_mfma_f32_16x16x32_bf16 v[106:109], v[158:161], v[190:193], v[106:109]
	v_mfma_f32_16x16x32_bf16 v[94:97], v[150:153], v[198:201], v[94:97]
	v_mfma_f32_16x16x32_bf16 v[90:93], v[158:161], v[198:201], v[90:93]
	v_mfma_f32_16x16x32_bf16 v[78:81], v[150:153], v[206:209], v[78:81]
	v_mfma_f32_16x16x32_bf16 v[74:77], v[158:161], v[206:209], v[74:77]
	v_mfma_f32_16x16x32_bf16 v[118:121], v[162:165], v[178:181], v[118:121]
	v_mfma_f32_16x16x32_bf16 v[114:117], v[170:173], v[178:181], v[114:117]
	v_mfma_f32_16x16x32_bf16 v[102:105], v[162:165], v[186:189], v[102:105]
	v_mfma_f32_16x16x32_bf16 v[98:101], v[170:173], v[186:189], v[98:101]
	v_mfma_f32_16x16x32_bf16 v[86:89], v[162:165], v[194:197], v[86:89]
	v_mfma_f32_16x16x32_bf16 v[82:85], v[170:173], v[194:197], v[82:85]
	v_mfma_f32_16x16x32_bf16 v[70:73], v[162:165], v[202:205], v[70:73]
	v_mfma_f32_16x16x32_bf16 v[66:69], v[170:173], v[202:205], v[66:69]
	v_mfma_f32_16x16x32_bf16 v[118:121], v[166:169], v[182:185], v[118:121]
	v_mfma_f32_16x16x32_bf16 v[114:117], v[174:177], v[182:185], v[114:117]
	v_mfma_f32_16x16x32_bf16 v[102:105], v[166:169], v[190:193], v[102:105]
	v_mfma_f32_16x16x32_bf16 v[98:101], v[174:177], v[190:193], v[98:101]
	v_mfma_f32_16x16x32_bf16 v[86:89], v[166:169], v[198:201], v[86:89]
	v_mfma_f32_16x16x32_bf16 v[82:85], v[174:177], v[198:201], v[82:85]
	v_mfma_f32_16x16x32_bf16 v[70:73], v[166:169], v[206:209], v[70:73]
	v_mfma_f32_16x16x32_bf16 v[66:69], v[174:177], v[206:209], v[66:69]
	s_barrier
	s_mov_b32 m0, s43
	v_lshl_add_u64 v[210:211], s[24:25], 0, v[132:133]
	s_add_u32 s20, s24, 0x160000
	ds_read_b128 v[178:181], v145 offset:16384
	ds_read_b128 v[182:185], v145 offset:17408
	ds_read_b128 v[186:189], v145 offset:18432
	ds_read_b128 v[190:193], v145 offset:19456
	ds_read_b128 v[194:197], v145 offset:20480
	ds_read_b128 v[198:201], v145 offset:21504
	ds_read_b128 v[202:205], v145 offset:22528
	ds_read_b128 v[206:209], v145 offset:23552
	global_load_lds_dwordx4 v[210:211], off
	v_lshl_add_u64 v[212:213], s[24:25], 0, v[130:131]
	s_mov_b32 m0, s44
	s_addc_u32 s21, s25, 0
	global_load_lds_dwordx4 v[212:213], off
	v_lshl_add_u64 v[214:215], s[20:21], 0, v[132:133]
	s_mov_b32 m0, s45
	v_lshl_add_u64 v[216:217], s[26:27], 0, v[130:131]
	global_load_lds_dwordx4 v[214:215], off
	v_lshl_add_u64 v[214:215], s[20:21], 0, v[130:131]
	s_mov_b32 m0, s46
	s_nop 0
	global_load_lds_dwordx4 v[214:215], off
	v_lshl_add_u64 v[214:215], s[26:27], 0, v[132:133]
	s_mov_b32 m0, s30
	s_nop 0
	global_load_lds_dwordx4 v[214:215], off
	s_mov_b32 m0, s31
	s_nop 0
	global_load_lds_dwordx4 v[216:217], off
	s_waitcnt vmcnt(8)
	s_waitcnt lgkmcnt(0)
	s_barrier
	s_waitcnt lgkmcnt(0)
	v_mfma_f32_16x16x32_bf16 v[62:65], v[138:141], v[178:181], v[62:65]
	v_mfma_f32_16x16x32_bf16 v[58:61], v[154:157], v[178:181], v[58:61]
	v_mfma_f32_16x16x32_bf16 v[46:49], v[138:141], v[186:189], v[46:49]
	v_mfma_f32_16x16x32_bf16 v[42:45], v[154:157], v[186:189], v[42:45]
	v_mfma_f32_16x16x32_bf16 v[30:33], v[138:141], v[194:197], v[30:33]
	v_mfma_f32_16x16x32_bf16 v[26:29], v[154:157], v[194:197], v[26:29]
	v_mfma_f32_16x16x32_bf16 v[14:17], v[138:141], v[202:205], v[14:17]
	v_mfma_f32_16x16x32_bf16 v[10:13], v[154:157], v[202:205], v[10:13]
	v_mfma_f32_16x16x32_bf16 v[62:65], v[150:153], v[182:185], v[62:65]
	v_mfma_f32_16x16x32_bf16 v[58:61], v[158:161], v[182:185], v[58:61]
	v_mfma_f32_16x16x32_bf16 v[46:49], v[150:153], v[190:193], v[46:49]
	v_mfma_f32_16x16x32_bf16 v[42:45], v[158:161], v[190:193], v[42:45]
	v_mfma_f32_16x16x32_bf16 v[30:33], v[150:153], v[198:201], v[30:33]
	v_mfma_f32_16x16x32_bf16 v[26:29], v[158:161], v[198:201], v[26:29]
	v_mfma_f32_16x16x32_bf16 v[14:17], v[150:153], v[206:209], v[14:17]
	v_mfma_f32_16x16x32_bf16 v[10:13], v[158:161], v[206:209], v[10:13]
	v_mfma_f32_16x16x32_bf16 v[54:57], v[162:165], v[178:181], v[54:57]
	v_mfma_f32_16x16x32_bf16 v[50:53], v[170:173], v[178:181], v[50:53]
	v_mfma_f32_16x16x32_bf16 v[38:41], v[162:165], v[186:189], v[38:41]
	v_mfma_f32_16x16x32_bf16 v[34:37], v[170:173], v[186:189], v[34:37]
	v_mfma_f32_16x16x32_bf16 v[22:25], v[162:165], v[194:197], v[22:25]
	v_mfma_f32_16x16x32_bf16 v[18:21], v[170:173], v[194:197], v[18:21]
	v_mfma_f32_16x16x32_bf16 v[6:9], v[162:165], v[202:205], v[6:9]
	v_mfma_f32_16x16x32_bf16 v[2:5], v[170:173], v[202:205], v[2:5]
	v_mfma_f32_16x16x32_bf16 v[54:57], v[166:169], v[182:185], v[54:57]
	v_mfma_f32_16x16x32_bf16 v[50:53], v[174:177], v[182:185], v[50:53]
	v_mfma_f32_16x16x32_bf16 v[38:41], v[166:169], v[190:193], v[38:41]
	v_mfma_f32_16x16x32_bf16 v[34:37], v[174:177], v[190:193], v[34:37]
	v_mfma_f32_16x16x32_bf16 v[22:25], v[166:169], v[198:201], v[22:25]
	v_mfma_f32_16x16x32_bf16 v[18:21], v[174:177], v[198:201], v[18:21]
	v_mfma_f32_16x16x32_bf16 v[6:9], v[166:169], v[206:209], v[6:9]
	v_mfma_f32_16x16x32_bf16 v[2:5], v[174:177], v[206:209], v[2:5]
	s_barrier
	ds_read_b128 v[138:141], v147
	ds_read_b128 v[150:153], v147 offset:1024
	ds_read_b128 v[154:157], v147 offset:2048
	ds_read_b128 v[158:161], v147 offset:3072
	ds_read_b128 v[162:165], v148
	ds_read_b128 v[166:169], v148 offset:1024
	ds_read_b128 v[170:173], v148 offset:2048
	ds_read_b128 v[174:177], v148 offset:3072
	s_add_u32 s20, s26, 0x160000
	s_addc_u32 s21, s27, 0
	s_mov_b32 m0, s33
	v_lshl_add_u64 v[218:219], s[20:21], 0, v[132:133]
	ds_read_b128 v[178:181], v145 offset:32768
	ds_read_b128 v[182:185], v145 offset:33792
	ds_read_b128 v[186:189], v145 offset:34816
	ds_read_b128 v[190:193], v145 offset:35840
	ds_read_b128 v[194:197], v145 offset:36864
	ds_read_b128 v[198:201], v145 offset:37888
	ds_read_b128 v[202:205], v145 offset:38912
	ds_read_b128 v[206:209], v145 offset:39936
	global_load_lds_dwordx4 v[218:219], off
	v_lshl_add_u64 v[218:219], s[20:21], 0, v[130:131]
	s_mov_b32 m0, s34
	s_nop 0
	global_load_lds_dwordx4 v[218:219], off
	s_waitcnt vmcnt(8)
	s_waitcnt lgkmcnt(0)
	s_barrier
	s_waitcnt lgkmcnt(0)
	v_mfma_f32_16x16x32_bf16 v[126:129], v[138:141], v[178:181], v[126:129]
	v_mfma_f32_16x16x32_bf16 v[122:125], v[154:157], v[178:181], v[122:125]
	v_mfma_f32_16x16x32_bf16 v[110:113], v[138:141], v[186:189], v[110:113]
	v_mfma_f32_16x16x32_bf16 v[106:109], v[154:157], v[186:189], v[106:109]
	v_mfma_f32_16x16x32_bf16 v[94:97], v[138:141], v[194:197], v[94:97]
	v_mfma_f32_16x16x32_bf16 v[90:93], v[154:157], v[194:197], v[90:93]
	v_mfma_f32_16x16x32_bf16 v[78:81], v[138:141], v[202:205], v[78:81]
	v_mfma_f32_16x16x32_bf16 v[74:77], v[154:157], v[202:205], v[74:77]
	v_mfma_f32_16x16x32_bf16 v[126:129], v[150:153], v[182:185], v[126:129]
	v_mfma_f32_16x16x32_bf16 v[122:125], v[158:161], v[182:185], v[122:125]
	v_mfma_f32_16x16x32_bf16 v[110:113], v[150:153], v[190:193], v[110:113]
	v_mfma_f32_16x16x32_bf16 v[106:109], v[158:161], v[190:193], v[106:109]
	v_mfma_f32_16x16x32_bf16 v[94:97], v[150:153], v[198:201], v[94:97]
	v_mfma_f32_16x16x32_bf16 v[90:93], v[158:161], v[198:201], v[90:93]
	v_mfma_f32_16x16x32_bf16 v[78:81], v[150:153], v[206:209], v[78:81]
	v_mfma_f32_16x16x32_bf16 v[74:77], v[158:161], v[206:209], v[74:77]
	v_mfma_f32_16x16x32_bf16 v[118:121], v[162:165], v[178:181], v[118:121]
	v_mfma_f32_16x16x32_bf16 v[114:117], v[170:173], v[178:181], v[114:117]
	v_mfma_f32_16x16x32_bf16 v[102:105], v[162:165], v[186:189], v[102:105]
	v_mfma_f32_16x16x32_bf16 v[98:101], v[170:173], v[186:189], v[98:101]
	v_mfma_f32_16x16x32_bf16 v[86:89], v[162:165], v[194:197], v[86:89]
	v_mfma_f32_16x16x32_bf16 v[82:85], v[170:173], v[194:197], v[82:85]
	v_mfma_f32_16x16x32_bf16 v[70:73], v[162:165], v[202:205], v[70:73]
	v_mfma_f32_16x16x32_bf16 v[66:69], v[170:173], v[202:205], v[66:69]
	v_mfma_f32_16x16x32_bf16 v[118:121], v[166:169], v[182:185], v[118:121]
	v_mfma_f32_16x16x32_bf16 v[114:117], v[174:177], v[182:185], v[114:117]
	v_mfma_f32_16x16x32_bf16 v[102:105], v[166:169], v[190:193], v[102:105]
	v_mfma_f32_16x16x32_bf16 v[98:101], v[174:177], v[190:193], v[98:101]
	v_mfma_f32_16x16x32_bf16 v[86:89], v[166:169], v[198:201], v[86:89]
	v_mfma_f32_16x16x32_bf16 v[82:85], v[174:177], v[198:201], v[82:85]
	v_mfma_f32_16x16x32_bf16 v[70:73], v[166:169], v[206:209], v[70:73]
	v_mfma_f32_16x16x32_bf16 v[66:69], v[174:177], v[206:209], v[66:69]
	s_barrier
	s_mov_b32 m0, s47
	v_lshl_add_u64 v[210:211], v[210:211], 0, s[12:13]
	s_add_u32 s20, s24, 0x160080
	ds_read_b128 v[178:181], v145 offset:49152
	ds_read_b128 v[182:185], v145 offset:50176
	ds_read_b128 v[186:189], v145 offset:51200
	ds_read_b128 v[190:193], v145 offset:52224
	ds_read_b128 v[194:197], v145 offset:53248
	ds_read_b128 v[198:201], v145 offset:54272
	ds_read_b128 v[202:205], v145 offset:55296
	ds_read_b128 v[206:209], v145 offset:56320
	global_load_lds_dwordx4 v[210:211], off
	v_lshl_add_u64 v[210:211], v[212:213], 0, s[12:13]
	s_mov_b32 m0, s48
	s_addc_u32 s21, s25, 0
	global_load_lds_dwordx4 v[210:211], off
	v_lshl_add_u64 v[210:211], s[20:21], 0, v[132:133]
	s_mov_b32 m0, s49
	s_nop 0
	global_load_lds_dwordx4 v[210:211], off
	v_lshl_add_u64 v[210:211], s[20:21], 0, v[130:131]
	s_mov_b32 m0, s50
	s_nop 0
	global_load_lds_dwordx4 v[210:211], off
	v_lshl_add_u64 v[210:211], v[214:215], 0, s[12:13]
	s_mov_b32 m0, s37
	s_nop 0
	global_load_lds_dwordx4 v[210:211], off
	v_lshl_add_u64 v[210:211], v[216:217], 0, s[12:13]
	s_mov_b32 m0, s39
	s_nop 0
	global_load_lds_dwordx4 v[210:211], off
	s_waitcnt vmcnt(8)
	s_waitcnt lgkmcnt(0)
	s_barrier
	s_waitcnt lgkmcnt(0)
	v_mfma_f32_16x16x32_bf16 v[62:65], v[138:141], v[178:181], v[62:65]
	v_mfma_f32_16x16x32_bf16 v[58:61], v[154:157], v[178:181], v[58:61]
	v_mfma_f32_16x16x32_bf16 v[46:49], v[138:141], v[186:189], v[46:49]
	v_mfma_f32_16x16x32_bf16 v[42:45], v[154:157], v[186:189], v[42:45]
	v_mfma_f32_16x16x32_bf16 v[30:33], v[138:141], v[194:197], v[30:33]
	v_mfma_f32_16x16x32_bf16 v[26:29], v[154:157], v[194:197], v[26:29]
	v_mfma_f32_16x16x32_bf16 v[14:17], v[138:141], v[202:205], v[14:17]
	v_mfma_f32_16x16x32_bf16 v[10:13], v[154:157], v[202:205], v[10:13]
	v_mfma_f32_16x16x32_bf16 v[62:65], v[150:153], v[182:185], v[62:65]
	v_mfma_f32_16x16x32_bf16 v[58:61], v[158:161], v[182:185], v[58:61]
	v_mfma_f32_16x16x32_bf16 v[46:49], v[150:153], v[190:193], v[46:49]
	v_mfma_f32_16x16x32_bf16 v[42:45], v[158:161], v[190:193], v[42:45]
	v_mfma_f32_16x16x32_bf16 v[30:33], v[150:153], v[198:201], v[30:33]
	v_mfma_f32_16x16x32_bf16 v[26:29], v[158:161], v[198:201], v[26:29]
	v_mfma_f32_16x16x32_bf16 v[14:17], v[150:153], v[206:209], v[14:17]
	v_mfma_f32_16x16x32_bf16 v[10:13], v[158:161], v[206:209], v[10:13]
	v_mfma_f32_16x16x32_bf16 v[54:57], v[162:165], v[178:181], v[54:57]
	v_mfma_f32_16x16x32_bf16 v[50:53], v[170:173], v[178:181], v[50:53]
	v_mfma_f32_16x16x32_bf16 v[38:41], v[162:165], v[186:189], v[38:41]
	v_mfma_f32_16x16x32_bf16 v[34:37], v[170:173], v[186:189], v[34:37]
	v_mfma_f32_16x16x32_bf16 v[22:25], v[162:165], v[194:197], v[22:25]
	v_mfma_f32_16x16x32_bf16 v[18:21], v[170:173], v[194:197], v[18:21]
	v_mfma_f32_16x16x32_bf16 v[6:9], v[162:165], v[202:205], v[6:9]
	v_mfma_f32_16x16x32_bf16 v[2:5], v[170:173], v[202:205], v[2:5]
	v_mfma_f32_16x16x32_bf16 v[54:57], v[166:169], v[182:185], v[54:57]
	v_mfma_f32_16x16x32_bf16 v[50:53], v[174:177], v[182:185], v[50:53]
	v_mfma_f32_16x16x32_bf16 v[38:41], v[166:169], v[190:193], v[38:41]
	v_mfma_f32_16x16x32_bf16 v[34:37], v[174:177], v[190:193], v[34:37]
	v_mfma_f32_16x16x32_bf16 v[22:25], v[166:169], v[198:201], v[22:25]
	v_mfma_f32_16x16x32_bf16 v[18:21], v[174:177], v[198:201], v[18:21]
	v_mfma_f32_16x16x32_bf16 v[6:9], v[166:169], v[206:209], v[6:9]
	v_mfma_f32_16x16x32_bf16 v[2:5], v[174:177], v[206:209], v[2:5]
	s_barrier
	s_add_i32 s6, s6, 2
	s_cmpk_gt_u32 s6, 0x55
	s_mov_b64 s[20:21], s[22:23]
	s_cbranch_scc0 .LBB0_1112
	s_and_b64 vcc, exec, s[14:15]
	s_cbranch_vccz .LBB0_1115
	s_barrier

.LBB0_1199:
	ds_read_b128 v[130:133], v169
	ds_read_b128 v[134:137], v169 offset:1024
	ds_read_b128 v[150:153], v169 offset:2048
	ds_read_b128 v[154:157], v169 offset:3072
	ds_read_b128 v[158:161], v170
	ds_read_b128 v[162:165], v170 offset:1024
	ds_read_b128 v[174:177], v170 offset:2048
	ds_read_b128 v[178:181], v170 offset:3072
	s_add_u32 s6, s0, 0xfff80080
	s_addc_u32 s7, s1, -1
	s_cmp_eq_u32 s54, 28
	s_cselect_b32 s27, s11, s7
	s_cselect_b32 s26, s10, s6
	s_cselect_b32 s7, s29, s53
	s_cselect_b32 s6, s30, s31
	s_mov_b32 m0, s48
	v_lshl_add_u64 v[166:167], s[0:1], 0, v[144:145]
	ds_read_b128 v[182:185], v171
	ds_read_b128 v[186:189], v171 offset:1024
	ds_read_b128 v[190:193], v171 offset:2048
	ds_read_b128 v[194:197], v171 offset:3072
	ds_read_b128 v[198:201], v171 offset:4096
	ds_read_b128 v[202:205], v171 offset:5120
	ds_read_b128 v[206:209], v171 offset:6144
	ds_read_b128 v[210:213], v171 offset:7168
	global_load_lds_dwordx4 v[166:167], off
	v_lshl_add_u64 v[166:167], s[0:1], 0, v[146:147]
	s_mov_b32 m0, s49
	s_nop 0
	global_load_lds_dwordx4 v[166:167], off
	s_waitcnt vmcnt(8)
	s_waitcnt lgkmcnt(0)
	s_barrier
	s_waitcnt lgkmcnt(0)
	v_mfma_f32_16x16x32_bf16 v[126:129], v[130:133], v[182:185], v[126:129]
	v_mfma_f32_16x16x32_bf16 v[122:125], v[150:153], v[182:185], v[122:125]
	v_mfma_f32_16x16x32_bf16 v[110:113], v[130:133], v[190:193], v[110:113]
	v_mfma_f32_16x16x32_bf16 v[106:109], v[150:153], v[190:193], v[106:109]
	v_mfma_f32_16x16x32_bf16 v[94:97], v[130:133], v[198:201], v[94:97]
	v_mfma_f32_16x16x32_bf16 v[90:93], v[150:153], v[198:201], v[90:93]
	v_mfma_f32_16x16x32_bf16 v[78:81], v[130:133], v[206:209], v[78:81]
	v_mfma_f32_16x16x32_bf16 v[74:77], v[150:153], v[206:209], v[74:77]
	v_mfma_f32_16x16x32_bf16 v[126:129], v[134:137], v[186:189], v[126:129]
	v_mfma_f32_16x16x32_bf16 v[122:125], v[154:157], v[186:189], v[122:125]
	v_mfma_f32_16x16x32_bf16 v[110:113], v[134:137], v[194:197], v[110:113]
	v_mfma_f32_16x16x32_bf16 v[106:109], v[154:157], v[194:197], v[106:109]
	v_mfma_f32_16x16x32_bf16 v[94:97], v[134:137], v[202:205], v[94:97]
	v_mfma_f32_16x16x32_bf16 v[90:93], v[154:157], v[202:205], v[90:93]
	v_mfma_f32_16x16x32_bf16 v[78:81], v[134:137], v[210:213], v[78:81]
	v_mfma_f32_16x16x32_bf16 v[74:77], v[154:157], v[210:213], v[74:77]
	v_mfma_f32_16x16x32_bf16 v[118:121], v[158:161], v[182:185], v[118:121]
	v_mfma_f32_16x16x32_bf16 v[114:117], v[174:177], v[182:185], v[114:117]
	v_mfma_f32_16x16x32_bf16 v[102:105], v[158:161], v[190:193], v[102:105]
	v_mfma_f32_16x16x32_bf16 v[98:101], v[174:177], v[190:193], v[98:101]
	v_mfma_f32_16x16x32_bf16 v[86:89], v[158:161], v[198:201], v[86:89]
	v_mfma_f32_16x16x32_bf16 v[82:85], v[174:177], v[198:201], v[82:85]
	v_mfma_f32_16x16x32_bf16 v[70:73], v[158:161], v[206:209], v[70:73]
	v_mfma_f32_16x16x32_bf16 v[66:69], v[174:177], v[206:209], v[66:69]
	v_mfma_f32_16x16x32_bf16 v[118:121], v[162:165], v[186:189], v[118:121]
	v_mfma_f32_16x16x32_bf16 v[114:117], v[178:181], v[186:189], v[114:117]
	v_mfma_f32_16x16x32_bf16 v[102:105], v[162:165], v[194:197], v[102:105]
	v_mfma_f32_16x16x32_bf16 v[98:101], v[178:181], v[194:197], v[98:101]
	v_mfma_f32_16x16x32_bf16 v[86:89], v[162:165], v[202:205], v[86:89]
	v_mfma_f32_16x16x32_bf16 v[82:85], v[178:181], v[202:205], v[82:85]
	v_mfma_f32_16x16x32_bf16 v[70:73], v[162:165], v[210:213], v[70:73]
	v_mfma_f32_16x16x32_bf16 v[66:69], v[178:181], v[210:213], v[66:69]
	s_barrier
	s_add_i32 s55, s46, s34
	v_lshl_add_u64 v[166:167], s[6:7], 0, v[140:141]
	s_mov_b32 m0, s55
	ds_read_b128 v[182:185], v171 offset:16384
	ds_read_b128 v[186:189], v171 offset:17408
	ds_read_b128 v[190:193], v171 offset:18432
	ds_read_b128 v[194:197], v171 offset:19456
	ds_read_b128 v[198:201], v171 offset:20480
	ds_read_b128 v[202:205], v171 offset:21504
	ds_read_b128 v[206:209], v171 offset:22528
	ds_read_b128 v[210:213], v171 offset:23552
	global_load_lds_dwordx4 v[166:167], off
	s_add_i32 m0, s55, 0x2000
	s_add_u32 s56, s6, 0x80000
	v_lshl_add_u64 v[214:215], s[6:7], 0, v[138:139]
	s_addc_u32 s57, s7, 0
	s_add_i32 s55, s47, s34
	global_load_lds_dwordx4 v[214:215], off
	v_lshl_add_u64 v[216:217], s[56:57], 0, v[140:141]
	s_mov_b32 m0, s55
	v_lshl_add_u64 v[218:219], s[26:27], 0, v[138:139]
	global_load_lds_dwordx4 v[216:217], off
	v_lshl_add_u64 v[216:217], s[56:57], 0, v[138:139]
	s_add_i32 m0, s55, 0x2000
	s_nop 0
	global_load_lds_dwordx4 v[216:217], off
	v_lshl_add_u64 v[216:217], s[26:27], 0, v[140:141]
	s_mov_b32 m0, s35
	s_nop 0
	global_load_lds_dwordx4 v[216:217], off
	s_mov_b32 m0, s36
	s_nop 0
	global_load_lds_dwordx4 v[218:219], off
	s_waitcnt vmcnt(8)
	s_waitcnt lgkmcnt(0)
	s_barrier
	s_waitcnt lgkmcnt(0)
	v_mfma_f32_16x16x32_bf16 v[62:65], v[130:133], v[182:185], v[62:65]
	v_mfma_f32_16x16x32_bf16 v[58:61], v[150:153], v[182:185], v[58:61]
	v_mfma_f32_16x16x32_bf16 v[46:49], v[130:133], v[190:193], v[46:49]
	v_mfma_f32_16x16x32_bf16 v[42:45], v[150:153], v[190:193], v[42:45]
	v_mfma_f32_16x16x32_bf16 v[30:33], v[130:133], v[198:201], v[30:33]
	v_mfma_f32_16x16x32_bf16 v[26:29], v[150:153], v[198:201], v[26:29]
	v_mfma_f32_16x16x32_bf16 v[14:17], v[130:133], v[206:209], v[14:17]
	v_mfma_f32_16x16x32_bf16 v[10:13], v[150:153], v[206:209], v[10:13]
	v_mfma_f32_16x16x32_bf16 v[62:65], v[134:137], v[186:189], v[62:65]
	v_mfma_f32_16x16x32_bf16 v[58:61], v[154:157], v[186:189], v[58:61]
	v_mfma_f32_16x16x32_bf16 v[46:49], v[134:137], v[194:197], v[46:49]
	v_mfma_f32_16x16x32_bf16 v[42:45], v[154:157], v[194:197], v[42:45]
	v_mfma_f32_16x16x32_bf16 v[30:33], v[134:137], v[202:205], v[30:33]
	v_mfma_f32_16x16x32_bf16 v[26:29], v[154:157], v[202:205], v[26:29]
	v_mfma_f32_16x16x32_bf16 v[14:17], v[134:137], v[210:213], v[14:17]
	v_mfma_f32_16x16x32_bf16 v[10:13], v[154:157], v[210:213], v[10:13]
	v_mfma_f32_16x16x32_bf16 v[54:57], v[158:161], v[182:185], v[54:57]
	v_mfma_f32_16x16x32_bf16 v[50:53], v[174:177], v[182:185], v[50:53]
	v_mfma_f32_16x16x32_bf16 v[38:41], v[158:161], v[190:193], v[38:41]
	v_mfma_f32_16x16x32_bf16 v[34:37], v[174:177], v[190:193], v[34:37]
	v_mfma_f32_16x16x32_bf16 v[22:25], v[158:161], v[198:201], v[22:25]
	v_mfma_f32_16x16x32_bf16 v[18:21], v[174:177], v[198:201], v[18:21]
	v_mfma_f32_16x16x32_bf16 v[6:9], v[158:161], v[206:209], v[6:9]
	v_mfma_f32_16x16x32_bf16 v[2:5], v[174:177], v[206:209], v[2:5]
	v_mfma_f32_16x16x32_bf16 v[54:57], v[162:165], v[186:189], v[54:57]
	v_mfma_f32_16x16x32_bf16 v[50:53], v[178:181], v[186:189], v[50:53]
	v_mfma_f32_16x16x32_bf16 v[38:41], v[162:165], v[194:197], v[38:41]
	v_mfma_f32_16x16x32_bf16 v[34:37], v[178:181], v[194:197], v[34:37]
	v_mfma_f32_16x16x32_bf16 v[22:25], v[162:165], v[202:205], v[22:25]
	v_mfma_f32_16x16x32_bf16 v[18:21], v[178:181], v[202:205], v[18:21]
	v_mfma_f32_16x16x32_bf16 v[6:9], v[162:165], v[210:213], v[6:9]
	v_mfma_f32_16x16x32_bf16 v[2:5], v[178:181], v[210:213], v[2:5]
	s_barrier
	s_add_i32 s55, 0, 0x18000
	v_add_u32_e32 v142, s55, v168
	s_add_i32 s56, 0, 0x1c000
	ds_read_b128 v[130:133], v142
	ds_read_b128 v[134:137], v142 offset:1024
	ds_read_b128 v[150:153], v142 offset:2048
	ds_read_b128 v[154:157], v142 offset:3072
	v_add_u32_e32 v142, s56, v168
	ds_read_b128 v[158:161], v142
	ds_read_b128 v[162:165], v142 offset:1024
	ds_read_b128 v[174:177], v142 offset:2048
	ds_read_b128 v[178:181], v142 offset:3072
	s_add_u32 s26, s26, 0x80000
	s_addc_u32 s27, s27, 0
	s_mov_b32 m0, s37
	v_lshl_add_u64 v[220:221], s[26:27], 0, v[140:141]
	ds_read_b128 v[182:185], v171 offset:32768
	ds_read_b128 v[186:189], v171 offset:33792
	ds_read_b128 v[190:193], v171 offset:34816
	ds_read_b128 v[194:197], v171 offset:35840
	ds_read_b128 v[198:201], v171 offset:36864
	ds_read_b128 v[202:205], v171 offset:37888
	ds_read_b128 v[206:209], v171 offset:38912
	ds_read_b128 v[210:213], v171 offset:39936
	global_load_lds_dwordx4 v[220:221], off
	v_lshl_add_u64 v[220:221], s[26:27], 0, v[138:139]
	s_mov_b32 m0, s39
	s_nop 0
	global_load_lds_dwordx4 v[220:221], off
	s_waitcnt vmcnt(8)
	s_waitcnt lgkmcnt(0)
	s_barrier
	s_waitcnt lgkmcnt(0)
	v_mfma_f32_16x16x32_bf16 v[126:129], v[130:133], v[182:185], v[126:129]
	v_mfma_f32_16x16x32_bf16 v[122:125], v[150:153], v[182:185], v[122:125]
	v_mfma_f32_16x16x32_bf16 v[110:113], v[130:133], v[190:193], v[110:113]
	v_mfma_f32_16x16x32_bf16 v[106:109], v[150:153], v[190:193], v[106:109]
	v_mfma_f32_16x16x32_bf16 v[94:97], v[130:133], v[198:201], v[94:97]
	v_mfma_f32_16x16x32_bf16 v[90:93], v[150:153], v[198:201], v[90:93]
	v_mfma_f32_16x16x32_bf16 v[78:81], v[130:133], v[206:209], v[78:81]
	v_mfma_f32_16x16x32_bf16 v[74:77], v[150:153], v[206:209], v[74:77]
	v_mfma_f32_16x16x32_bf16 v[126:129], v[134:137], v[186:189], v[126:129]
	v_mfma_f32_16x16x32_bf16 v[122:125], v[154:157], v[186:189], v[122:125]
	v_mfma_f32_16x16x32_bf16 v[110:113], v[134:137], v[194:197], v[110:113]
	v_mfma_f32_16x16x32_bf16 v[106:109], v[154:157], v[194:197], v[106:109]
	v_mfma_f32_16x16x32_bf16 v[94:97], v[134:137], v[202:205], v[94:97]
	v_mfma_f32_16x16x32_bf16 v[90:93], v[154:157], v[202:205], v[90:93]
	v_mfma_f32_16x16x32_bf16 v[78:81], v[134:137], v[210:213], v[78:81]
	v_mfma_f32_16x16x32_bf16 v[74:77], v[154:157], v[210:213], v[74:77]
	v_mfma_f32_16x16x32_bf16 v[118:121], v[158:161], v[182:185], v[118:121]
	v_mfma_f32_16x16x32_bf16 v[114:117], v[174:177], v[182:185], v[114:117]
	v_mfma_f32_16x16x32_bf16 v[102:105], v[158:161], v[190:193], v[102:105]
	v_mfma_f32_16x16x32_bf16 v[98:101], v[174:177], v[190:193], v[98:101]
	v_mfma_f32_16x16x32_bf16 v[86:89], v[158:161], v[198:201], v[86:89]
	v_mfma_f32_16x16x32_bf16 v[82:85], v[174:177], v[198:201], v[82:85]
	v_mfma_f32_16x16x32_bf16 v[70:73], v[158:161], v[206:209], v[70:73]
	v_mfma_f32_16x16x32_bf16 v[66:69], v[174:177], v[206:209], v[66:69]
	v_mfma_f32_16x16x32_bf16 v[118:121], v[162:165], v[186:189], v[118:121]
	v_mfma_f32_16x16x32_bf16 v[114:117], v[178:181], v[186:189], v[114:117]
	v_mfma_f32_16x16x32_bf16 v[102:105], v[162:165], v[194:197], v[102:105]
	v_mfma_f32_16x16x32_bf16 v[98:101], v[178:181], v[194:197], v[98:101]
	v_mfma_f32_16x16x32_bf16 v[86:89], v[162:165], v[202:205], v[86:89]
	v_mfma_f32_16x16x32_bf16 v[82:85], v[178:181], v[202:205], v[82:85]
	v_mfma_f32_16x16x32_bf16 v[70:73], v[162:165], v[210:213], v[70:73]
	v_mfma_f32_16x16x32_bf16 v[66:69], v[178:181], v[210:213], v[66:69]
	s_barrier
	s_add_i32 s26, s55, s34
	v_lshl_add_u64 v[166:167], v[166:167], 0, s[14:15]
	s_mov_b32 m0, s26
	ds_read_b128 v[182:185], v171 offset:49152
	ds_read_b128 v[186:189], v171 offset:50176
	ds_read_b128 v[190:193], v171 offset:51200
	ds_read_b128 v[194:197], v171 offset:52224
	ds_read_b128 v[198:201], v171 offset:53248
	ds_read_b128 v[202:205], v171 offset:54272
	ds_read_b128 v[206:209], v171 offset:55296
	ds_read_b128 v[210:213], v171 offset:56320
	global_load_lds_dwordx4 v[166:167], off
	s_add_i32 m0, s26, 0x2000
	s_add_u32 s6, s6, 0x80080
	v_lshl_add_u64 v[166:167], v[214:215], 0, s[14:15]
	s_addc_u32 s7, s7, 0
	s_add_i32 s26, s56, s34
	global_load_lds_dwordx4 v[166:167], off
	v_lshl_add_u64 v[166:167], s[6:7], 0, v[140:141]
	s_mov_b32 m0, s26
	s_nop 0
	global_load_lds_dwordx4 v[166:167], off
	v_lshl_add_u64 v[166:167], s[6:7], 0, v[138:139]
	s_add_i32 m0, s26, 0x2000
	s_nop 0
	global_load_lds_dwordx4 v[166:167], off
	v_lshl_add_u64 v[166:167], v[216:217], 0, s[14:15]
	s_mov_b32 m0, s43
	s_nop 0
	global_load_lds_dwordx4 v[166:167], off
	v_lshl_add_u64 v[166:167], v[218:219], 0, s[14:15]
	s_mov_b32 m0, s44
	s_nop 0
	global_load_lds_dwordx4 v[166:167], off
	s_waitcnt vmcnt(8)
	s_waitcnt lgkmcnt(0)
	s_barrier
	s_waitcnt lgkmcnt(0)
	v_mfma_f32_16x16x32_bf16 v[62:65], v[130:133], v[182:185], v[62:65]
	v_mfma_f32_16x16x32_bf16 v[58:61], v[150:153], v[182:185], v[58:61]
	v_mfma_f32_16x16x32_bf16 v[46:49], v[130:133], v[190:193], v[46:49]
	v_mfma_f32_16x16x32_bf16 v[42:45], v[150:153], v[190:193], v[42:45]
	v_mfma_f32_16x16x32_bf16 v[30:33], v[130:133], v[198:201], v[30:33]
	v_mfma_f32_16x16x32_bf16 v[26:29], v[150:153], v[198:201], v[26:29]
	v_mfma_f32_16x16x32_bf16 v[14:17], v[130:133], v[206:209], v[14:17]
	v_mfma_f32_16x16x32_bf16 v[10:13], v[150:153], v[206:209], v[10:13]
	v_mfma_f32_16x16x32_bf16 v[62:65], v[134:137], v[186:189], v[62:65]
	v_mfma_f32_16x16x32_bf16 v[58:61], v[154:157], v[186:189], v[58:61]
	v_mfma_f32_16x16x32_bf16 v[46:49], v[134:137], v[194:197], v[46:49]
	v_mfma_f32_16x16x32_bf16 v[42:45], v[154:157], v[194:197], v[42:45]
	v_mfma_f32_16x16x32_bf16 v[30:33], v[134:137], v[202:205], v[30:33]
	v_mfma_f32_16x16x32_bf16 v[26:29], v[154:157], v[202:205], v[26:29]
	v_mfma_f32_16x16x32_bf16 v[14:17], v[134:137], v[210:213], v[14:17]
	v_mfma_f32_16x16x32_bf16 v[10:13], v[154:157], v[210:213], v[10:13]
	v_mfma_f32_16x16x32_bf16 v[54:57], v[158:161], v[182:185], v[54:57]
	v_mfma_f32_16x16x32_bf16 v[50:53], v[174:177], v[182:185], v[50:53]
	v_mfma_f32_16x16x32_bf16 v[38:41], v[158:161], v[190:193], v[38:41]
	v_mfma_f32_16x16x32_bf16 v[34:37], v[174:177], v[190:193], v[34:37]
	v_mfma_f32_16x16x32_bf16 v[22:25], v[158:161], v[198:201], v[22:25]
	v_mfma_f32_16x16x32_bf16 v[18:21], v[174:177], v[198:201], v[18:21]
	v_mfma_f32_16x16x32_bf16 v[6:9], v[158:161], v[206:209], v[6:9]
	v_mfma_f32_16x16x32_bf16 v[2:5], v[174:177], v[206:209], v[2:5]
	v_mfma_f32_16x16x32_bf16 v[54:57], v[162:165], v[186:189], v[54:57]
	v_mfma_f32_16x16x32_bf16 v[50:53], v[178:181], v[186:189], v[50:53]
	v_mfma_f32_16x16x32_bf16 v[38:41], v[162:165], v[194:197], v[38:41]
	v_mfma_f32_16x16x32_bf16 v[34:37], v[178:181], v[194:197], v[34:37]
	v_mfma_f32_16x16x32_bf16 v[22:25], v[162:165], v[202:205], v[22:25]
	v_mfma_f32_16x16x32_bf16 v[18:21], v[178:181], v[202:205], v[18:21]
	v_mfma_f32_16x16x32_bf16 v[6:9], v[162:165], v[210:213], v[6:9]
	v_mfma_f32_16x16x32_bf16 v[2:5], v[178:181], v[210:213], v[2:5]
	s_barrier
	s_add_i32 s54, s54, 2
	s_add_u32 s0, s0, 0x100
	s_addc_u32 s1, s1, 0
	s_add_u32 s31, s31, 0x100
	s_addc_u32 s53, s53, 0
	s_cmp_gt_u32 s54, 29
	s_cbranch_scc0 .LBB0_1199
	s_and_b64 vcc, exec, s[16:17]
	s_cbranch_vccz .LBB0_1202
	s_barrier

.LBB0_1855:
	ds_read_b128 v[142:145], v148
	ds_read_b128 v[152:155], v148 offset:1024
	ds_read_b128 v[156:159], v148 offset:2048
	ds_read_b128 v[160:163], v148 offset:3072
	ds_read_b128 v[164:167], v149
	ds_read_b128 v[168:171], v149 offset:1024
	ds_read_b128 v[172:175], v149 offset:2048
	ds_read_b128 v[176:179], v149 offset:3072
	s_add_u32 s26, s24, 0x100
	s_addc_u32 s27, s25, 0
	s_cmp_eq_u32 s55, 60
	s_cselect_b32 s31, s19, s27
	s_cselect_b32 s30, s51, s26
	s_cselect_b32 s29, s17, s54
	s_cselect_b32 s28, s52, s53
	v_lshl_add_u64 v[212:213], s[24:25], 0, v[134:135]
	s_add_i32 m0, s5, 0xc000
	ds_read_b128 v[180:183], v150
	ds_read_b128 v[184:187], v150 offset:1024
	ds_read_b128 v[188:191], v150 offset:2048
	ds_read_b128 v[192:195], v150 offset:3072
	ds_read_b128 v[196:199], v150 offset:4096
	ds_read_b128 v[200:203], v150 offset:5120
	ds_read_b128 v[204:207], v150 offset:6144
	ds_read_b128 v[208:211], v150 offset:7168
	global_load_lds_dwordx4 v[212:213], off
	v_lshl_add_u64 v[212:213], s[24:25], 0, v[136:137]
	s_add_i32 m0, s5, 0xe000
	s_nop 0
	global_load_lds_dwordx4 v[212:213], off
	s_waitcnt vmcnt(8)
	s_waitcnt lgkmcnt(0)
	s_barrier
	s_waitcnt lgkmcnt(0)
	v_mfma_f32_16x16x32_bf16 v[126:129], v[142:145], v[180:183], v[126:129]
	v_mfma_f32_16x16x32_bf16 v[122:125], v[156:159], v[180:183], v[122:125]
	v_mfma_f32_16x16x32_bf16 v[110:113], v[142:145], v[188:191], v[110:113]
	v_mfma_f32_16x16x32_bf16 v[106:109], v[156:159], v[188:191], v[106:109]
	v_mfma_f32_16x16x32_bf16 v[94:97], v[142:145], v[196:199], v[94:97]
	v_mfma_f32_16x16x32_bf16 v[90:93], v[156:159], v[196:199], v[90:93]
	v_mfma_f32_16x16x32_bf16 v[78:81], v[142:145], v[204:207], v[78:81]
	v_mfma_f32_16x16x32_bf16 v[74:77], v[156:159], v[204:207], v[74:77]
	v_mfma_f32_16x16x32_bf16 v[126:129], v[152:155], v[184:187], v[126:129]
	v_mfma_f32_16x16x32_bf16 v[122:125], v[160:163], v[184:187], v[122:125]
	v_mfma_f32_16x16x32_bf16 v[110:113], v[152:155], v[192:195], v[110:113]
	v_mfma_f32_16x16x32_bf16 v[106:109], v[160:163], v[192:195], v[106:109]
	v_mfma_f32_16x16x32_bf16 v[94:97], v[152:155], v[200:203], v[94:97]
	v_mfma_f32_16x16x32_bf16 v[90:93], v[160:163], v[200:203], v[90:93]
	v_mfma_f32_16x16x32_bf16 v[78:81], v[152:155], v[208:211], v[78:81]
	v_mfma_f32_16x16x32_bf16 v[74:77], v[160:163], v[208:211], v[74:77]
	v_mfma_f32_16x16x32_bf16 v[118:121], v[164:167], v[180:183], v[118:121]
	v_mfma_f32_16x16x32_bf16 v[114:117], v[172:175], v[180:183], v[114:117]
	v_mfma_f32_16x16x32_bf16 v[102:105], v[164:167], v[188:191], v[102:105]
	v_mfma_f32_16x16x32_bf16 v[98:101], v[172:175], v[188:191], v[98:101]
	v_mfma_f32_16x16x32_bf16 v[86:89], v[164:167], v[196:199], v[86:89]
	v_mfma_f32_16x16x32_bf16 v[82:85], v[172:175], v[196:199], v[82:85]
	v_mfma_f32_16x16x32_bf16 v[70:73], v[164:167], v[204:207], v[70:73]
	v_mfma_f32_16x16x32_bf16 v[66:69], v[172:175], v[204:207], v[66:69]
	v_mfma_f32_16x16x32_bf16 v[118:121], v[168:171], v[184:187], v[118:121]
	v_mfma_f32_16x16x32_bf16 v[114:117], v[176:179], v[184:187], v[114:117]
	v_mfma_f32_16x16x32_bf16 v[102:105], v[168:171], v[192:195], v[102:105]
	v_mfma_f32_16x16x32_bf16 v[98:101], v[176:179], v[192:195], v[98:101]
	v_mfma_f32_16x16x32_bf16 v[86:89], v[168:171], v[200:203], v[86:89]
	v_mfma_f32_16x16x32_bf16 v[82:85], v[176:179], v[200:203], v[82:85]
	v_mfma_f32_16x16x32_bf16 v[70:73], v[168:171], v[208:211], v[70:73]
	v_mfma_f32_16x16x32_bf16 v[66:69], v[176:179], v[208:211], v[66:69]
	s_barrier
	s_add_i32 s24, s48, s37
	v_lshl_add_u64 v[212:213], s[28:29], 0, v[130:131]
	s_mov_b32 m0, s24
	ds_read_b128 v[180:183], v150 offset:16384
	ds_read_b128 v[184:187], v150 offset:17408
	ds_read_b128 v[188:191], v150 offset:18432
	ds_read_b128 v[192:195], v150 offset:19456
	ds_read_b128 v[196:199], v150 offset:20480
	ds_read_b128 v[200:203], v150 offset:21504
	ds_read_b128 v[204:207], v150 offset:22528
	ds_read_b128 v[208:211], v150 offset:23552
	global_load_lds_dwordx4 v[212:213], off
	s_add_i32 m0, s24, 0x2000
	s_add_u32 s24, s28, 0x100000
	v_lshl_add_u64 v[214:215], s[28:29], 0, v[132:133]
	s_addc_u32 s25, s29, 0
	s_add_i32 s56, s49, s37
	global_load_lds_dwordx4 v[214:215], off
	v_lshl_add_u64 v[216:217], s[24:25], 0, v[130:131]
	s_mov_b32 m0, s56
	v_lshl_add_u64 v[218:219], s[30:31], 0, v[132:133]
	global_load_lds_dwordx4 v[216:217], off
	v_lshl_add_u64 v[216:217], s[24:25], 0, v[132:133]
	s_add_i32 m0, s56, 0x2000
	s_nop 0
	global_load_lds_dwordx4 v[216:217], off
	v_lshl_add_u64 v[216:217], s[30:31], 0, v[130:131]
	s_mov_b32 m0, s5
	s_nop 0
	global_load_lds_dwordx4 v[216:217], off
	s_mov_b32 m0, s38
	s_nop 0
	global_load_lds_dwordx4 v[218:219], off
	s_waitcnt vmcnt(8)
	s_waitcnt lgkmcnt(0)
	s_barrier
	s_waitcnt lgkmcnt(0)
	v_mfma_f32_16x16x32_bf16 v[62:65], v[142:145], v[180:183], v[62:65]
	v_mfma_f32_16x16x32_bf16 v[58:61], v[156:159], v[180:183], v[58:61]
	v_mfma_f32_16x16x32_bf16 v[46:49], v[142:145], v[188:191], v[46:49]
	v_mfma_f32_16x16x32_bf16 v[42:45], v[156:159], v[188:191], v[42:45]
	v_mfma_f32_16x16x32_bf16 v[30:33], v[142:145], v[196:199], v[30:33]
	v_mfma_f32_16x16x32_bf16 v[26:29], v[156:159], v[196:199], v[26:29]
	v_mfma_f32_16x16x32_bf16 v[14:17], v[142:145], v[204:207], v[14:17]
	v_mfma_f32_16x16x32_bf16 v[10:13], v[156:159], v[204:207], v[10:13]
	v_mfma_f32_16x16x32_bf16 v[62:65], v[152:155], v[184:187], v[62:65]
	v_mfma_f32_16x16x32_bf16 v[58:61], v[160:163], v[184:187], v[58:61]
	v_mfma_f32_16x16x32_bf16 v[46:49], v[152:155], v[192:195], v[46:49]
	v_mfma_f32_16x16x32_bf16 v[42:45], v[160:163], v[192:195], v[42:45]
	v_mfma_f32_16x16x32_bf16 v[30:33], v[152:155], v[200:203], v[30:33]
	v_mfma_f32_16x16x32_bf16 v[26:29], v[160:163], v[200:203], v[26:29]
	v_mfma_f32_16x16x32_bf16 v[14:17], v[152:155], v[208:211], v[14:17]
	v_mfma_f32_16x16x32_bf16 v[10:13], v[160:163], v[208:211], v[10:13]
	v_mfma_f32_16x16x32_bf16 v[54:57], v[164:167], v[180:183], v[54:57]
	v_mfma_f32_16x16x32_bf16 v[50:53], v[172:175], v[180:183], v[50:53]
	v_mfma_f32_16x16x32_bf16 v[38:41], v[164:167], v[188:191], v[38:41]
	v_mfma_f32_16x16x32_bf16 v[34:37], v[172:175], v[188:191], v[34:37]
	v_mfma_f32_16x16x32_bf16 v[22:25], v[164:167], v[196:199], v[22:25]
	v_mfma_f32_16x16x32_bf16 v[18:21], v[172:175], v[196:199], v[18:21]
	v_mfma_f32_16x16x32_bf16 v[6:9], v[164:167], v[204:207], v[6:9]
	v_mfma_f32_16x16x32_bf16 v[2:5], v[172:175], v[204:207], v[2:5]
	v_mfma_f32_16x16x32_bf16 v[54:57], v[168:171], v[184:187], v[54:57]
	v_mfma_f32_16x16x32_bf16 v[50:53], v[176:179], v[184:187], v[50:53]
	v_mfma_f32_16x16x32_bf16 v[38:41], v[168:171], v[192:195], v[38:41]
	v_mfma_f32_16x16x32_bf16 v[34:37], v[176:179], v[192:195], v[34:37]
	v_mfma_f32_16x16x32_bf16 v[22:25], v[168:171], v[200:203], v[22:25]
	v_mfma_f32_16x16x32_bf16 v[18:21], v[176:179], v[200:203], v[18:21]
	v_mfma_f32_16x16x32_bf16 v[6:9], v[168:171], v[208:211], v[6:9]
	v_mfma_f32_16x16x32_bf16 v[2:5], v[176:179], v[208:211], v[2:5]
	s_barrier
	s_add_i32 s56, 0, 0x18000
	s_add_i32 s57, 0, 0x1c000
	v_add_u32_e32 v160, s56, v147
	v_add_u32_e32 v176, s57, v147
	ds_read_b128 v[142:145], v160
	ds_read_b128 v[152:155], v160 offset:1024
	ds_read_b128 v[156:159], v160 offset:2048
	ds_read_b128 v[160:163], v160 offset:3072
	ds_read_b128 v[164:167], v176
	ds_read_b128 v[168:171], v176 offset:1024
	ds_read_b128 v[172:175], v176 offset:2048
	ds_read_b128 v[176:179], v176 offset:3072
	s_add_u32 s24, s30, 0x100000
	s_addc_u32 s25, s31, 0
	s_mov_b32 m0, s39
	v_lshl_add_u64 v[220:221], s[24:25], 0, v[130:131]
	ds_read_b128 v[180:183], v150 offset:32768
	ds_read_b128 v[184:187], v150 offset:33792
	ds_read_b128 v[188:191], v150 offset:34816
	ds_read_b128 v[192:195], v150 offset:35840
	ds_read_b128 v[196:199], v150 offset:36864
	ds_read_b128 v[200:203], v150 offset:37888
	ds_read_b128 v[204:207], v150 offset:38912
	ds_read_b128 v[208:211], v150 offset:39936
	global_load_lds_dwordx4 v[220:221], off
	v_lshl_add_u64 v[220:221], s[24:25], 0, v[132:133]
	s_mov_b32 m0, s40
	s_nop 0
	global_load_lds_dwordx4 v[220:221], off
	s_waitcnt vmcnt(8)
	s_waitcnt lgkmcnt(0)
	s_barrier
	s_waitcnt lgkmcnt(0)
	v_mfma_f32_16x16x32_bf16 v[126:129], v[142:145], v[180:183], v[126:129]
	v_mfma_f32_16x16x32_bf16 v[122:125], v[156:159], v[180:183], v[122:125]
	v_mfma_f32_16x16x32_bf16 v[110:113], v[142:145], v[188:191], v[110:113]
	v_mfma_f32_16x16x32_bf16 v[106:109], v[156:159], v[188:191], v[106:109]
	v_mfma_f32_16x16x32_bf16 v[94:97], v[142:145], v[196:199], v[94:97]
	v_mfma_f32_16x16x32_bf16 v[90:93], v[156:159], v[196:199], v[90:93]
	v_mfma_f32_16x16x32_bf16 v[78:81], v[142:145], v[204:207], v[78:81]
	v_mfma_f32_16x16x32_bf16 v[74:77], v[156:159], v[204:207], v[74:77]
	v_mfma_f32_16x16x32_bf16 v[126:129], v[152:155], v[184:187], v[126:129]
	v_mfma_f32_16x16x32_bf16 v[122:125], v[160:163], v[184:187], v[122:125]
	v_mfma_f32_16x16x32_bf16 v[110:113], v[152:155], v[192:195], v[110:113]
	v_mfma_f32_16x16x32_bf16 v[106:109], v[160:163], v[192:195], v[106:109]
	v_mfma_f32_16x16x32_bf16 v[94:97], v[152:155], v[200:203], v[94:97]
	v_mfma_f32_16x16x32_bf16 v[90:93], v[160:163], v[200:203], v[90:93]
	v_mfma_f32_16x16x32_bf16 v[78:81], v[152:155], v[208:211], v[78:81]
	v_mfma_f32_16x16x32_bf16 v[74:77], v[160:163], v[208:211], v[74:77]
	v_mfma_f32_16x16x32_bf16 v[118:121], v[164:167], v[180:183], v[118:121]
	v_mfma_f32_16x16x32_bf16 v[114:117], v[172:175], v[180:183], v[114:117]
	v_mfma_f32_16x16x32_bf16 v[102:105], v[164:167], v[188:191], v[102:105]
	v_mfma_f32_16x16x32_bf16 v[98:101], v[172:175], v[188:191], v[98:101]
	v_mfma_f32_16x16x32_bf16 v[86:89], v[164:167], v[196:199], v[86:89]
	v_mfma_f32_16x16x32_bf16 v[82:85], v[172:175], v[196:199], v[82:85]
	v_mfma_f32_16x16x32_bf16 v[70:73], v[164:167], v[204:207], v[70:73]
	v_mfma_f32_16x16x32_bf16 v[66:69], v[172:175], v[204:207], v[66:69]
	v_mfma_f32_16x16x32_bf16 v[118:121], v[168:171], v[184:187], v[118:121]
	v_mfma_f32_16x16x32_bf16 v[114:117], v[176:179], v[184:187], v[114:117]
	v_mfma_f32_16x16x32_bf16 v[102:105], v[168:171], v[192:195], v[102:105]
	v_mfma_f32_16x16x32_bf16 v[98:101], v[176:179], v[192:195], v[98:101]
	v_mfma_f32_16x16x32_bf16 v[86:89], v[168:171], v[200:203], v[86:89]
	v_mfma_f32_16x16x32_bf16 v[82:85], v[176:179], v[200:203], v[82:85]
	v_mfma_f32_16x16x32_bf16 v[70:73], v[168:171], v[208:211], v[70:73]
	v_mfma_f32_16x16x32_bf16 v[66:69], v[176:179], v[208:211], v[66:69]
	s_barrier
	s_add_i32 s24, s56, s37
	v_lshl_add_u64 v[212:213], v[212:213], 0, s[12:13]
	s_mov_b32 m0, s24
	ds_read_b128 v[180:183], v150 offset:49152
	ds_read_b128 v[184:187], v150 offset:50176
	ds_read_b128 v[188:191], v150 offset:51200
	ds_read_b128 v[192:195], v150 offset:52224
	ds_read_b128 v[196:199], v150 offset:53248
	ds_read_b128 v[200:203], v150 offset:54272
	ds_read_b128 v[204:207], v150 offset:55296
	ds_read_b128 v[208:211], v150 offset:56320
	global_load_lds_dwordx4 v[212:213], off
	s_add_i32 m0, s24, 0x2000
	s_add_u32 s24, s28, 0x100080
	v_lshl_add_u64 v[212:213], v[214:215], 0, s[12:13]
	s_addc_u32 s25, s29, 0
	s_add_i32 s28, s57, s37
	global_load_lds_dwordx4 v[212:213], off
	v_lshl_add_u64 v[212:213], s[24:25], 0, v[130:131]
	s_mov_b32 m0, s28
	s_nop 0
	global_load_lds_dwordx4 v[212:213], off
	v_lshl_add_u64 v[212:213], s[24:25], 0, v[132:133]
	s_add_i32 m0, s28, 0x2000
	s_nop 0
	global_load_lds_dwordx4 v[212:213], off
	v_lshl_add_u64 v[212:213], v[216:217], 0, s[12:13]
	s_mov_b32 m0, s44
	s_nop 0
	global_load_lds_dwordx4 v[212:213], off
	v_lshl_add_u64 v[212:213], v[218:219], 0, s[12:13]
	s_mov_b32 m0, s45
	s_nop 0
	global_load_lds_dwordx4 v[212:213], off
	s_waitcnt vmcnt(8)
	s_waitcnt lgkmcnt(0)
	s_barrier
	s_waitcnt lgkmcnt(0)
	v_mfma_f32_16x16x32_bf16 v[62:65], v[142:145], v[180:183], v[62:65]
	v_mfma_f32_16x16x32_bf16 v[58:61], v[156:159], v[180:183], v[58:61]
	v_mfma_f32_16x16x32_bf16 v[46:49], v[142:145], v[188:191], v[46:49]
	v_mfma_f32_16x16x32_bf16 v[42:45], v[156:159], v[188:191], v[42:45]
	v_mfma_f32_16x16x32_bf16 v[30:33], v[142:145], v[196:199], v[30:33]
	v_mfma_f32_16x16x32_bf16 v[26:29], v[156:159], v[196:199], v[26:29]
	v_mfma_f32_16x16x32_bf16 v[14:17], v[142:145], v[204:207], v[14:17]
	v_mfma_f32_16x16x32_bf16 v[10:13], v[156:159], v[204:207], v[10:13]
	v_mfma_f32_16x16x32_bf16 v[62:65], v[152:155], v[184:187], v[62:65]
	v_mfma_f32_16x16x32_bf16 v[58:61], v[160:163], v[184:187], v[58:61]
	v_mfma_f32_16x16x32_bf16 v[46:49], v[152:155], v[192:195], v[46:49]
	v_mfma_f32_16x16x32_bf16 v[42:45], v[160:163], v[192:195], v[42:45]
	v_mfma_f32_16x16x32_bf16 v[30:33], v[152:155], v[200:203], v[30:33]
	v_mfma_f32_16x16x32_bf16 v[26:29], v[160:163], v[200:203], v[26:29]
	v_mfma_f32_16x16x32_bf16 v[14:17], v[152:155], v[208:211], v[14:17]
	v_mfma_f32_16x16x32_bf16 v[10:13], v[160:163], v[208:211], v[10:13]
	v_mfma_f32_16x16x32_bf16 v[54:57], v[164:167], v[180:183], v[54:57]
	v_mfma_f32_16x16x32_bf16 v[50:53], v[172:175], v[180:183], v[50:53]
	v_mfma_f32_16x16x32_bf16 v[38:41], v[164:167], v[188:191], v[38:41]
	v_mfma_f32_16x16x32_bf16 v[34:37], v[172:175], v[188:191], v[34:37]
	v_mfma_f32_16x16x32_bf16 v[22:25], v[164:167], v[196:199], v[22:25]
	v_mfma_f32_16x16x32_bf16 v[18:21], v[172:175], v[196:199], v[18:21]
	v_mfma_f32_16x16x32_bf16 v[6:9], v[164:167], v[204:207], v[6:9]
	v_mfma_f32_16x16x32_bf16 v[2:5], v[172:175], v[204:207], v[2:5]
	v_mfma_f32_16x16x32_bf16 v[54:57], v[168:171], v[184:187], v[54:57]
	v_mfma_f32_16x16x32_bf16 v[50:53], v[176:179], v[184:187], v[50:53]
	v_mfma_f32_16x16x32_bf16 v[38:41], v[168:171], v[192:195], v[38:41]
	v_mfma_f32_16x16x32_bf16 v[34:37], v[176:179], v[192:195], v[34:37]
	v_mfma_f32_16x16x32_bf16 v[22:25], v[168:171], v[200:203], v[22:25]
	v_mfma_f32_16x16x32_bf16 v[18:21], v[176:179], v[200:203], v[18:21]
	v_mfma_f32_16x16x32_bf16 v[6:9], v[168:171], v[208:211], v[6:9]
	v_mfma_f32_16x16x32_bf16 v[2:5], v[176:179], v[208:211], v[2:5]
	s_barrier
	s_add_i32 s55, s55, 2
	s_add_u32 s53, s53, 0x100
	s_addc_u32 s54, s54, 0
	s_cmp_gt_u32 s55, 61
	s_mov_b64 s[24:25], s[26:27]
	s_cbranch_scc0 .LBB0_1855
	s_and_b64 vcc, exec, s[14:15]
	s_cbranch_vccz .LBB0_1858
	s_barrier

.LBB0_1942:
	s_waitcnt lgkmcnt(0)
	s_add_u32 s26, s8, 0xfff80080
	s_addc_u32 s27, s9, -1
	s_cmp_eq_u32 s53, 28
	s_cselect_b32 s29, s7, s27
	s_cselect_b32 s28, s21, s26
	s_cselect_b32 s27, s19, s52
	s_cselect_b32 s26, s50, s51
	v_lshl_add_u64 v[216:217], s[8:9], 0, v[190:191]
	s_add_i32 m0, s35, 0xc000
	s_nop 0
	global_load_lds_dwordx4 v[216:217], off
	v_lshl_add_u64 v[216:217], s[8:9], 0, v[192:193]
	s_add_i32 m0, s35, 0xe000
	s_nop 0
	global_load_lds_dwordx4 v[216:217], off
	ds_read_b128 v[130:133], v200
	ds_read_b128 v[134:137], v200 offset:1024
	ds_read_b128 v[138:141], v200 offset:2048
	ds_read_b128 v[142:145], v200 offset:3072
	ds_read_b128 v[146:149], v201
	ds_read_b128 v[150:153], v201 offset:1024
	ds_read_b128 v[154:157], v201 offset:2048
	ds_read_b128 v[158:161], v201 offset:3072
	ds_read_b128 v[162:165], v202
	ds_read_b128 v[166:169], v202 offset:1024
	ds_read_b128 v[170:173], v202 offset:2048
	ds_read_b128 v[174:177], v202 offset:3072
	ds_read_b128 v[178:181], v202 offset:4096
	ds_read_b128 v[204:207], v202 offset:5120
	ds_read_b128 v[208:211], v202 offset:6144
	ds_read_b128 v[212:215], v202 offset:7168
	s_waitcnt vmcnt(8)
	s_waitcnt lgkmcnt(0)
	s_barrier
	s_waitcnt lgkmcnt(0)
	v_mfma_f32_16x16x32_bf16 v[126:129], v[130:133], v[162:165], v[126:129]
	v_mfma_f32_16x16x32_bf16 v[122:125], v[138:141], v[162:165], v[122:125]
	v_mfma_f32_16x16x32_bf16 v[118:121], v[130:133], v[170:173], v[118:121]
	v_mfma_f32_16x16x32_bf16 v[110:113], v[138:141], v[170:173], v[110:113]
	v_mfma_f32_16x16x32_bf16 v[102:105], v[130:133], v[178:181], v[102:105]
	v_mfma_f32_16x16x32_bf16 v[94:97], v[138:141], v[178:181], v[94:97]
	v_mfma_f32_16x16x32_bf16 v[86:89], v[130:133], v[208:211], v[86:89]
	v_mfma_f32_16x16x32_bf16 v[78:81], v[138:141], v[208:211], v[78:81]
	v_mfma_f32_16x16x32_bf16 v[126:129], v[134:137], v[166:169], v[126:129]
	v_mfma_f32_16x16x32_bf16 v[122:125], v[142:145], v[166:169], v[122:125]
	v_mfma_f32_16x16x32_bf16 v[118:121], v[134:137], v[174:177], v[118:121]
	v_mfma_f32_16x16x32_bf16 v[110:113], v[142:145], v[174:177], v[110:113]
	v_mfma_f32_16x16x32_bf16 v[102:105], v[134:137], v[204:207], v[102:105]
	v_mfma_f32_16x16x32_bf16 v[94:97], v[142:145], v[204:207], v[94:97]
	v_mfma_f32_16x16x32_bf16 v[86:89], v[134:137], v[212:215], v[86:89]
	v_mfma_f32_16x16x32_bf16 v[78:81], v[142:145], v[212:215], v[78:81]
	v_mfma_f32_16x16x32_bf16 v[114:117], v[146:149], v[162:165], v[114:117]
	v_mfma_f32_16x16x32_bf16 v[106:109], v[154:157], v[162:165], v[106:109]
	v_mfma_f32_16x16x32_bf16 v[98:101], v[146:149], v[170:173], v[98:101]
	v_mfma_f32_16x16x32_bf16 v[90:93], v[154:157], v[170:173], v[90:93]
	v_mfma_f32_16x16x32_bf16 v[82:85], v[146:149], v[178:181], v[82:85]
	v_mfma_f32_16x16x32_bf16 v[74:77], v[154:157], v[178:181], v[74:77]
	v_mfma_f32_16x16x32_bf16 v[70:73], v[146:149], v[208:211], v[70:73]
	v_mfma_f32_16x16x32_bf16 v[66:69], v[154:157], v[208:211], v[66:69]
	v_mfma_f32_16x16x32_bf16 v[114:117], v[150:153], v[166:169], v[114:117]
	v_mfma_f32_16x16x32_bf16 v[106:109], v[158:161], v[166:169], v[106:109]
	v_mfma_f32_16x16x32_bf16 v[98:101], v[150:153], v[174:177], v[98:101]
	v_mfma_f32_16x16x32_bf16 v[90:93], v[158:161], v[174:177], v[90:93]
	v_mfma_f32_16x16x32_bf16 v[82:85], v[150:153], v[204:207], v[82:85]
	v_mfma_f32_16x16x32_bf16 v[74:77], v[158:161], v[204:207], v[74:77]
	v_mfma_f32_16x16x32_bf16 v[70:73], v[150:153], v[212:215], v[70:73]
	v_mfma_f32_16x16x32_bf16 v[66:69], v[158:161], v[212:215], v[66:69]
	s_barrier
	s_add_i32 s54, s45, s31
	v_lshl_add_u64 v[216:217], s[26:27], 0, v[186:187]
	s_mov_b32 m0, s54
	s_nop 0
	global_load_lds_dwordx4 v[216:217], off
	s_add_i32 m0, s54, 0x2000
	s_add_u32 s54, s26, 0x80000
	v_lshl_add_u64 v[218:219], s[26:27], 0, v[182:183]
	s_addc_u32 s55, s27, 0
	s_add_i32 s56, s46, s31
	global_load_lds_dwordx4 v[218:219], off
	v_lshl_add_u64 v[220:221], s[54:55], 0, v[186:187]
	s_mov_b32 m0, s56
	v_lshl_add_u64 v[222:223], s[28:29], 0, v[184:185]
	global_load_lds_dwordx4 v[220:221], off
	v_lshl_add_u64 v[220:221], s[54:55], 0, v[182:183]
	s_add_i32 m0, s56, 0x2000
	s_nop 0
	global_load_lds_dwordx4 v[220:221], off
	v_lshl_add_u64 v[220:221], s[28:29], 0, v[188:189]
	s_mov_b32 m0, s35
	s_nop 0
	global_load_lds_dwordx4 v[220:221], off
	s_mov_b32 m0, s36
	s_nop 0
	global_load_lds_dwordx4 v[222:223], off
	ds_read_b128 v[162:165], v202 offset:16384
	ds_read_b128 v[166:169], v202 offset:17408
	ds_read_b128 v[170:173], v202 offset:18432
	ds_read_b128 v[174:177], v202 offset:19456
	ds_read_b128 v[178:181], v202 offset:20480
	ds_read_b128 v[204:207], v202 offset:21504
	ds_read_b128 v[208:211], v202 offset:22528
	ds_read_b128 v[212:215], v202 offset:23552
	s_waitcnt vmcnt(8)
	s_waitcnt lgkmcnt(0)
	s_barrier
	s_waitcnt lgkmcnt(0)
	v_mfma_f32_16x16x32_bf16 v[62:65], v[130:133], v[162:165], v[62:65]
	v_mfma_f32_16x16x32_bf16 v[58:61], v[138:141], v[162:165], v[58:61]
	v_mfma_f32_16x16x32_bf16 v[54:57], v[130:133], v[170:173], v[54:57]
	v_mfma_f32_16x16x32_bf16 v[46:49], v[138:141], v[170:173], v[46:49]
	v_mfma_f32_16x16x32_bf16 v[38:41], v[130:133], v[178:181], v[38:41]
	v_mfma_f32_16x16x32_bf16 v[30:33], v[138:141], v[178:181], v[30:33]
	v_mfma_f32_16x16x32_bf16 v[22:25], v[130:133], v[208:211], v[22:25]
	v_mfma_f32_16x16x32_bf16 v[14:17], v[138:141], v[208:211], v[14:17]
	v_mfma_f32_16x16x32_bf16 v[62:65], v[134:137], v[166:169], v[62:65]
	v_mfma_f32_16x16x32_bf16 v[58:61], v[142:145], v[166:169], v[58:61]
	v_mfma_f32_16x16x32_bf16 v[54:57], v[134:137], v[174:177], v[54:57]
	v_mfma_f32_16x16x32_bf16 v[46:49], v[142:145], v[174:177], v[46:49]
	v_mfma_f32_16x16x32_bf16 v[38:41], v[134:137], v[204:207], v[38:41]
	v_mfma_f32_16x16x32_bf16 v[30:33], v[142:145], v[204:207], v[30:33]
	v_mfma_f32_16x16x32_bf16 v[22:25], v[134:137], v[212:215], v[22:25]
	v_mfma_f32_16x16x32_bf16 v[14:17], v[142:145], v[212:215], v[14:17]
	v_mfma_f32_16x16x32_bf16 v[50:53], v[146:149], v[162:165], v[50:53]
	v_mfma_f32_16x16x32_bf16 v[42:45], v[154:157], v[162:165], v[42:45]
	v_mfma_f32_16x16x32_bf16 v[34:37], v[146:149], v[170:173], v[34:37]
	v_mfma_f32_16x16x32_bf16 v[26:29], v[154:157], v[170:173], v[26:29]
	v_mfma_f32_16x16x32_bf16 v[18:21], v[146:149], v[178:181], v[18:21]
	v_mfma_f32_16x16x32_bf16 v[10:13], v[154:157], v[178:181], v[10:13]
	v_mfma_f32_16x16x32_bf16 v[6:9], v[146:149], v[208:211], v[6:9]
	v_mfma_f32_16x16x32_bf16 v[2:5], v[154:157], v[208:211], v[2:5]
	v_mfma_f32_16x16x32_bf16 v[50:53], v[150:153], v[166:169], v[50:53]
	v_mfma_f32_16x16x32_bf16 v[42:45], v[158:161], v[166:169], v[42:45]
	v_mfma_f32_16x16x32_bf16 v[34:37], v[150:153], v[174:177], v[34:37]
	v_mfma_f32_16x16x32_bf16 v[26:29], v[158:161], v[174:177], v[26:29]
	v_mfma_f32_16x16x32_bf16 v[18:21], v[150:153], v[204:207], v[18:21]
	v_mfma_f32_16x16x32_bf16 v[10:13], v[158:161], v[204:207], v[10:13]
	v_mfma_f32_16x16x32_bf16 v[6:9], v[150:153], v[212:215], v[6:9]
	v_mfma_f32_16x16x32_bf16 v[2:5], v[158:161], v[212:215], v[2:5]
	s_barrier
	s_add_i32 s54, 0, 0x18000
	s_add_i32 s55, 0, 0x1c000
	v_add_u32_e32 v142, s54, v199
	v_add_u32_e32 v158, s55, v199
	s_add_u32 s28, s28, 0x80000
	s_addc_u32 s29, s29, 0
	s_mov_b32 m0, s37
	v_lshl_add_u64 v[224:225], s[28:29], 0, v[188:189]
	global_load_lds_dwordx4 v[224:225], off
	v_lshl_add_u64 v[224:225], s[28:29], 0, v[184:185]
	s_mov_b32 m0, s38
	s_nop 0
	global_load_lds_dwordx4 v[224:225], off
	ds_read_b128 v[130:133], v142
	ds_read_b128 v[134:137], v142 offset:1024
	ds_read_b128 v[138:141], v142 offset:2048
	ds_read_b128 v[142:145], v142 offset:3072
	ds_read_b128 v[146:149], v158
	ds_read_b128 v[150:153], v158 offset:1024
	ds_read_b128 v[154:157], v158 offset:2048
	ds_read_b128 v[158:161], v158 offset:3072
	ds_read_b128 v[162:165], v202 offset:32768
	ds_read_b128 v[166:169], v202 offset:33792
	ds_read_b128 v[170:173], v202 offset:34816
	ds_read_b128 v[174:177], v202 offset:35840
	ds_read_b128 v[178:181], v202 offset:36864
	ds_read_b128 v[204:207], v202 offset:37888
	ds_read_b128 v[208:211], v202 offset:38912
	ds_read_b128 v[212:215], v202 offset:39936
	s_waitcnt vmcnt(8)
	s_waitcnt lgkmcnt(0)
	s_barrier
	s_waitcnt lgkmcnt(0)
	v_mfma_f32_16x16x32_bf16 v[126:129], v[130:133], v[162:165], v[126:129]
	v_mfma_f32_16x16x32_bf16 v[122:125], v[138:141], v[162:165], v[122:125]
	v_mfma_f32_16x16x32_bf16 v[118:121], v[130:133], v[170:173], v[118:121]
	v_mfma_f32_16x16x32_bf16 v[110:113], v[138:141], v[170:173], v[110:113]
	v_mfma_f32_16x16x32_bf16 v[102:105], v[130:133], v[178:181], v[102:105]
	v_mfma_f32_16x16x32_bf16 v[94:97], v[138:141], v[178:181], v[94:97]
	v_mfma_f32_16x16x32_bf16 v[86:89], v[130:133], v[208:211], v[86:89]
	v_mfma_f32_16x16x32_bf16 v[78:81], v[138:141], v[208:211], v[78:81]
	v_mfma_f32_16x16x32_bf16 v[126:129], v[134:137], v[166:169], v[126:129]
	v_mfma_f32_16x16x32_bf16 v[122:125], v[142:145], v[166:169], v[122:125]
	v_mfma_f32_16x16x32_bf16 v[118:121], v[134:137], v[174:177], v[118:121]
	v_mfma_f32_16x16x32_bf16 v[110:113], v[142:145], v[174:177], v[110:113]
	v_mfma_f32_16x16x32_bf16 v[102:105], v[134:137], v[204:207], v[102:105]
	v_mfma_f32_16x16x32_bf16 v[94:97], v[142:145], v[204:207], v[94:97]
	v_mfma_f32_16x16x32_bf16 v[86:89], v[134:137], v[212:215], v[86:89]
	v_mfma_f32_16x16x32_bf16 v[78:81], v[142:145], v[212:215], v[78:81]
	v_mfma_f32_16x16x32_bf16 v[114:117], v[146:149], v[162:165], v[114:117]
	v_mfma_f32_16x16x32_bf16 v[106:109], v[154:157], v[162:165], v[106:109]
	v_mfma_f32_16x16x32_bf16 v[98:101], v[146:149], v[170:173], v[98:101]
	v_mfma_f32_16x16x32_bf16 v[90:93], v[154:157], v[170:173], v[90:93]
	v_mfma_f32_16x16x32_bf16 v[82:85], v[146:149], v[178:181], v[82:85]
	v_mfma_f32_16x16x32_bf16 v[74:77], v[154:157], v[178:181], v[74:77]
	v_mfma_f32_16x16x32_bf16 v[70:73], v[146:149], v[208:211], v[70:73]
	v_mfma_f32_16x16x32_bf16 v[66:69], v[154:157], v[208:211], v[66:69]
	v_mfma_f32_16x16x32_bf16 v[114:117], v[150:153], v[166:169], v[114:117]
	v_mfma_f32_16x16x32_bf16 v[106:109], v[158:161], v[166:169], v[106:109]
	v_mfma_f32_16x16x32_bf16 v[98:101], v[150:153], v[174:177], v[98:101]
	v_mfma_f32_16x16x32_bf16 v[90:93], v[158:161], v[174:177], v[90:93]
	v_mfma_f32_16x16x32_bf16 v[82:85], v[150:153], v[204:207], v[82:85]
	v_mfma_f32_16x16x32_bf16 v[74:77], v[158:161], v[204:207], v[74:77]
	v_mfma_f32_16x16x32_bf16 v[70:73], v[150:153], v[212:215], v[70:73]
	v_mfma_f32_16x16x32_bf16 v[66:69], v[158:161], v[212:215], v[66:69]
	s_barrier
	s_add_i32 s28, s54, s31
	v_lshl_add_u64 v[216:217], v[216:217], 0, s[12:13]
	s_mov_b32 m0, s28
	s_nop 0
	global_load_lds_dwordx4 v[216:217], off
	s_add_i32 m0, s28, 0x2000
	s_add_u32 s26, s26, 0x80080
	v_lshl_add_u64 v[216:217], v[218:219], 0, s[12:13]
	s_addc_u32 s27, s27, 0
	s_add_i32 s28, s55, s31
	global_load_lds_dwordx4 v[216:217], off
	v_lshl_add_u64 v[216:217], s[26:27], 0, v[186:187]
	s_mov_b32 m0, s28
	s_nop 0
	global_load_lds_dwordx4 v[216:217], off
	v_lshl_add_u64 v[216:217], s[26:27], 0, v[182:183]
	s_add_i32 m0, s28, 0x2000
	s_nop 0
	global_load_lds_dwordx4 v[216:217], off
	v_lshl_add_u64 v[216:217], v[220:221], 0, s[12:13]
	s_mov_b32 m0, s42
	s_nop 0
	global_load_lds_dwordx4 v[216:217], off
	v_lshl_add_u64 v[216:217], v[222:223], 0, s[12:13]
	s_mov_b32 m0, s43
	s_nop 0
	global_load_lds_dwordx4 v[216:217], off
	ds_read_b128 v[162:165], v202 offset:49152
	ds_read_b128 v[166:169], v202 offset:50176
	ds_read_b128 v[170:173], v202 offset:51200
	ds_read_b128 v[174:177], v202 offset:52224
	ds_read_b128 v[178:181], v202 offset:53248
	ds_read_b128 v[204:207], v202 offset:54272
	ds_read_b128 v[208:211], v202 offset:55296
	ds_read_b128 v[212:215], v202 offset:56320
	s_waitcnt vmcnt(8)
	s_waitcnt lgkmcnt(0)
	s_barrier
	s_waitcnt lgkmcnt(0)
	v_mfma_f32_16x16x32_bf16 v[62:65], v[130:133], v[162:165], v[62:65]
	v_mfma_f32_16x16x32_bf16 v[58:61], v[138:141], v[162:165], v[58:61]
	v_mfma_f32_16x16x32_bf16 v[54:57], v[130:133], v[170:173], v[54:57]
	v_mfma_f32_16x16x32_bf16 v[46:49], v[138:141], v[170:173], v[46:49]
	v_mfma_f32_16x16x32_bf16 v[38:41], v[130:133], v[178:181], v[38:41]
	v_mfma_f32_16x16x32_bf16 v[30:33], v[138:141], v[178:181], v[30:33]
	v_mfma_f32_16x16x32_bf16 v[22:25], v[130:133], v[208:211], v[22:25]
	v_mfma_f32_16x16x32_bf16 v[14:17], v[138:141], v[208:211], v[14:17]
	v_mfma_f32_16x16x32_bf16 v[62:65], v[134:137], v[166:169], v[62:65]
	v_mfma_f32_16x16x32_bf16 v[58:61], v[142:145], v[166:169], v[58:61]
	v_mfma_f32_16x16x32_bf16 v[54:57], v[134:137], v[174:177], v[54:57]
	v_mfma_f32_16x16x32_bf16 v[46:49], v[142:145], v[174:177], v[46:49]
	v_mfma_f32_16x16x32_bf16 v[38:41], v[134:137], v[204:207], v[38:41]
	v_mfma_f32_16x16x32_bf16 v[30:33], v[142:145], v[204:207], v[30:33]
	v_mfma_f32_16x16x32_bf16 v[22:25], v[134:137], v[212:215], v[22:25]
	v_mfma_f32_16x16x32_bf16 v[14:17], v[142:145], v[212:215], v[14:17]
	v_mfma_f32_16x16x32_bf16 v[50:53], v[146:149], v[162:165], v[50:53]
	v_mfma_f32_16x16x32_bf16 v[42:45], v[154:157], v[162:165], v[42:45]
	v_mfma_f32_16x16x32_bf16 v[34:37], v[146:149], v[170:173], v[34:37]
	v_mfma_f32_16x16x32_bf16 v[26:29], v[154:157], v[170:173], v[26:29]
	v_mfma_f32_16x16x32_bf16 v[18:21], v[146:149], v[178:181], v[18:21]
	v_mfma_f32_16x16x32_bf16 v[10:13], v[154:157], v[178:181], v[10:13]
	v_mfma_f32_16x16x32_bf16 v[6:9], v[146:149], v[208:211], v[6:9]
	v_mfma_f32_16x16x32_bf16 v[2:5], v[154:157], v[208:211], v[2:5]
	v_mfma_f32_16x16x32_bf16 v[50:53], v[150:153], v[166:169], v[50:53]
	v_mfma_f32_16x16x32_bf16 v[42:45], v[158:161], v[166:169], v[42:45]
	v_mfma_f32_16x16x32_bf16 v[34:37], v[150:153], v[174:177], v[34:37]
	v_mfma_f32_16x16x32_bf16 v[26:29], v[158:161], v[174:177], v[26:29]
	v_mfma_f32_16x16x32_bf16 v[18:21], v[150:153], v[204:207], v[18:21]
	v_mfma_f32_16x16x32_bf16 v[10:13], v[158:161], v[204:207], v[10:13]
	v_mfma_f32_16x16x32_bf16 v[6:9], v[150:153], v[212:215], v[6:9]
	v_mfma_f32_16x16x32_bf16 v[2:5], v[158:161], v[212:215], v[2:5]
	s_barrier
	s_add_i32 s53, s53, 2
	s_add_u32 s8, s8, 0x100
	s_addc_u32 s9, s9, 0
	s_add_u32 s51, s51, 0x100
	s_addc_u32 s52, s52, 0
	s_cmp_gt_u32 s53, 29
	s_cbranch_scc0 .LBB0_1942
	s_and_b64 vcc, exec, s[14:15]
	s_cbranch_vccz .LBB0_1945
	s_barrier

.LBB0_2118:
	ds_read_b128 v[142:145], v148
	ds_read_b128 v[152:155], v148 offset:1024
	ds_read_b128 v[156:159], v148 offset:2048
	ds_read_b128 v[160:163], v148 offset:3072
	ds_read_b128 v[164:167], v149
	ds_read_b128 v[168:171], v149 offset:1024
	ds_read_b128 v[172:175], v149 offset:2048
	ds_read_b128 v[176:179], v149 offset:3072
	s_add_u32 s20, s18, 0x100
	s_addc_u32 s21, s19, 0
	s_cmpk_eq_i32 s49, 0x54
	s_cselect_b32 s25, s7, s21
	s_cselect_b32 s24, s6, s20
	s_cselect_b32 s23, s17, s48
	s_cselect_b32 s22, s16, s47
	v_lshl_add_u64 v[212:213], s[18:19], 0, v[134:135]
	s_add_i32 m0, s30, 0xc000
	ds_read_b128 v[180:183], v150
	ds_read_b128 v[184:187], v150 offset:1024
	ds_read_b128 v[188:191], v150 offset:2048
	ds_read_b128 v[192:195], v150 offset:3072
	ds_read_b128 v[196:199], v150 offset:4096
	ds_read_b128 v[200:203], v150 offset:5120
	ds_read_b128 v[204:207], v150 offset:6144
	ds_read_b128 v[208:211], v150 offset:7168
	global_load_lds_dwordx4 v[212:213], off
	v_lshl_add_u64 v[212:213], s[18:19], 0, v[136:137]
	s_add_i32 m0, s30, 0xe000
	s_nop 0
	global_load_lds_dwordx4 v[212:213], off
	s_waitcnt vmcnt(8)
	s_waitcnt lgkmcnt(0)
	s_barrier
	s_waitcnt lgkmcnt(0)
	v_mfma_f32_16x16x32_bf16 v[126:129], v[142:145], v[180:183], v[126:129]
	v_mfma_f32_16x16x32_bf16 v[122:125], v[156:159], v[180:183], v[122:125]
	v_mfma_f32_16x16x32_bf16 v[110:113], v[142:145], v[188:191], v[110:113]
	v_mfma_f32_16x16x32_bf16 v[106:109], v[156:159], v[188:191], v[106:109]
	v_mfma_f32_16x16x32_bf16 v[94:97], v[142:145], v[196:199], v[94:97]
	v_mfma_f32_16x16x32_bf16 v[90:93], v[156:159], v[196:199], v[90:93]
	v_mfma_f32_16x16x32_bf16 v[78:81], v[142:145], v[204:207], v[78:81]
	v_mfma_f32_16x16x32_bf16 v[74:77], v[156:159], v[204:207], v[74:77]
	v_mfma_f32_16x16x32_bf16 v[126:129], v[152:155], v[184:187], v[126:129]
	v_mfma_f32_16x16x32_bf16 v[122:125], v[160:163], v[184:187], v[122:125]
	v_mfma_f32_16x16x32_bf16 v[110:113], v[152:155], v[192:195], v[110:113]
	v_mfma_f32_16x16x32_bf16 v[106:109], v[160:163], v[192:195], v[106:109]
	v_mfma_f32_16x16x32_bf16 v[94:97], v[152:155], v[200:203], v[94:97]
	v_mfma_f32_16x16x32_bf16 v[90:93], v[160:163], v[200:203], v[90:93]
	v_mfma_f32_16x16x32_bf16 v[78:81], v[152:155], v[208:211], v[78:81]
	v_mfma_f32_16x16x32_bf16 v[74:77], v[160:163], v[208:211], v[74:77]
	v_mfma_f32_16x16x32_bf16 v[118:121], v[164:167], v[180:183], v[118:121]
	v_mfma_f32_16x16x32_bf16 v[114:117], v[172:175], v[180:183], v[114:117]
	v_mfma_f32_16x16x32_bf16 v[102:105], v[164:167], v[188:191], v[102:105]
	v_mfma_f32_16x16x32_bf16 v[98:101], v[172:175], v[188:191], v[98:101]
	v_mfma_f32_16x16x32_bf16 v[86:89], v[164:167], v[196:199], v[86:89]
	v_mfma_f32_16x16x32_bf16 v[82:85], v[172:175], v[196:199], v[82:85]
	v_mfma_f32_16x16x32_bf16 v[70:73], v[164:167], v[204:207], v[70:73]
	v_mfma_f32_16x16x32_bf16 v[66:69], v[172:175], v[204:207], v[66:69]
	v_mfma_f32_16x16x32_bf16 v[118:121], v[168:171], v[184:187], v[118:121]
	v_mfma_f32_16x16x32_bf16 v[114:117], v[176:179], v[184:187], v[114:117]
	v_mfma_f32_16x16x32_bf16 v[102:105], v[168:171], v[192:195], v[102:105]
	v_mfma_f32_16x16x32_bf16 v[98:101], v[176:179], v[192:195], v[98:101]
	v_mfma_f32_16x16x32_bf16 v[86:89], v[168:171], v[200:203], v[86:89]
	v_mfma_f32_16x16x32_bf16 v[82:85], v[176:179], v[200:203], v[82:85]
	v_mfma_f32_16x16x32_bf16 v[70:73], v[168:171], v[208:211], v[70:73]
	v_mfma_f32_16x16x32_bf16 v[66:69], v[176:179], v[208:211], v[66:69]
	s_barrier
	s_add_i32 s18, s42, s29
	v_lshl_add_u64 v[212:213], s[22:23], 0, v[130:131]
	s_mov_b32 m0, s18
	ds_read_b128 v[180:183], v150 offset:16384
	ds_read_b128 v[184:187], v150 offset:17408
	ds_read_b128 v[188:191], v150 offset:18432
	ds_read_b128 v[192:195], v150 offset:19456
	ds_read_b128 v[196:199], v150 offset:20480
	ds_read_b128 v[200:203], v150 offset:21504
	ds_read_b128 v[204:207], v150 offset:22528
	ds_read_b128 v[208:211], v150 offset:23552
	global_load_lds_dwordx4 v[212:213], off
	s_add_i32 m0, s18, 0x2000
	s_add_u32 s18, s22, 0x160000
	v_lshl_add_u64 v[214:215], s[22:23], 0, v[132:133]
	s_addc_u32 s19, s23, 0
	s_add_i32 s50, s43, s29
	global_load_lds_dwordx4 v[214:215], off
	v_lshl_add_u64 v[216:217], s[18:19], 0, v[130:131]
	s_mov_b32 m0, s50
	v_lshl_add_u64 v[218:219], s[24:25], 0, v[132:133]
	global_load_lds_dwordx4 v[216:217], off
	v_lshl_add_u64 v[216:217], s[18:19], 0, v[132:133]
	s_add_i32 m0, s50, 0x2000
	s_nop 0
	global_load_lds_dwordx4 v[216:217], off
	v_lshl_add_u64 v[216:217], s[24:25], 0, v[130:131]
	s_mov_b32 m0, s30
	s_nop 0
	global_load_lds_dwordx4 v[216:217], off
	s_mov_b32 m0, s31
	s_nop 0
	global_load_lds_dwordx4 v[218:219], off
	s_waitcnt vmcnt(8)
	s_waitcnt lgkmcnt(0)
	s_barrier
	s_waitcnt lgkmcnt(0)
	v_mfma_f32_16x16x32_bf16 v[62:65], v[142:145], v[180:183], v[62:65]
	v_mfma_f32_16x16x32_bf16 v[58:61], v[156:159], v[180:183], v[58:61]
	v_mfma_f32_16x16x32_bf16 v[46:49], v[142:145], v[188:191], v[46:49]
	v_mfma_f32_16x16x32_bf16 v[42:45], v[156:159], v[188:191], v[42:45]
	v_mfma_f32_16x16x32_bf16 v[30:33], v[142:145], v[196:199], v[30:33]
	v_mfma_f32_16x16x32_bf16 v[26:29], v[156:159], v[196:199], v[26:29]
	v_mfma_f32_16x16x32_bf16 v[14:17], v[142:145], v[204:207], v[14:17]
	v_mfma_f32_16x16x32_bf16 v[10:13], v[156:159], v[204:207], v[10:13]
	v_mfma_f32_16x16x32_bf16 v[62:65], v[152:155], v[184:187], v[62:65]
	v_mfma_f32_16x16x32_bf16 v[58:61], v[160:163], v[184:187], v[58:61]
	v_mfma_f32_16x16x32_bf16 v[46:49], v[152:155], v[192:195], v[46:49]
	v_mfma_f32_16x16x32_bf16 v[42:45], v[160:163], v[192:195], v[42:45]
	v_mfma_f32_16x16x32_bf16 v[30:33], v[152:155], v[200:203], v[30:33]
	v_mfma_f32_16x16x32_bf16 v[26:29], v[160:163], v[200:203], v[26:29]
	v_mfma_f32_16x16x32_bf16 v[14:17], v[152:155], v[208:211], v[14:17]
	v_mfma_f32_16x16x32_bf16 v[10:13], v[160:163], v[208:211], v[10:13]
	v_mfma_f32_16x16x32_bf16 v[54:57], v[164:167], v[180:183], v[54:57]
	v_mfma_f32_16x16x32_bf16 v[50:53], v[172:175], v[180:183], v[50:53]
	v_mfma_f32_16x16x32_bf16 v[38:41], v[164:167], v[188:191], v[38:41]
	v_mfma_f32_16x16x32_bf16 v[34:37], v[172:175], v[188:191], v[34:37]
	v_mfma_f32_16x16x32_bf16 v[22:25], v[164:167], v[196:199], v[22:25]
	v_mfma_f32_16x16x32_bf16 v[18:21], v[172:175], v[196:199], v[18:21]
	v_mfma_f32_16x16x32_bf16 v[6:9], v[164:167], v[204:207], v[6:9]
	v_mfma_f32_16x16x32_bf16 v[2:5], v[172:175], v[204:207], v[2:5]
	v_mfma_f32_16x16x32_bf16 v[54:57], v[168:171], v[184:187], v[54:57]
	v_mfma_f32_16x16x32_bf16 v[50:53], v[176:179], v[184:187], v[50:53]
	v_mfma_f32_16x16x32_bf16 v[38:41], v[168:171], v[192:195], v[38:41]
	v_mfma_f32_16x16x32_bf16 v[34:37], v[176:179], v[192:195], v[34:37]
	v_mfma_f32_16x16x32_bf16 v[22:25], v[168:171], v[200:203], v[22:25]
	v_mfma_f32_16x16x32_bf16 v[18:21], v[176:179], v[200:203], v[18:21]
	v_mfma_f32_16x16x32_bf16 v[6:9], v[168:171], v[208:211], v[6:9]
	v_mfma_f32_16x16x32_bf16 v[2:5], v[176:179], v[208:211], v[2:5]
	s_barrier
	s_add_i32 s50, 0, 0x18000
	s_add_i32 s51, 0, 0x1c000
	v_add_u32_e32 v160, s50, v147
	v_add_u32_e32 v176, s51, v147
	ds_read_b128 v[142:145], v160
	ds_read_b128 v[152:155], v160 offset:1024
	ds_read_b128 v[156:159], v160 offset:2048
	ds_read_b128 v[160:163], v160 offset:3072
	ds_read_b128 v[164:167], v176
	ds_read_b128 v[168:171], v176 offset:1024
	ds_read_b128 v[172:175], v176 offset:2048
	ds_read_b128 v[176:179], v176 offset:3072
	s_add_u32 s18, s24, 0x160000
	s_addc_u32 s19, s25, 0
	s_mov_b32 m0, s33
	v_lshl_add_u64 v[220:221], s[18:19], 0, v[130:131]
	ds_read_b128 v[180:183], v150 offset:32768
	ds_read_b128 v[184:187], v150 offset:33792
	ds_read_b128 v[188:191], v150 offset:34816
	ds_read_b128 v[192:195], v150 offset:35840
	ds_read_b128 v[196:199], v150 offset:36864
	ds_read_b128 v[200:203], v150 offset:37888
	ds_read_b128 v[204:207], v150 offset:38912
	ds_read_b128 v[208:211], v150 offset:39936
	global_load_lds_dwordx4 v[220:221], off
	v_lshl_add_u64 v[220:221], s[18:19], 0, v[132:133]
	s_mov_b32 m0, s34
	s_nop 0
	global_load_lds_dwordx4 v[220:221], off
	s_waitcnt vmcnt(8)
	s_waitcnt lgkmcnt(0)
	s_barrier
	s_waitcnt lgkmcnt(0)
	v_mfma_f32_16x16x32_bf16 v[126:129], v[142:145], v[180:183], v[126:129]
	v_mfma_f32_16x16x32_bf16 v[122:125], v[156:159], v[180:183], v[122:125]
	v_mfma_f32_16x16x32_bf16 v[110:113], v[142:145], v[188:191], v[110:113]
	v_mfma_f32_16x16x32_bf16 v[106:109], v[156:159], v[188:191], v[106:109]
	v_mfma_f32_16x16x32_bf16 v[94:97], v[142:145], v[196:199], v[94:97]
	v_mfma_f32_16x16x32_bf16 v[90:93], v[156:159], v[196:199], v[90:93]
	v_mfma_f32_16x16x32_bf16 v[78:81], v[142:145], v[204:207], v[78:81]
	v_mfma_f32_16x16x32_bf16 v[74:77], v[156:159], v[204:207], v[74:77]
	v_mfma_f32_16x16x32_bf16 v[126:129], v[152:155], v[184:187], v[126:129]
	v_mfma_f32_16x16x32_bf16 v[122:125], v[160:163], v[184:187], v[122:125]
	v_mfma_f32_16x16x32_bf16 v[110:113], v[152:155], v[192:195], v[110:113]
	v_mfma_f32_16x16x32_bf16 v[106:109], v[160:163], v[192:195], v[106:109]
	v_mfma_f32_16x16x32_bf16 v[94:97], v[152:155], v[200:203], v[94:97]
	v_mfma_f32_16x16x32_bf16 v[90:93], v[160:163], v[200:203], v[90:93]
	v_mfma_f32_16x16x32_bf16 v[78:81], v[152:155], v[208:211], v[78:81]
	v_mfma_f32_16x16x32_bf16 v[74:77], v[160:163], v[208:211], v[74:77]
	v_mfma_f32_16x16x32_bf16 v[118:121], v[164:167], v[180:183], v[118:121]
	v_mfma_f32_16x16x32_bf16 v[114:117], v[172:175], v[180:183], v[114:117]
	v_mfma_f32_16x16x32_bf16 v[102:105], v[164:167], v[188:191], v[102:105]
	v_mfma_f32_16x16x32_bf16 v[98:101], v[172:175], v[188:191], v[98:101]
	v_mfma_f32_16x16x32_bf16 v[86:89], v[164:167], v[196:199], v[86:89]
	v_mfma_f32_16x16x32_bf16 v[82:85], v[172:175], v[196:199], v[82:85]
	v_mfma_f32_16x16x32_bf16 v[70:73], v[164:167], v[204:207], v[70:73]
	v_mfma_f32_16x16x32_bf16 v[66:69], v[172:175], v[204:207], v[66:69]
	v_mfma_f32_16x16x32_bf16 v[118:121], v[168:171], v[184:187], v[118:121]
	v_mfma_f32_16x16x32_bf16 v[114:117], v[176:179], v[184:187], v[114:117]
	v_mfma_f32_16x16x32_bf16 v[102:105], v[168:171], v[192:195], v[102:105]
	v_mfma_f32_16x16x32_bf16 v[98:101], v[176:179], v[192:195], v[98:101]
	v_mfma_f32_16x16x32_bf16 v[86:89], v[168:171], v[200:203], v[86:89]
	v_mfma_f32_16x16x32_bf16 v[82:85], v[176:179], v[200:203], v[82:85]
	v_mfma_f32_16x16x32_bf16 v[70:73], v[168:171], v[208:211], v[70:73]
	v_mfma_f32_16x16x32_bf16 v[66:69], v[176:179], v[208:211], v[66:69]
	s_barrier
	s_add_i32 s18, s50, s29
	v_lshl_add_u64 v[212:213], v[212:213], 0, s[12:13]
	s_mov_b32 m0, s18
	ds_read_b128 v[180:183], v150 offset:49152
	ds_read_b128 v[184:187], v150 offset:50176
	ds_read_b128 v[188:191], v150 offset:51200
	ds_read_b128 v[192:195], v150 offset:52224
	ds_read_b128 v[196:199], v150 offset:53248
	ds_read_b128 v[200:203], v150 offset:54272
	ds_read_b128 v[204:207], v150 offset:55296
	ds_read_b128 v[208:211], v150 offset:56320
	global_load_lds_dwordx4 v[212:213], off
	s_add_i32 m0, s18, 0x2000
	s_add_u32 s18, s22, 0x160080
	v_lshl_add_u64 v[212:213], v[214:215], 0, s[12:13]
	s_addc_u32 s19, s23, 0
	s_add_i32 s22, s51, s29
	global_load_lds_dwordx4 v[212:213], off
	v_lshl_add_u64 v[212:213], s[18:19], 0, v[130:131]
	s_mov_b32 m0, s22
	s_nop 0
	global_load_lds_dwordx4 v[212:213], off
	v_lshl_add_u64 v[212:213], s[18:19], 0, v[132:133]
	s_add_i32 m0, s22, 0x2000
	s_nop 0
	global_load_lds_dwordx4 v[212:213], off
	v_lshl_add_u64 v[212:213], v[216:217], 0, s[12:13]
	s_mov_b32 m0, s38
	s_nop 0
	global_load_lds_dwordx4 v[212:213], off
	v_lshl_add_u64 v[212:213], v[218:219], 0, s[12:13]
	s_mov_b32 m0, s39
	s_nop 0
	global_load_lds_dwordx4 v[212:213], off
	s_waitcnt vmcnt(8)
	s_waitcnt lgkmcnt(0)
	s_barrier
	s_waitcnt lgkmcnt(0)
	v_mfma_f32_16x16x32_bf16 v[62:65], v[142:145], v[180:183], v[62:65]
	v_mfma_f32_16x16x32_bf16 v[58:61], v[156:159], v[180:183], v[58:61]
	v_mfma_f32_16x16x32_bf16 v[46:49], v[142:145], v[188:191], v[46:49]
	v_mfma_f32_16x16x32_bf16 v[42:45], v[156:159], v[188:191], v[42:45]
	v_mfma_f32_16x16x32_bf16 v[30:33], v[142:145], v[196:199], v[30:33]
	v_mfma_f32_16x16x32_bf16 v[26:29], v[156:159], v[196:199], v[26:29]
	v_mfma_f32_16x16x32_bf16 v[14:17], v[142:145], v[204:207], v[14:17]
	v_mfma_f32_16x16x32_bf16 v[10:13], v[156:159], v[204:207], v[10:13]
	v_mfma_f32_16x16x32_bf16 v[62:65], v[152:155], v[184:187], v[62:65]
	v_mfma_f32_16x16x32_bf16 v[58:61], v[160:163], v[184:187], v[58:61]
	v_mfma_f32_16x16x32_bf16 v[46:49], v[152:155], v[192:195], v[46:49]
	v_mfma_f32_16x16x32_bf16 v[42:45], v[160:163], v[192:195], v[42:45]
	v_mfma_f32_16x16x32_bf16 v[30:33], v[152:155], v[200:203], v[30:33]
	v_mfma_f32_16x16x32_bf16 v[26:29], v[160:163], v[200:203], v[26:29]
	v_mfma_f32_16x16x32_bf16 v[14:17], v[152:155], v[208:211], v[14:17]
	v_mfma_f32_16x16x32_bf16 v[10:13], v[160:163], v[208:211], v[10:13]
	v_mfma_f32_16x16x32_bf16 v[54:57], v[164:167], v[180:183], v[54:57]
	v_mfma_f32_16x16x32_bf16 v[50:53], v[172:175], v[180:183], v[50:53]
	v_mfma_f32_16x16x32_bf16 v[38:41], v[164:167], v[188:191], v[38:41]
	v_mfma_f32_16x16x32_bf16 v[34:37], v[172:175], v[188:191], v[34:37]
	v_mfma_f32_16x16x32_bf16 v[22:25], v[164:167], v[196:199], v[22:25]
	v_mfma_f32_16x16x32_bf16 v[18:21], v[172:175], v[196:199], v[18:21]
	v_mfma_f32_16x16x32_bf16 v[6:9], v[164:167], v[204:207], v[6:9]
	v_mfma_f32_16x16x32_bf16 v[2:5], v[172:175], v[204:207], v[2:5]
	v_mfma_f32_16x16x32_bf16 v[54:57], v[168:171], v[184:187], v[54:57]
	v_mfma_f32_16x16x32_bf16 v[50:53], v[176:179], v[184:187], v[50:53]
	v_mfma_f32_16x16x32_bf16 v[38:41], v[168:171], v[192:195], v[38:41]
	v_mfma_f32_16x16x32_bf16 v[34:37], v[176:179], v[192:195], v[34:37]
	v_mfma_f32_16x16x32_bf16 v[22:25], v[168:171], v[200:203], v[22:25]
	v_mfma_f32_16x16x32_bf16 v[18:21], v[176:179], v[200:203], v[18:21]
	v_mfma_f32_16x16x32_bf16 v[6:9], v[168:171], v[208:211], v[6:9]
	v_mfma_f32_16x16x32_bf16 v[2:5], v[176:179], v[208:211], v[2:5]
	s_barrier
	s_add_i32 s49, s49, 2
	s_add_u32 s47, s47, 0x100
	s_addc_u32 s48, s48, 0
	s_cmpk_gt_u32 s49, 0x55
	s_mov_b64 s[18:19], s[20:21]
	s_cbranch_scc0 .LBB0_2118
	s_and_b64 vcc, exec, s[14:15]
	s_cbranch_vccz .LBB0_2121
	s_barrier

.LBB0_2207:
	ds_read_b128 v[130:133], v197
	ds_read_b128 v[134:137], v197 offset:1024
	ds_read_b128 v[138:141], v197 offset:2048
	ds_read_b128 v[142:145], v197 offset:3072
	ds_read_b128 v[146:149], v198
	ds_read_b128 v[150:153], v198 offset:1024
	ds_read_b128 v[154:157], v198 offset:2048
	ds_read_b128 v[158:161], v198 offset:3072
	s_add_u32 s28, s10, 0xfff80080
	s_addc_u32 s29, s11, -1
	s_cmp_eq_u32 s36, 28
	s_cselect_b32 s31, s7, s29
	s_cselect_b32 s30, s9, s28
	s_cselect_b32 s29, s21, s35
	s_cselect_b32 s28, s23, s34
	v_lshl_add_u64 v[194:195], s[10:11], 0, v[184:185]
	s_add_i32 m0, s39, 0xc000
	ds_read_b128 v[162:165], v199
	ds_read_b128 v[166:169], v199 offset:1024
	ds_read_b128 v[170:173], v199 offset:2048
	ds_read_b128 v[174:177], v199 offset:3072
	ds_read_b128 v[202:205], v199 offset:4096
	ds_read_b128 v[206:209], v199 offset:5120
	ds_read_b128 v[210:213], v199 offset:6144
	ds_read_b128 v[214:217], v199 offset:7168
	global_load_lds_dwordx4 v[194:195], off
	v_lshl_add_u64 v[194:195], s[10:11], 0, v[186:187]
	s_add_i32 m0, s39, 0xe000
	s_nop 0
	global_load_lds_dwordx4 v[194:195], off
	s_waitcnt vmcnt(8)
	s_waitcnt lgkmcnt(0)
	s_barrier
	s_waitcnt lgkmcnt(0)
	v_mfma_f32_16x16x32_bf16 v[126:129], v[130:133], v[162:165], v[126:129]
	v_mfma_f32_16x16x32_bf16 v[122:125], v[138:141], v[162:165], v[122:125]
	v_mfma_f32_16x16x32_bf16 v[110:113], v[130:133], v[170:173], v[110:113]
	v_mfma_f32_16x16x32_bf16 v[106:109], v[138:141], v[170:173], v[106:109]
	v_mfma_f32_16x16x32_bf16 v[94:97], v[130:133], v[202:205], v[94:97]
	v_mfma_f32_16x16x32_bf16 v[90:93], v[138:141], v[202:205], v[90:93]
	v_mfma_f32_16x16x32_bf16 v[78:81], v[130:133], v[210:213], v[78:81]
	v_mfma_f32_16x16x32_bf16 v[74:77], v[138:141], v[210:213], v[74:77]
	v_mfma_f32_16x16x32_bf16 v[126:129], v[134:137], v[166:169], v[126:129]
	v_mfma_f32_16x16x32_bf16 v[122:125], v[142:145], v[166:169], v[122:125]
	v_mfma_f32_16x16x32_bf16 v[110:113], v[134:137], v[174:177], v[110:113]
	v_mfma_f32_16x16x32_bf16 v[106:109], v[142:145], v[174:177], v[106:109]
	v_mfma_f32_16x16x32_bf16 v[94:97], v[134:137], v[206:209], v[94:97]
	v_mfma_f32_16x16x32_bf16 v[90:93], v[142:145], v[206:209], v[90:93]
	v_mfma_f32_16x16x32_bf16 v[78:81], v[134:137], v[214:217], v[78:81]
	v_mfma_f32_16x16x32_bf16 v[74:77], v[142:145], v[214:217], v[74:77]
	v_mfma_f32_16x16x32_bf16 v[118:121], v[146:149], v[162:165], v[118:121]
	v_mfma_f32_16x16x32_bf16 v[114:117], v[154:157], v[162:165], v[114:117]
	v_mfma_f32_16x16x32_bf16 v[102:105], v[146:149], v[170:173], v[102:105]
	v_mfma_f32_16x16x32_bf16 v[98:101], v[154:157], v[170:173], v[98:101]
	v_mfma_f32_16x16x32_bf16 v[86:89], v[146:149], v[202:205], v[86:89]
	v_mfma_f32_16x16x32_bf16 v[82:85], v[154:157], v[202:205], v[82:85]
	v_mfma_f32_16x16x32_bf16 v[70:73], v[146:149], v[210:213], v[70:73]
	v_mfma_f32_16x16x32_bf16 v[66:69], v[154:157], v[210:213], v[66:69]
	v_mfma_f32_16x16x32_bf16 v[118:121], v[150:153], v[166:169], v[118:121]
	v_mfma_f32_16x16x32_bf16 v[114:117], v[158:161], v[166:169], v[114:117]
	v_mfma_f32_16x16x32_bf16 v[102:105], v[150:153], v[174:177], v[102:105]
	v_mfma_f32_16x16x32_bf16 v[98:101], v[158:161], v[174:177], v[98:101]
	v_mfma_f32_16x16x32_bf16 v[86:89], v[150:153], v[206:209], v[86:89]
	v_mfma_f32_16x16x32_bf16 v[82:85], v[158:161], v[206:209], v[82:85]
	v_mfma_f32_16x16x32_bf16 v[70:73], v[150:153], v[214:217], v[70:73]
	v_mfma_f32_16x16x32_bf16 v[66:69], v[158:161], v[214:217], v[66:69]
	s_barrier
	s_add_i32 s37, s52, s38
	v_lshl_add_u64 v[194:195], s[28:29], 0, v[178:179]
	s_mov_b32 m0, s37
	ds_read_b128 v[162:165], v199 offset:16384
	ds_read_b128 v[166:169], v199 offset:17408
	ds_read_b128 v[170:173], v199 offset:18432
	ds_read_b128 v[174:177], v199 offset:19456
	ds_read_b128 v[202:205], v199 offset:20480
	ds_read_b128 v[206:209], v199 offset:21504
	ds_read_b128 v[210:213], v199 offset:22528
	ds_read_b128 v[214:217], v199 offset:23552
	global_load_lds_dwordx4 v[194:195], off
	s_add_i32 m0, s37, 0x2000
	s_add_u32 s56, s28, 0x80000
	v_lshl_add_u64 v[218:219], s[28:29], 0, v[180:181]
	s_addc_u32 s57, s29, 0
	s_add_i32 s37, s53, s38
	global_load_lds_dwordx4 v[218:219], off
	v_lshl_add_u64 v[220:221], s[56:57], 0, v[178:179]
	s_mov_b32 m0, s37
	v_lshl_add_u64 v[222:223], s[30:31], 0, v[180:181]
	global_load_lds_dwordx4 v[220:221], off
	v_lshl_add_u64 v[220:221], s[56:57], 0, v[180:181]
	s_add_i32 m0, s37, 0x2000
	s_nop 0
	global_load_lds_dwordx4 v[220:221], off
	v_lshl_add_u64 v[220:221], s[30:31], 0, v[178:179]
	s_mov_b32 m0, s39
	s_nop 0
	global_load_lds_dwordx4 v[220:221], off
	s_mov_b32 m0, s40
	s_nop 0
	global_load_lds_dwordx4 v[222:223], off
	s_waitcnt vmcnt(8)
	s_waitcnt lgkmcnt(0)
	s_barrier
	s_waitcnt lgkmcnt(0)
	v_mfma_f32_16x16x32_bf16 v[62:65], v[130:133], v[162:165], v[62:65]
	v_mfma_f32_16x16x32_bf16 v[58:61], v[138:141], v[162:165], v[58:61]
	v_mfma_f32_16x16x32_bf16 v[46:49], v[130:133], v[170:173], v[46:49]
	v_mfma_f32_16x16x32_bf16 v[42:45], v[138:141], v[170:173], v[42:45]
	v_mfma_f32_16x16x32_bf16 v[30:33], v[130:133], v[202:205], v[30:33]
	v_mfma_f32_16x16x32_bf16 v[26:29], v[138:141], v[202:205], v[26:29]
	v_mfma_f32_16x16x32_bf16 v[14:17], v[130:133], v[210:213], v[14:17]
	v_mfma_f32_16x16x32_bf16 v[10:13], v[138:141], v[210:213], v[10:13]
	v_mfma_f32_16x16x32_bf16 v[62:65], v[134:137], v[166:169], v[62:65]
	v_mfma_f32_16x16x32_bf16 v[58:61], v[142:145], v[166:169], v[58:61]
	v_mfma_f32_16x16x32_bf16 v[46:49], v[134:137], v[174:177], v[46:49]
	v_mfma_f32_16x16x32_bf16 v[42:45], v[142:145], v[174:177], v[42:45]
	v_mfma_f32_16x16x32_bf16 v[30:33], v[134:137], v[206:209], v[30:33]
	v_mfma_f32_16x16x32_bf16 v[26:29], v[142:145], v[206:209], v[26:29]
	v_mfma_f32_16x16x32_bf16 v[14:17], v[134:137], v[214:217], v[14:17]
	v_mfma_f32_16x16x32_bf16 v[10:13], v[142:145], v[214:217], v[10:13]
	v_mfma_f32_16x16x32_bf16 v[54:57], v[146:149], v[162:165], v[54:57]
	v_mfma_f32_16x16x32_bf16 v[50:53], v[154:157], v[162:165], v[50:53]
	v_mfma_f32_16x16x32_bf16 v[38:41], v[146:149], v[170:173], v[38:41]
	v_mfma_f32_16x16x32_bf16 v[34:37], v[154:157], v[170:173], v[34:37]
	v_mfma_f32_16x16x32_bf16 v[22:25], v[146:149], v[202:205], v[22:25]
	v_mfma_f32_16x16x32_bf16 v[18:21], v[154:157], v[202:205], v[18:21]
	v_mfma_f32_16x16x32_bf16 v[6:9], v[146:149], v[210:213], v[6:9]
	v_mfma_f32_16x16x32_bf16 v[2:5], v[154:157], v[210:213], v[2:5]
	v_mfma_f32_16x16x32_bf16 v[54:57], v[150:153], v[166:169], v[54:57]
	v_mfma_f32_16x16x32_bf16 v[50:53], v[158:161], v[166:169], v[50:53]
	v_mfma_f32_16x16x32_bf16 v[38:41], v[150:153], v[174:177], v[38:41]
	v_mfma_f32_16x16x32_bf16 v[34:37], v[158:161], v[174:177], v[34:37]
	v_mfma_f32_16x16x32_bf16 v[22:25], v[150:153], v[206:209], v[22:25]
	v_mfma_f32_16x16x32_bf16 v[18:21], v[158:161], v[206:209], v[18:21]
	v_mfma_f32_16x16x32_bf16 v[6:9], v[150:153], v[214:217], v[6:9]
	v_mfma_f32_16x16x32_bf16 v[2:5], v[158:161], v[214:217], v[2:5]
	s_barrier
	s_add_i32 s37, 0, 0x18000
	s_add_i32 s56, 0, 0x1c000
	v_add_u32_e32 v142, s37, v196
	v_add_u32_e32 v158, s56, v196
	ds_read_b128 v[130:133], v142
	ds_read_b128 v[134:137], v142 offset:1024
	ds_read_b128 v[138:141], v142 offset:2048
	ds_read_b128 v[142:145], v142 offset:3072
	ds_read_b128 v[146:149], v158
	ds_read_b128 v[150:153], v158 offset:1024
	ds_read_b128 v[154:157], v158 offset:2048
	ds_read_b128 v[158:161], v158 offset:3072
	s_add_u32 s30, s30, 0x80000
	s_addc_u32 s31, s31, 0
	s_mov_b32 m0, s41
	v_lshl_add_u64 v[224:225], s[30:31], 0, v[178:179]
	ds_read_b128 v[162:165], v199 offset:32768
	ds_read_b128 v[166:169], v199 offset:33792
	ds_read_b128 v[170:173], v199 offset:34816
	ds_read_b128 v[174:177], v199 offset:35840
	ds_read_b128 v[202:205], v199 offset:36864
	ds_read_b128 v[206:209], v199 offset:37888
	ds_read_b128 v[210:213], v199 offset:38912
	ds_read_b128 v[214:217], v199 offset:39936
	global_load_lds_dwordx4 v[224:225], off
	v_lshl_add_u64 v[224:225], s[30:31], 0, v[180:181]
	s_mov_b32 m0, s42
	s_nop 0
	global_load_lds_dwordx4 v[224:225], off
	s_waitcnt vmcnt(8)
	s_waitcnt lgkmcnt(0)
	s_barrier
	s_waitcnt lgkmcnt(0)
	v_mfma_f32_16x16x32_bf16 v[126:129], v[130:133], v[162:165], v[126:129]
	v_mfma_f32_16x16x32_bf16 v[122:125], v[138:141], v[162:165], v[122:125]
	v_mfma_f32_16x16x32_bf16 v[110:113], v[130:133], v[170:173], v[110:113]
	v_mfma_f32_16x16x32_bf16 v[106:109], v[138:141], v[170:173], v[106:109]
	v_mfma_f32_16x16x32_bf16 v[94:97], v[130:133], v[202:205], v[94:97]
	v_mfma_f32_16x16x32_bf16 v[90:93], v[138:141], v[202:205], v[90:93]
	v_mfma_f32_16x16x32_bf16 v[78:81], v[130:133], v[210:213], v[78:81]
	v_mfma_f32_16x16x32_bf16 v[74:77], v[138:141], v[210:213], v[74:77]
	v_mfma_f32_16x16x32_bf16 v[126:129], v[134:137], v[166:169], v[126:129]
	v_mfma_f32_16x16x32_bf16 v[122:125], v[142:145], v[166:169], v[122:125]
	v_mfma_f32_16x16x32_bf16 v[110:113], v[134:137], v[174:177], v[110:113]
	v_mfma_f32_16x16x32_bf16 v[106:109], v[142:145], v[174:177], v[106:109]
	v_mfma_f32_16x16x32_bf16 v[94:97], v[134:137], v[206:209], v[94:97]
	v_mfma_f32_16x16x32_bf16 v[90:93], v[142:145], v[206:209], v[90:93]
	v_mfma_f32_16x16x32_bf16 v[78:81], v[134:137], v[214:217], v[78:81]
	v_mfma_f32_16x16x32_bf16 v[74:77], v[142:145], v[214:217], v[74:77]
	v_mfma_f32_16x16x32_bf16 v[118:121], v[146:149], v[162:165], v[118:121]
	v_mfma_f32_16x16x32_bf16 v[114:117], v[154:157], v[162:165], v[114:117]
	v_mfma_f32_16x16x32_bf16 v[102:105], v[146:149], v[170:173], v[102:105]
	v_mfma_f32_16x16x32_bf16 v[98:101], v[154:157], v[170:173], v[98:101]
	v_mfma_f32_16x16x32_bf16 v[86:89], v[146:149], v[202:205], v[86:89]
	v_mfma_f32_16x16x32_bf16 v[82:85], v[154:157], v[202:205], v[82:85]
	v_mfma_f32_16x16x32_bf16 v[70:73], v[146:149], v[210:213], v[70:73]
	v_mfma_f32_16x16x32_bf16 v[66:69], v[154:157], v[210:213], v[66:69]
	v_mfma_f32_16x16x32_bf16 v[118:121], v[150:153], v[166:169], v[118:121]
	v_mfma_f32_16x16x32_bf16 v[114:117], v[158:161], v[166:169], v[114:117]
	v_mfma_f32_16x16x32_bf16 v[102:105], v[150:153], v[174:177], v[102:105]
	v_mfma_f32_16x16x32_bf16 v[98:101], v[158:161], v[174:177], v[98:101]
	v_mfma_f32_16x16x32_bf16 v[86:89], v[150:153], v[206:209], v[86:89]
	v_mfma_f32_16x16x32_bf16 v[82:85], v[158:161], v[206:209], v[82:85]
	v_mfma_f32_16x16x32_bf16 v[70:73], v[150:153], v[214:217], v[70:73]
	v_mfma_f32_16x16x32_bf16 v[66:69], v[158:161], v[214:217], v[66:69]
	s_barrier
	s_add_i32 s30, s37, s38
	v_lshl_add_u64 v[194:195], v[194:195], 0, s[14:15]
	s_mov_b32 m0, s30
	ds_read_b128 v[162:165], v199 offset:49152
	ds_read_b128 v[166:169], v199 offset:50176
	ds_read_b128 v[170:173], v199 offset:51200
	ds_read_b128 v[174:177], v199 offset:52224
	ds_read_b128 v[202:205], v199 offset:53248
	ds_read_b128 v[206:209], v199 offset:54272
	ds_read_b128 v[210:213], v199 offset:55296
	ds_read_b128 v[214:217], v199 offset:56320
	global_load_lds_dwordx4 v[194:195], off
	s_add_i32 m0, s30, 0x2000
	s_add_u32 s28, s28, 0x80080
	v_lshl_add_u64 v[194:195], v[218:219], 0, s[14:15]
	s_addc_u32 s29, s29, 0
	s_add_i32 s30, s56, s38
	global_load_lds_dwordx4 v[194:195], off
	v_lshl_add_u64 v[194:195], s[28:29], 0, v[178:179]
	s_mov_b32 m0, s30
	s_nop 0
	global_load_lds_dwordx4 v[194:195], off
	v_lshl_add_u64 v[194:195], s[28:29], 0, v[180:181]
	s_add_i32 m0, s30, 0x2000
	s_nop 0
	global_load_lds_dwordx4 v[194:195], off
	v_lshl_add_u64 v[194:195], v[220:221], 0, s[14:15]
	s_mov_b32 m0, s46
	s_nop 0
	global_load_lds_dwordx4 v[194:195], off
	v_lshl_add_u64 v[194:195], v[222:223], 0, s[14:15]
	s_mov_b32 m0, s47
	s_nop 0
	global_load_lds_dwordx4 v[194:195], off
	s_waitcnt vmcnt(8)
	s_waitcnt lgkmcnt(0)
	s_barrier
	s_waitcnt lgkmcnt(0)
	v_mfma_f32_16x16x32_bf16 v[62:65], v[130:133], v[162:165], v[62:65]
	v_mfma_f32_16x16x32_bf16 v[58:61], v[138:141], v[162:165], v[58:61]
	v_mfma_f32_16x16x32_bf16 v[46:49], v[130:133], v[170:173], v[46:49]
	v_mfma_f32_16x16x32_bf16 v[42:45], v[138:141], v[170:173], v[42:45]
	v_mfma_f32_16x16x32_bf16 v[30:33], v[130:133], v[202:205], v[30:33]
	v_mfma_f32_16x16x32_bf16 v[26:29], v[138:141], v[202:205], v[26:29]
	v_mfma_f32_16x16x32_bf16 v[14:17], v[130:133], v[210:213], v[14:17]
	v_mfma_f32_16x16x32_bf16 v[10:13], v[138:141], v[210:213], v[10:13]
	v_mfma_f32_16x16x32_bf16 v[62:65], v[134:137], v[166:169], v[62:65]
	v_mfma_f32_16x16x32_bf16 v[58:61], v[142:145], v[166:169], v[58:61]
	v_mfma_f32_16x16x32_bf16 v[46:49], v[134:137], v[174:177], v[46:49]
	v_mfma_f32_16x16x32_bf16 v[42:45], v[142:145], v[174:177], v[42:45]
	v_mfma_f32_16x16x32_bf16 v[30:33], v[134:137], v[206:209], v[30:33]
	v_mfma_f32_16x16x32_bf16 v[26:29], v[142:145], v[206:209], v[26:29]
	v_mfma_f32_16x16x32_bf16 v[14:17], v[134:137], v[214:217], v[14:17]
	v_mfma_f32_16x16x32_bf16 v[10:13], v[142:145], v[214:217], v[10:13]
	v_mfma_f32_16x16x32_bf16 v[54:57], v[146:149], v[162:165], v[54:57]
	v_mfma_f32_16x16x32_bf16 v[50:53], v[154:157], v[162:165], v[50:53]
	v_mfma_f32_16x16x32_bf16 v[38:41], v[146:149], v[170:173], v[38:41]
	v_mfma_f32_16x16x32_bf16 v[34:37], v[154:157], v[170:173], v[34:37]
	v_mfma_f32_16x16x32_bf16 v[22:25], v[146:149], v[202:205], v[22:25]
	v_mfma_f32_16x16x32_bf16 v[18:21], v[154:157], v[202:205], v[18:21]
	v_mfma_f32_16x16x32_bf16 v[6:9], v[146:149], v[210:213], v[6:9]
	v_mfma_f32_16x16x32_bf16 v[2:5], v[154:157], v[210:213], v[2:5]
	v_mfma_f32_16x16x32_bf16 v[54:57], v[150:153], v[166:169], v[54:57]
	v_mfma_f32_16x16x32_bf16 v[50:53], v[158:161], v[166:169], v[50:53]
	v_mfma_f32_16x16x32_bf16 v[38:41], v[150:153], v[174:177], v[38:41]
	v_mfma_f32_16x16x32_bf16 v[34:37], v[158:161], v[174:177], v[34:37]
	v_mfma_f32_16x16x32_bf16 v[22:25], v[150:153], v[206:209], v[22:25]
	v_mfma_f32_16x16x32_bf16 v[18:21], v[158:161], v[206:209], v[18:21]
	v_mfma_f32_16x16x32_bf16 v[6:9], v[150:153], v[214:217], v[6:9]
	v_mfma_f32_16x16x32_bf16 v[2:5], v[158:161], v[214:217], v[2:5]
	s_barrier
	s_add_i32 s36, s36, 2
	s_add_u32 s10, s10, 0x100
	s_addc_u32 s11, s11, 0
	s_add_u32 s34, s34, 0x100
	s_addc_u32 s35, s35, 0
	s_cmp_gt_u32 s36, 29
	s_cbranch_scc0 .LBB0_2207
	s_and_b64 vcc, exec, s[16:17]
	s_cbranch_vccz .LBB0_2210
	s_barrier

.LBB0_2412:
	ds_read_b128 v[138:141], v144
	ds_read_b128 v[150:153], v144 offset:1024
	ds_read_b128 v[154:157], v144 offset:2048
	ds_read_b128 v[158:161], v144 offset:3072
	ds_read_b128 v[162:165], v145
	ds_read_b128 v[166:169], v145 offset:1024
	ds_read_b128 v[170:173], v145 offset:2048
	ds_read_b128 v[174:177], v145 offset:3072
	s_add_u32 s24, s22, 0x100
	s_addc_u32 s25, s23, 0
	s_add_u32 s26, s54, s22
	s_addc_u32 s27, s55, s23
	s_cmp_eq_u32 s56, 28
	s_cselect_b32 s28, 0, s24
	s_cselect_b32 s29, 0, s25
	s_cselect_b32 s26, s19, s26
	s_cselect_b32 s27, s10, s27
	s_add_u32 s28, s8, s28
	s_addc_u32 s29, s9, s29
	s_mov_b32 m0, s42
	v_lshl_add_u64 v[210:211], v[134:135], 0, s[22:23]
	ds_read_b128 v[178:181], v146
	ds_read_b128 v[182:185], v146 offset:1024
	ds_read_b128 v[186:189], v146 offset:2048
	ds_read_b128 v[190:193], v146 offset:3072
	ds_read_b128 v[194:197], v146 offset:4096
	ds_read_b128 v[198:201], v146 offset:5120
	ds_read_b128 v[202:205], v146 offset:6144
	ds_read_b128 v[206:209], v146 offset:7168
	global_load_lds_dwordx4 v[210:211], off
	v_lshl_add_u64 v[210:211], v[136:137], 0, s[22:23]
	s_mov_b32 m0, s43
	s_nop 0
	global_load_lds_dwordx4 v[210:211], off
	s_waitcnt vmcnt(8)
	s_waitcnt lgkmcnt(0)
	s_barrier
	s_waitcnt lgkmcnt(0)
	v_mfma_f32_16x16x32_bf16 v[126:129], v[138:141], v[178:181], v[126:129]
	v_mfma_f32_16x16x32_bf16 v[122:125], v[154:157], v[178:181], v[122:125]
	v_mfma_f32_16x16x32_bf16 v[110:113], v[138:141], v[186:189], v[110:113]
	v_mfma_f32_16x16x32_bf16 v[106:109], v[154:157], v[186:189], v[106:109]
	v_mfma_f32_16x16x32_bf16 v[94:97], v[138:141], v[194:197], v[94:97]
	v_mfma_f32_16x16x32_bf16 v[90:93], v[154:157], v[194:197], v[90:93]
	v_mfma_f32_16x16x32_bf16 v[78:81], v[138:141], v[202:205], v[78:81]
	v_mfma_f32_16x16x32_bf16 v[74:77], v[154:157], v[202:205], v[74:77]
	v_mfma_f32_16x16x32_bf16 v[126:129], v[150:153], v[182:185], v[126:129]
	v_mfma_f32_16x16x32_bf16 v[122:125], v[158:161], v[182:185], v[122:125]
	v_mfma_f32_16x16x32_bf16 v[110:113], v[150:153], v[190:193], v[110:113]
	v_mfma_f32_16x16x32_bf16 v[106:109], v[158:161], v[190:193], v[106:109]
	v_mfma_f32_16x16x32_bf16 v[94:97], v[150:153], v[198:201], v[94:97]
	v_mfma_f32_16x16x32_bf16 v[90:93], v[158:161], v[198:201], v[90:93]
	v_mfma_f32_16x16x32_bf16 v[78:81], v[150:153], v[206:209], v[78:81]
	v_mfma_f32_16x16x32_bf16 v[74:77], v[158:161], v[206:209], v[74:77]
	v_mfma_f32_16x16x32_bf16 v[118:121], v[162:165], v[178:181], v[118:121]
	v_mfma_f32_16x16x32_bf16 v[114:117], v[170:173], v[178:181], v[114:117]
	v_mfma_f32_16x16x32_bf16 v[102:105], v[162:165], v[186:189], v[102:105]
	v_mfma_f32_16x16x32_bf16 v[98:101], v[170:173], v[186:189], v[98:101]
	v_mfma_f32_16x16x32_bf16 v[86:89], v[162:165], v[194:197], v[86:89]
	v_mfma_f32_16x16x32_bf16 v[82:85], v[170:173], v[194:197], v[82:85]
	v_mfma_f32_16x16x32_bf16 v[70:73], v[162:165], v[202:205], v[70:73]
	v_mfma_f32_16x16x32_bf16 v[66:69], v[170:173], v[202:205], v[66:69]
	v_mfma_f32_16x16x32_bf16 v[118:121], v[166:169], v[182:185], v[118:121]
	v_mfma_f32_16x16x32_bf16 v[114:117], v[174:177], v[182:185], v[114:117]
	v_mfma_f32_16x16x32_bf16 v[102:105], v[166:169], v[190:193], v[102:105]
	v_mfma_f32_16x16x32_bf16 v[98:101], v[174:177], v[190:193], v[98:101]
	v_mfma_f32_16x16x32_bf16 v[86:89], v[166:169], v[198:201], v[86:89]
	v_mfma_f32_16x16x32_bf16 v[82:85], v[174:177], v[198:201], v[82:85]
	v_mfma_f32_16x16x32_bf16 v[70:73], v[166:169], v[206:209], v[70:73]
	v_mfma_f32_16x16x32_bf16 v[66:69], v[174:177], v[206:209], v[66:69]
	s_barrier
	s_mov_b32 m0, s44
	v_lshl_add_u64 v[210:211], s[26:27], 0, v[132:133]
	s_add_u32 s22, s26, 0x80000
	ds_read_b128 v[178:181], v146 offset:16384
	ds_read_b128 v[182:185], v146 offset:17408
	ds_read_b128 v[186:189], v146 offset:18432
	ds_read_b128 v[190:193], v146 offset:19456
	ds_read_b128 v[194:197], v146 offset:20480
	ds_read_b128 v[198:201], v146 offset:21504
	ds_read_b128 v[202:205], v146 offset:22528
	ds_read_b128 v[206:209], v146 offset:23552
	global_load_lds_dwordx4 v[210:211], off
	v_lshl_add_u64 v[212:213], s[26:27], 0, v[130:131]
	s_mov_b32 m0, s45
	s_addc_u32 s23, s27, 0
	global_load_lds_dwordx4 v[212:213], off
	v_lshl_add_u64 v[214:215], s[22:23], 0, v[132:133]
	s_mov_b32 m0, s46
	v_lshl_add_u64 v[216:217], s[28:29], 0, v[130:131]
	global_load_lds_dwordx4 v[214:215], off
	v_lshl_add_u64 v[214:215], s[22:23], 0, v[130:131]
	s_mov_b32 m0, s47
	s_nop 0
	global_load_lds_dwordx4 v[214:215], off
	v_lshl_add_u64 v[214:215], s[28:29], 0, v[132:133]
	s_mov_b32 m0, s33
	s_nop 0
	global_load_lds_dwordx4 v[214:215], off
	s_mov_b32 m0, s34
	s_nop 0
	global_load_lds_dwordx4 v[216:217], off
	s_waitcnt vmcnt(8)
	s_waitcnt lgkmcnt(0)
	s_barrier
	s_waitcnt lgkmcnt(0)
	v_mfma_f32_16x16x32_bf16 v[62:65], v[138:141], v[178:181], v[62:65]
	v_mfma_f32_16x16x32_bf16 v[58:61], v[154:157], v[178:181], v[58:61]
	v_mfma_f32_16x16x32_bf16 v[46:49], v[138:141], v[186:189], v[46:49]
	v_mfma_f32_16x16x32_bf16 v[42:45], v[154:157], v[186:189], v[42:45]
	v_mfma_f32_16x16x32_bf16 v[30:33], v[138:141], v[194:197], v[30:33]
	v_mfma_f32_16x16x32_bf16 v[26:29], v[154:157], v[194:197], v[26:29]
	v_mfma_f32_16x16x32_bf16 v[14:17], v[138:141], v[202:205], v[14:17]
	v_mfma_f32_16x16x32_bf16 v[10:13], v[154:157], v[202:205], v[10:13]
	v_mfma_f32_16x16x32_bf16 v[62:65], v[150:153], v[182:185], v[62:65]
	v_mfma_f32_16x16x32_bf16 v[58:61], v[158:161], v[182:185], v[58:61]
	v_mfma_f32_16x16x32_bf16 v[46:49], v[150:153], v[190:193], v[46:49]
	v_mfma_f32_16x16x32_bf16 v[42:45], v[158:161], v[190:193], v[42:45]
	v_mfma_f32_16x16x32_bf16 v[30:33], v[150:153], v[198:201], v[30:33]
	v_mfma_f32_16x16x32_bf16 v[26:29], v[158:161], v[198:201], v[26:29]
	v_mfma_f32_16x16x32_bf16 v[14:17], v[150:153], v[206:209], v[14:17]
	v_mfma_f32_16x16x32_bf16 v[10:13], v[158:161], v[206:209], v[10:13]
	v_mfma_f32_16x16x32_bf16 v[54:57], v[162:165], v[178:181], v[54:57]
	v_mfma_f32_16x16x32_bf16 v[50:53], v[170:173], v[178:181], v[50:53]
	v_mfma_f32_16x16x32_bf16 v[38:41], v[162:165], v[186:189], v[38:41]
	v_mfma_f32_16x16x32_bf16 v[34:37], v[170:173], v[186:189], v[34:37]
	v_mfma_f32_16x16x32_bf16 v[22:25], v[162:165], v[194:197], v[22:25]
	v_mfma_f32_16x16x32_bf16 v[18:21], v[170:173], v[194:197], v[18:21]
	v_mfma_f32_16x16x32_bf16 v[6:9], v[162:165], v[202:205], v[6:9]
	v_mfma_f32_16x16x32_bf16 v[2:5], v[170:173], v[202:205], v[2:5]
	v_mfma_f32_16x16x32_bf16 v[54:57], v[166:169], v[182:185], v[54:57]
	v_mfma_f32_16x16x32_bf16 v[50:53], v[174:177], v[182:185], v[50:53]
	v_mfma_f32_16x16x32_bf16 v[38:41], v[166:169], v[190:193], v[38:41]
	v_mfma_f32_16x16x32_bf16 v[34:37], v[174:177], v[190:193], v[34:37]
	v_mfma_f32_16x16x32_bf16 v[22:25], v[166:169], v[198:201], v[22:25]
	v_mfma_f32_16x16x32_bf16 v[18:21], v[174:177], v[198:201], v[18:21]
	v_mfma_f32_16x16x32_bf16 v[6:9], v[166:169], v[206:209], v[6:9]
	v_mfma_f32_16x16x32_bf16 v[2:5], v[174:177], v[206:209], v[2:5]
	s_barrier
	ds_read_b128 v[138:141], v147
	ds_read_b128 v[150:153], v147 offset:1024
	ds_read_b128 v[154:157], v147 offset:2048
	ds_read_b128 v[158:161], v147 offset:3072
	ds_read_b128 v[162:165], v148
	ds_read_b128 v[166:169], v148 offset:1024
	ds_read_b128 v[170:173], v148 offset:2048
	ds_read_b128 v[174:177], v148 offset:3072
	s_add_u32 s22, s28, 0x80000
	s_addc_u32 s23, s29, 0
	s_mov_b32 m0, s35
	v_lshl_add_u64 v[218:219], s[22:23], 0, v[132:133]
	ds_read_b128 v[178:181], v146 offset:32768
	ds_read_b128 v[182:185], v146 offset:33792
	ds_read_b128 v[186:189], v146 offset:34816
	ds_read_b128 v[190:193], v146 offset:35840
	ds_read_b128 v[194:197], v146 offset:36864
	ds_read_b128 v[198:201], v146 offset:37888
	ds_read_b128 v[202:205], v146 offset:38912
	ds_read_b128 v[206:209], v146 offset:39936
	global_load_lds_dwordx4 v[218:219], off
	v_lshl_add_u64 v[218:219], s[22:23], 0, v[130:131]
	s_mov_b32 m0, s36
	s_nop 0
	global_load_lds_dwordx4 v[218:219], off
	s_waitcnt vmcnt(8)
	s_waitcnt lgkmcnt(0)
	s_barrier
	s_waitcnt lgkmcnt(0)
	v_mfma_f32_16x16x32_bf16 v[126:129], v[138:141], v[178:181], v[126:129]
	v_mfma_f32_16x16x32_bf16 v[122:125], v[154:157], v[178:181], v[122:125]
	v_mfma_f32_16x16x32_bf16 v[110:113], v[138:141], v[186:189], v[110:113]
	v_mfma_f32_16x16x32_bf16 v[106:109], v[154:157], v[186:189], v[106:109]
	v_mfma_f32_16x16x32_bf16 v[94:97], v[138:141], v[194:197], v[94:97]
	v_mfma_f32_16x16x32_bf16 v[90:93], v[154:157], v[194:197], v[90:93]
	v_mfma_f32_16x16x32_bf16 v[78:81], v[138:141], v[202:205], v[78:81]
	v_mfma_f32_16x16x32_bf16 v[74:77], v[154:157], v[202:205], v[74:77]
	v_mfma_f32_16x16x32_bf16 v[126:129], v[150:153], v[182:185], v[126:129]
	v_mfma_f32_16x16x32_bf16 v[122:125], v[158:161], v[182:185], v[122:125]
	v_mfma_f32_16x16x32_bf16 v[110:113], v[150:153], v[190:193], v[110:113]
	v_mfma_f32_16x16x32_bf16 v[106:109], v[158:161], v[190:193], v[106:109]
	v_mfma_f32_16x16x32_bf16 v[94:97], v[150:153], v[198:201], v[94:97]
	v_mfma_f32_16x16x32_bf16 v[90:93], v[158:161], v[198:201], v[90:93]
	v_mfma_f32_16x16x32_bf16 v[78:81], v[150:153], v[206:209], v[78:81]
	v_mfma_f32_16x16x32_bf16 v[74:77], v[158:161], v[206:209], v[74:77]
	v_mfma_f32_16x16x32_bf16 v[118:121], v[162:165], v[178:181], v[118:121]
	v_mfma_f32_16x16x32_bf16 v[114:117], v[170:173], v[178:181], v[114:117]
	v_mfma_f32_16x16x32_bf16 v[102:105], v[162:165], v[186:189], v[102:105]
	v_mfma_f32_16x16x32_bf16 v[98:101], v[170:173], v[186:189], v[98:101]
	v_mfma_f32_16x16x32_bf16 v[86:89], v[162:165], v[194:197], v[86:89]
	v_mfma_f32_16x16x32_bf16 v[82:85], v[170:173], v[194:197], v[82:85]
	v_mfma_f32_16x16x32_bf16 v[70:73], v[162:165], v[202:205], v[70:73]
	v_mfma_f32_16x16x32_bf16 v[66:69], v[170:173], v[202:205], v[66:69]
	v_mfma_f32_16x16x32_bf16 v[118:121], v[166:169], v[182:185], v[118:121]
	v_mfma_f32_16x16x32_bf16 v[114:117], v[174:177], v[182:185], v[114:117]
	v_mfma_f32_16x16x32_bf16 v[102:105], v[166:169], v[190:193], v[102:105]
	v_mfma_f32_16x16x32_bf16 v[98:101], v[174:177], v[190:193], v[98:101]
	v_mfma_f32_16x16x32_bf16 v[86:89], v[166:169], v[198:201], v[86:89]
	v_mfma_f32_16x16x32_bf16 v[82:85], v[174:177], v[198:201], v[82:85]
	v_mfma_f32_16x16x32_bf16 v[70:73], v[166:169], v[206:209], v[70:73]
	v_mfma_f32_16x16x32_bf16 v[66:69], v[174:177], v[206:209], v[66:69]
	s_barrier
	s_mov_b32 m0, s48
	v_lshl_add_u64 v[210:211], v[210:211], 0, s[14:15]
	s_add_u32 s22, s26, 0x80080
	ds_read_b128 v[178:181], v146 offset:49152
	ds_read_b128 v[182:185], v146 offset:50176
	ds_read_b128 v[186:189], v146 offset:51200
	ds_read_b128 v[190:193], v146 offset:52224
	ds_read_b128 v[194:197], v146 offset:53248
	ds_read_b128 v[198:201], v146 offset:54272
	ds_read_b128 v[202:205], v146 offset:55296
	ds_read_b128 v[206:209], v146 offset:56320
	global_load_lds_dwordx4 v[210:211], off
	v_lshl_add_u64 v[210:211], v[212:213], 0, s[14:15]
	s_mov_b32 m0, s49
	s_addc_u32 s23, s27, 0
	global_load_lds_dwordx4 v[210:211], off
	v_lshl_add_u64 v[210:211], s[22:23], 0, v[132:133]
	s_mov_b32 m0, s50
	s_nop 0
	global_load_lds_dwordx4 v[210:211], off
	v_lshl_add_u64 v[210:211], s[22:23], 0, v[130:131]
	s_mov_b32 m0, s51
	s_nop 0
	global_load_lds_dwordx4 v[210:211], off
	v_lshl_add_u64 v[210:211], v[214:215], 0, s[14:15]
	s_mov_b32 m0, s39
	s_nop 0
	global_load_lds_dwordx4 v[210:211], off
	v_lshl_add_u64 v[210:211], v[216:217], 0, s[14:15]
	s_mov_b32 m0, s40
	s_nop 0
	global_load_lds_dwordx4 v[210:211], off
	s_waitcnt vmcnt(8)
	s_waitcnt lgkmcnt(0)
	s_barrier
	s_waitcnt lgkmcnt(0)
	v_mfma_f32_16x16x32_bf16 v[62:65], v[138:141], v[178:181], v[62:65]
	v_mfma_f32_16x16x32_bf16 v[58:61], v[154:157], v[178:181], v[58:61]
	v_mfma_f32_16x16x32_bf16 v[46:49], v[138:141], v[186:189], v[46:49]
	v_mfma_f32_16x16x32_bf16 v[42:45], v[154:157], v[186:189], v[42:45]
	v_mfma_f32_16x16x32_bf16 v[30:33], v[138:141], v[194:197], v[30:33]
	v_mfma_f32_16x16x32_bf16 v[26:29], v[154:157], v[194:197], v[26:29]
	v_mfma_f32_16x16x32_bf16 v[14:17], v[138:141], v[202:205], v[14:17]
	v_mfma_f32_16x16x32_bf16 v[10:13], v[154:157], v[202:205], v[10:13]
	v_mfma_f32_16x16x32_bf16 v[62:65], v[150:153], v[182:185], v[62:65]
	v_mfma_f32_16x16x32_bf16 v[58:61], v[158:161], v[182:185], v[58:61]
	v_mfma_f32_16x16x32_bf16 v[46:49], v[150:153], v[190:193], v[46:49]
	v_mfma_f32_16x16x32_bf16 v[42:45], v[158:161], v[190:193], v[42:45]
	v_mfma_f32_16x16x32_bf16 v[30:33], v[150:153], v[198:201], v[30:33]
	v_mfma_f32_16x16x32_bf16 v[26:29], v[158:161], v[198:201], v[26:29]
	v_mfma_f32_16x16x32_bf16 v[14:17], v[150:153], v[206:209], v[14:17]
	v_mfma_f32_16x16x32_bf16 v[10:13], v[158:161], v[206:209], v[10:13]
	v_mfma_f32_16x16x32_bf16 v[54:57], v[162:165], v[178:181], v[54:57]
	v_mfma_f32_16x16x32_bf16 v[50:53], v[170:173], v[178:181], v[50:53]
	v_mfma_f32_16x16x32_bf16 v[38:41], v[162:165], v[186:189], v[38:41]
	v_mfma_f32_16x16x32_bf16 v[34:37], v[170:173], v[186:189], v[34:37]
	v_mfma_f32_16x16x32_bf16 v[22:25], v[162:165], v[194:197], v[22:25]
	v_mfma_f32_16x16x32_bf16 v[18:21], v[170:173], v[194:197], v[18:21]
	v_mfma_f32_16x16x32_bf16 v[6:9], v[162:165], v[202:205], v[6:9]
	v_mfma_f32_16x16x32_bf16 v[2:5], v[170:173], v[202:205], v[2:5]
	v_mfma_f32_16x16x32_bf16 v[54:57], v[166:169], v[182:185], v[54:57]
	v_mfma_f32_16x16x32_bf16 v[50:53], v[174:177], v[182:185], v[50:53]
	v_mfma_f32_16x16x32_bf16 v[38:41], v[166:169], v[190:193], v[38:41]
	v_mfma_f32_16x16x32_bf16 v[34:37], v[174:177], v[190:193], v[34:37]
	v_mfma_f32_16x16x32_bf16 v[22:25], v[166:169], v[198:201], v[22:25]
	v_mfma_f32_16x16x32_bf16 v[18:21], v[174:177], v[198:201], v[18:21]
	v_mfma_f32_16x16x32_bf16 v[6:9], v[166:169], v[206:209], v[6:9]
	v_mfma_f32_16x16x32_bf16 v[2:5], v[174:177], v[206:209], v[2:5]
	s_barrier
	s_add_i32 s56, s56, 2
	s_cmp_gt_u32 s56, 29
	s_mov_b64 s[22:23], s[24:25]
	s_cbranch_scc0 .LBB0_2412
	s_and_b64 vcc, exec, s[16:17]
	s_cbranch_vccz .LBB0_2415
	s_barrier

.LBB0_2492:
	ds_read_b128 v[130:133], v159
	ds_read_b128 v[134:137], v159 offset:1024
	ds_read_b128 v[164:167], v159 offset:2048
	ds_read_b128 v[168:171], v159 offset:3072
	ds_read_b128 v[172:175], v161
	ds_read_b128 v[182:185], v161 offset:1024
	ds_read_b128 v[186:189], v161 offset:2048
	ds_read_b128 v[190:193], v161 offset:3072
	s_add_u32 s22, s0, 0xfff80080
	s_addc_u32 s23, s1, -1
	s_cmp_eq_u32 s48, 28
	s_cselect_b32 s25, s9, s23
	s_cselect_b32 s24, s8, s22
	s_cselect_b32 s23, s44, s47
	s_cselect_b32 s22, s45, s46
	v_lshl_add_u64 v[154:155], s[0:1], 0, v[146:147]
	s_add_i32 m0, s28, 0xc000
	ds_read_b128 v[194:197], v163
	ds_read_b128 v[198:201], v163 offset:1024
	ds_read_b128 v[202:205], v163 offset:2048
	ds_read_b128 v[206:209], v163 offset:3072
	ds_read_b128 v[210:213], v163 offset:4096
	ds_read_b128 v[214:217], v163 offset:5120
	ds_read_b128 v[218:221], v163 offset:6144
	ds_read_b128 v[222:225], v163 offset:7168
	global_load_lds_dwordx4 v[154:155], off
	v_lshl_add_u64 v[154:155], s[0:1], 0, v[148:149]
	s_add_i32 m0, s28, 0xe000
	s_nop 0
	global_load_lds_dwordx4 v[154:155], off
	s_waitcnt vmcnt(8)
	s_waitcnt lgkmcnt(0)
	s_barrier
	s_waitcnt lgkmcnt(0)
	v_mfma_f32_16x16x32_bf16 v[126:129], v[130:133], v[194:197], v[126:129]
	v_mfma_f32_16x16x32_bf16 v[122:125], v[164:167], v[194:197], v[122:125]
	v_mfma_f32_16x16x32_bf16 v[118:121], v[130:133], v[202:205], v[118:121]
	v_mfma_f32_16x16x32_bf16 v[110:113], v[164:167], v[202:205], v[110:113]
	v_mfma_f32_16x16x32_bf16 v[102:105], v[130:133], v[210:213], v[102:105]
	v_mfma_f32_16x16x32_bf16 v[94:97], v[164:167], v[210:213], v[94:97]
	v_mfma_f32_16x16x32_bf16 v[86:89], v[130:133], v[218:221], v[86:89]
	v_mfma_f32_16x16x32_bf16 v[78:81], v[164:167], v[218:221], v[78:81]
	v_mfma_f32_16x16x32_bf16 v[126:129], v[134:137], v[198:201], v[126:129]
	v_mfma_f32_16x16x32_bf16 v[122:125], v[168:171], v[198:201], v[122:125]
	v_mfma_f32_16x16x32_bf16 v[118:121], v[134:137], v[206:209], v[118:121]
	v_mfma_f32_16x16x32_bf16 v[110:113], v[168:171], v[206:209], v[110:113]
	v_mfma_f32_16x16x32_bf16 v[102:105], v[134:137], v[214:217], v[102:105]
	v_mfma_f32_16x16x32_bf16 v[94:97], v[168:171], v[214:217], v[94:97]
	v_mfma_f32_16x16x32_bf16 v[86:89], v[134:137], v[222:225], v[86:89]
	v_mfma_f32_16x16x32_bf16 v[78:81], v[168:171], v[222:225], v[78:81]
	v_mfma_f32_16x16x32_bf16 v[114:117], v[172:175], v[194:197], v[114:117]
	v_mfma_f32_16x16x32_bf16 v[106:109], v[186:189], v[194:197], v[106:109]
	v_mfma_f32_16x16x32_bf16 v[98:101], v[172:175], v[202:205], v[98:101]
	v_mfma_f32_16x16x32_bf16 v[90:93], v[186:189], v[202:205], v[90:93]
	v_mfma_f32_16x16x32_bf16 v[82:85], v[172:175], v[210:213], v[82:85]
	v_mfma_f32_16x16x32_bf16 v[74:77], v[186:189], v[210:213], v[74:77]
	v_mfma_f32_16x16x32_bf16 v[70:73], v[172:175], v[218:221], v[70:73]
	v_mfma_f32_16x16x32_bf16 v[66:69], v[186:189], v[218:221], v[66:69]
	v_mfma_f32_16x16x32_bf16 v[114:117], v[182:185], v[198:201], v[114:117]
	v_mfma_f32_16x16x32_bf16 v[106:109], v[190:193], v[198:201], v[106:109]
	v_mfma_f32_16x16x32_bf16 v[98:101], v[182:185], v[206:209], v[98:101]
	v_mfma_f32_16x16x32_bf16 v[90:93], v[190:193], v[206:209], v[90:93]
	v_mfma_f32_16x16x32_bf16 v[82:85], v[182:185], v[214:217], v[82:85]
	v_mfma_f32_16x16x32_bf16 v[74:77], v[190:193], v[214:217], v[74:77]
	v_mfma_f32_16x16x32_bf16 v[70:73], v[182:185], v[222:225], v[70:73]
	v_mfma_f32_16x16x32_bf16 v[66:69], v[190:193], v[222:225], v[66:69]
	s_barrier
	s_add_i32 s49, s64, s27
	v_lshl_add_u64 v[154:155], s[22:23], 0, v[142:143]
	s_mov_b32 m0, s49
	ds_read_b128 v[194:197], v163 offset:16384
	ds_read_b128 v[198:201], v163 offset:17408
	ds_read_b128 v[202:205], v163 offset:18432
	ds_read_b128 v[206:209], v163 offset:19456
	ds_read_b128 v[210:213], v163 offset:20480
	ds_read_b128 v[214:217], v163 offset:21504
	ds_read_b128 v[218:221], v163 offset:22528
	ds_read_b128 v[222:225], v163 offset:23552
	global_load_lds_dwordx4 v[154:155], off
	s_add_i32 m0, s49, 0x2000
	s_add_u32 s50, s22, 0x80000
	v_lshl_add_u64 v[176:177], s[22:23], 0, v[138:139]
	s_addc_u32 s51, s23, 0
	s_add_i32 s49, s65, s27
	global_load_lds_dwordx4 v[176:177], off
	v_lshl_add_u64 v[226:227], s[50:51], 0, v[142:143]
	s_mov_b32 m0, s49
	v_lshl_add_u64 v[228:229], s[24:25], 0, v[140:141]
	global_load_lds_dwordx4 v[226:227], off
	v_lshl_add_u64 v[226:227], s[50:51], 0, v[138:139]
	s_add_i32 m0, s49, 0x2000
	s_nop 0
	global_load_lds_dwordx4 v[226:227], off
	v_lshl_add_u64 v[226:227], s[24:25], 0, v[144:145]
	s_mov_b32 m0, s28
	s_nop 0
	global_load_lds_dwordx4 v[226:227], off
	s_mov_b32 m0, s29
	s_nop 0
	global_load_lds_dwordx4 v[228:229], off
	s_waitcnt vmcnt(8)
	s_waitcnt lgkmcnt(0)
	s_barrier
	s_waitcnt lgkmcnt(0)
	v_mfma_f32_16x16x32_bf16 v[62:65], v[130:133], v[194:197], v[62:65]
	v_mfma_f32_16x16x32_bf16 v[58:61], v[164:167], v[194:197], v[58:61]
	v_mfma_f32_16x16x32_bf16 v[54:57], v[130:133], v[202:205], v[54:57]
	v_mfma_f32_16x16x32_bf16 v[46:49], v[164:167], v[202:205], v[46:49]
	v_mfma_f32_16x16x32_bf16 v[38:41], v[130:133], v[210:213], v[38:41]
	v_mfma_f32_16x16x32_bf16 v[30:33], v[164:167], v[210:213], v[30:33]
	v_mfma_f32_16x16x32_bf16 v[22:25], v[130:133], v[218:221], v[22:25]
	v_mfma_f32_16x16x32_bf16 v[14:17], v[164:167], v[218:221], v[14:17]
	v_mfma_f32_16x16x32_bf16 v[62:65], v[134:137], v[198:201], v[62:65]
	v_mfma_f32_16x16x32_bf16 v[58:61], v[168:171], v[198:201], v[58:61]
	v_mfma_f32_16x16x32_bf16 v[54:57], v[134:137], v[206:209], v[54:57]
	v_mfma_f32_16x16x32_bf16 v[46:49], v[168:171], v[206:209], v[46:49]
	v_mfma_f32_16x16x32_bf16 v[38:41], v[134:137], v[214:217], v[38:41]
	v_mfma_f32_16x16x32_bf16 v[30:33], v[168:171], v[214:217], v[30:33]
	v_mfma_f32_16x16x32_bf16 v[22:25], v[134:137], v[222:225], v[22:25]
	v_mfma_f32_16x16x32_bf16 v[14:17], v[168:171], v[222:225], v[14:17]
	v_mfma_f32_16x16x32_bf16 v[50:53], v[172:175], v[194:197], v[50:53]
	v_mfma_f32_16x16x32_bf16 v[42:45], v[186:189], v[194:197], v[42:45]
	v_mfma_f32_16x16x32_bf16 v[34:37], v[172:175], v[202:205], v[34:37]
	v_mfma_f32_16x16x32_bf16 v[26:29], v[186:189], v[202:205], v[26:29]
	v_mfma_f32_16x16x32_bf16 v[18:21], v[172:175], v[210:213], v[18:21]
	v_mfma_f32_16x16x32_bf16 v[10:13], v[186:189], v[210:213], v[10:13]
	v_mfma_f32_16x16x32_bf16 v[6:9], v[172:175], v[218:221], v[6:9]
	v_mfma_f32_16x16x32_bf16 v[2:5], v[186:189], v[218:221], v[2:5]
	v_mfma_f32_16x16x32_bf16 v[50:53], v[182:185], v[198:201], v[50:53]
	v_mfma_f32_16x16x32_bf16 v[42:45], v[190:193], v[198:201], v[42:45]
	v_mfma_f32_16x16x32_bf16 v[34:37], v[182:185], v[206:209], v[34:37]
	v_mfma_f32_16x16x32_bf16 v[26:29], v[190:193], v[206:209], v[26:29]
	v_mfma_f32_16x16x32_bf16 v[18:21], v[182:185], v[214:217], v[18:21]
	v_mfma_f32_16x16x32_bf16 v[10:13], v[190:193], v[214:217], v[10:13]
	v_mfma_f32_16x16x32_bf16 v[6:9], v[182:185], v[222:225], v[6:9]
	v_mfma_f32_16x16x32_bf16 v[2:5], v[190:193], v[222:225], v[2:5]
	s_barrier
	v_add_u32_e32 v150, s66, v157
	ds_read_b128 v[130:133], v150
	ds_read_b128 v[134:137], v150 offset:1024
	ds_read_b128 v[164:167], v150 offset:2048
	ds_read_b128 v[168:171], v150 offset:3072
	v_add_u32_e32 v150, s67, v157
	ds_read_b128 v[172:175], v150
	ds_read_b128 v[182:185], v150 offset:1024
	ds_read_b128 v[186:189], v150 offset:2048
	ds_read_b128 v[190:193], v150 offset:3072
	s_add_u32 s24, s24, 0x80000
	s_addc_u32 s25, s25, 0
	s_mov_b32 m0, s30
	v_lshl_add_u64 v[230:231], s[24:25], 0, v[144:145]
	ds_read_b128 v[194:197], v163 offset:32768
	ds_read_b128 v[198:201], v163 offset:33792
	ds_read_b128 v[202:205], v163 offset:34816
	ds_read_b128 v[206:209], v163 offset:35840
	ds_read_b128 v[210:213], v163 offset:36864
	ds_read_b128 v[214:217], v163 offset:37888
	ds_read_b128 v[218:221], v163 offset:38912
	ds_read_b128 v[222:225], v163 offset:39936
	global_load_lds_dwordx4 v[230:231], off
	v_lshl_add_u64 v[230:231], s[24:25], 0, v[140:141]
	s_mov_b32 m0, s31
	s_nop 0
	global_load_lds_dwordx4 v[230:231], off
	s_waitcnt vmcnt(8)
	s_waitcnt lgkmcnt(0)
	s_barrier
	s_waitcnt lgkmcnt(0)
	v_mfma_f32_16x16x32_bf16 v[126:129], v[130:133], v[194:197], v[126:129]
	v_mfma_f32_16x16x32_bf16 v[122:125], v[164:167], v[194:197], v[122:125]
	v_mfma_f32_16x16x32_bf16 v[118:121], v[130:133], v[202:205], v[118:121]
	v_mfma_f32_16x16x32_bf16 v[110:113], v[164:167], v[202:205], v[110:113]
	v_mfma_f32_16x16x32_bf16 v[102:105], v[130:133], v[210:213], v[102:105]
	v_mfma_f32_16x16x32_bf16 v[94:97], v[164:167], v[210:213], v[94:97]
	v_mfma_f32_16x16x32_bf16 v[86:89], v[130:133], v[218:221], v[86:89]
	v_mfma_f32_16x16x32_bf16 v[78:81], v[164:167], v[218:221], v[78:81]
	v_mfma_f32_16x16x32_bf16 v[126:129], v[134:137], v[198:201], v[126:129]
	v_mfma_f32_16x16x32_bf16 v[122:125], v[168:171], v[198:201], v[122:125]
	v_mfma_f32_16x16x32_bf16 v[118:121], v[134:137], v[206:209], v[118:121]
	v_mfma_f32_16x16x32_bf16 v[110:113], v[168:171], v[206:209], v[110:113]
	v_mfma_f32_16x16x32_bf16 v[102:105], v[134:137], v[214:217], v[102:105]
	v_mfma_f32_16x16x32_bf16 v[94:97], v[168:171], v[214:217], v[94:97]
	v_mfma_f32_16x16x32_bf16 v[86:89], v[134:137], v[222:225], v[86:89]
	v_mfma_f32_16x16x32_bf16 v[78:81], v[168:171], v[222:225], v[78:81]
	v_mfma_f32_16x16x32_bf16 v[114:117], v[172:175], v[194:197], v[114:117]
	v_mfma_f32_16x16x32_bf16 v[106:109], v[186:189], v[194:197], v[106:109]
	v_mfma_f32_16x16x32_bf16 v[98:101], v[172:175], v[202:205], v[98:101]
	v_mfma_f32_16x16x32_bf16 v[90:93], v[186:189], v[202:205], v[90:93]
	v_mfma_f32_16x16x32_bf16 v[82:85], v[172:175], v[210:213], v[82:85]
	v_mfma_f32_16x16x32_bf16 v[74:77], v[186:189], v[210:213], v[74:77]
	v_mfma_f32_16x16x32_bf16 v[70:73], v[172:175], v[218:221], v[70:73]
	v_mfma_f32_16x16x32_bf16 v[66:69], v[186:189], v[218:221], v[66:69]
	v_mfma_f32_16x16x32_bf16 v[114:117], v[182:185], v[198:201], v[114:117]
	v_mfma_f32_16x16x32_bf16 v[106:109], v[190:193], v[198:201], v[106:109]
	v_mfma_f32_16x16x32_bf16 v[98:101], v[182:185], v[206:209], v[98:101]
	v_mfma_f32_16x16x32_bf16 v[90:93], v[190:193], v[206:209], v[90:93]
	v_mfma_f32_16x16x32_bf16 v[82:85], v[182:185], v[214:217], v[82:85]
	v_mfma_f32_16x16x32_bf16 v[74:77], v[190:193], v[214:217], v[74:77]
	v_mfma_f32_16x16x32_bf16 v[70:73], v[182:185], v[222:225], v[70:73]
	v_mfma_f32_16x16x32_bf16 v[66:69], v[190:193], v[222:225], v[66:69]
	s_barrier
	s_add_i32 s24, s66, s27
	v_lshl_add_u64 v[154:155], v[154:155], 0, s[12:13]
	s_mov_b32 m0, s24
	ds_read_b128 v[194:197], v163 offset:49152
	ds_read_b128 v[198:201], v163 offset:50176
	ds_read_b128 v[202:205], v163 offset:51200
	ds_read_b128 v[206:209], v163 offset:52224
	ds_read_b128 v[210:213], v163 offset:53248
	ds_read_b128 v[214:217], v163 offset:54272
	ds_read_b128 v[218:221], v163 offset:55296
	ds_read_b128 v[222:225], v163 offset:56320
	global_load_lds_dwordx4 v[154:155], off
	s_add_i32 m0, s24, 0x2000
	s_add_u32 s22, s22, 0x80080
	v_lshl_add_u64 v[154:155], v[176:177], 0, s[12:13]
	s_addc_u32 s23, s23, 0
	s_add_i32 s24, s67, s27
	global_load_lds_dwordx4 v[154:155], off
	v_lshl_add_u64 v[154:155], s[22:23], 0, v[142:143]
	s_mov_b32 m0, s24
	s_nop 0
	global_load_lds_dwordx4 v[154:155], off
	v_lshl_add_u64 v[154:155], s[22:23], 0, v[138:139]
	s_add_i32 m0, s24, 0x2000
	s_nop 0
	global_load_lds_dwordx4 v[154:155], off
	v_lshl_add_u64 v[154:155], v[226:227], 0, s[12:13]
	s_mov_b32 m0, s35
	s_nop 0
	global_load_lds_dwordx4 v[154:155], off
	v_lshl_add_u64 v[154:155], v[228:229], 0, s[12:13]
	s_mov_b32 m0, s36
	s_nop 0
	global_load_lds_dwordx4 v[154:155], off
	s_waitcnt vmcnt(8)
	s_waitcnt lgkmcnt(0)
	s_barrier
	s_waitcnt lgkmcnt(0)
	v_mfma_f32_16x16x32_bf16 v[62:65], v[130:133], v[194:197], v[62:65]
	v_mfma_f32_16x16x32_bf16 v[58:61], v[164:167], v[194:197], v[58:61]
	v_mfma_f32_16x16x32_bf16 v[54:57], v[130:133], v[202:205], v[54:57]
	v_mfma_f32_16x16x32_bf16 v[46:49], v[164:167], v[202:205], v[46:49]
	v_mfma_f32_16x16x32_bf16 v[38:41], v[130:133], v[210:213], v[38:41]
	v_mfma_f32_16x16x32_bf16 v[30:33], v[164:167], v[210:213], v[30:33]
	v_mfma_f32_16x16x32_bf16 v[22:25], v[130:133], v[218:221], v[22:25]
	v_mfma_f32_16x16x32_bf16 v[14:17], v[164:167], v[218:221], v[14:17]
	v_mfma_f32_16x16x32_bf16 v[62:65], v[134:137], v[198:201], v[62:65]
	v_mfma_f32_16x16x32_bf16 v[58:61], v[168:171], v[198:201], v[58:61]
	v_mfma_f32_16x16x32_bf16 v[54:57], v[134:137], v[206:209], v[54:57]
	v_mfma_f32_16x16x32_bf16 v[46:49], v[168:171], v[206:209], v[46:49]
	v_mfma_f32_16x16x32_bf16 v[38:41], v[134:137], v[214:217], v[38:41]
	v_mfma_f32_16x16x32_bf16 v[30:33], v[168:171], v[214:217], v[30:33]
	v_mfma_f32_16x16x32_bf16 v[22:25], v[134:137], v[222:225], v[22:25]
	v_mfma_f32_16x16x32_bf16 v[14:17], v[168:171], v[222:225], v[14:17]
	v_mfma_f32_16x16x32_bf16 v[50:53], v[172:175], v[194:197], v[50:53]
	v_mfma_f32_16x16x32_bf16 v[42:45], v[186:189], v[194:197], v[42:45]
	v_mfma_f32_16x16x32_bf16 v[34:37], v[172:175], v[202:205], v[34:37]
	v_mfma_f32_16x16x32_bf16 v[26:29], v[186:189], v[202:205], v[26:29]
	v_mfma_f32_16x16x32_bf16 v[18:21], v[172:175], v[210:213], v[18:21]
	v_mfma_f32_16x16x32_bf16 v[10:13], v[186:189], v[210:213], v[10:13]
	v_mfma_f32_16x16x32_bf16 v[6:9], v[172:175], v[218:221], v[6:9]
	v_mfma_f32_16x16x32_bf16 v[2:5], v[186:189], v[218:221], v[2:5]
	v_mfma_f32_16x16x32_bf16 v[50:53], v[182:185], v[198:201], v[50:53]
	v_mfma_f32_16x16x32_bf16 v[42:45], v[190:193], v[198:201], v[42:45]
	v_mfma_f32_16x16x32_bf16 v[34:37], v[182:185], v[206:209], v[34:37]
	v_mfma_f32_16x16x32_bf16 v[26:29], v[190:193], v[206:209], v[26:29]
	v_mfma_f32_16x16x32_bf16 v[18:21], v[182:185], v[214:217], v[18:21]
	v_mfma_f32_16x16x32_bf16 v[10:13], v[190:193], v[214:217], v[10:13]
	v_mfma_f32_16x16x32_bf16 v[6:9], v[182:185], v[222:225], v[6:9]
	v_mfma_f32_16x16x32_bf16 v[2:5], v[190:193], v[222:225], v[2:5]
	s_barrier
	s_add_i32 s48, s48, 2
	s_add_u32 s0, s0, 0x100
	s_addc_u32 s1, s1, 0
	s_add_u32 s46, s46, 0x100
	s_addc_u32 s47, s47, 0
	s_cmp_gt_u32 s48, 29
	s_cbranch_scc0 .LBB0_2492
	s_and_b64 vcc, exec, s[14:15]
	s_cbranch_vccz .LBB0_2495
	s_barrier

.LBB0_2644:
	ds_read_b128 v[138:141], v144
	ds_read_b128 v[150:153], v144 offset:1024
	ds_read_b128 v[154:157], v144 offset:2048
	ds_read_b128 v[158:161], v144 offset:3072
	ds_read_b128 v[162:165], v145
	ds_read_b128 v[166:169], v145 offset:1024
	ds_read_b128 v[170:173], v145 offset:2048
	ds_read_b128 v[174:177], v145 offset:3072
	s_add_u32 s20, s18, 0x100
	s_addc_u32 s21, s19, 0
	s_add_u32 s22, s4, s18
	s_addc_u32 s23, s52, s19
	s_cmpk_eq_i32 s53, 0x54
	s_cselect_b32 s24, 0, s20
	s_cselect_b32 s25, 0, s21
	s_cselect_b32 s22, s14, s22
	s_cselect_b32 s23, s15, s23
	s_add_u32 s24, s0, s24
	s_addc_u32 s25, s1, s25
	s_mov_b32 m0, s39
	v_lshl_add_u64 v[214:215], v[134:135], 0, s[18:19]
	ds_read_b128 v[182:185], v146
	ds_read_b128 v[186:189], v146 offset:1024
	ds_read_b128 v[190:193], v146 offset:2048
	ds_read_b128 v[194:197], v146 offset:3072
	ds_read_b128 v[198:201], v146 offset:4096
	ds_read_b128 v[202:205], v146 offset:5120
	ds_read_b128 v[206:209], v146 offset:6144
	ds_read_b128 v[210:213], v146 offset:7168
	global_load_lds_dwordx4 v[214:215], off
	v_lshl_add_u64 v[214:215], v[136:137], 0, s[18:19]
	s_mov_b32 m0, s41
	s_nop 0
	global_load_lds_dwordx4 v[214:215], off
	s_waitcnt vmcnt(8)
	s_waitcnt lgkmcnt(0)
	s_barrier
	s_waitcnt lgkmcnt(0)
	v_mfma_f32_16x16x32_bf16 v[126:129], v[138:141], v[182:185], v[126:129]
	v_mfma_f32_16x16x32_bf16 v[122:125], v[154:157], v[182:185], v[122:125]
	v_mfma_f32_16x16x32_bf16 v[110:113], v[138:141], v[190:193], v[110:113]
	v_mfma_f32_16x16x32_bf16 v[106:109], v[154:157], v[190:193], v[106:109]
	v_mfma_f32_16x16x32_bf16 v[94:97], v[138:141], v[198:201], v[94:97]
	v_mfma_f32_16x16x32_bf16 v[90:93], v[154:157], v[198:201], v[90:93]
	v_mfma_f32_16x16x32_bf16 v[78:81], v[138:141], v[206:209], v[78:81]
	v_mfma_f32_16x16x32_bf16 v[74:77], v[154:157], v[206:209], v[74:77]
	v_mfma_f32_16x16x32_bf16 v[126:129], v[150:153], v[186:189], v[126:129]
	v_mfma_f32_16x16x32_bf16 v[122:125], v[158:161], v[186:189], v[122:125]
	v_mfma_f32_16x16x32_bf16 v[110:113], v[150:153], v[194:197], v[110:113]
	v_mfma_f32_16x16x32_bf16 v[106:109], v[158:161], v[194:197], v[106:109]
	v_mfma_f32_16x16x32_bf16 v[94:97], v[150:153], v[202:205], v[94:97]
	v_mfma_f32_16x16x32_bf16 v[90:93], v[158:161], v[202:205], v[90:93]
	v_mfma_f32_16x16x32_bf16 v[78:81], v[150:153], v[210:213], v[78:81]
	v_mfma_f32_16x16x32_bf16 v[74:77], v[158:161], v[210:213], v[74:77]
	v_mfma_f32_16x16x32_bf16 v[118:121], v[162:165], v[182:185], v[118:121]
	v_mfma_f32_16x16x32_bf16 v[114:117], v[170:173], v[182:185], v[114:117]
	v_mfma_f32_16x16x32_bf16 v[102:105], v[162:165], v[190:193], v[102:105]
	v_mfma_f32_16x16x32_bf16 v[98:101], v[170:173], v[190:193], v[98:101]
	v_mfma_f32_16x16x32_bf16 v[86:89], v[162:165], v[198:201], v[86:89]
	v_mfma_f32_16x16x32_bf16 v[82:85], v[170:173], v[198:201], v[82:85]
	v_mfma_f32_16x16x32_bf16 v[70:73], v[162:165], v[206:209], v[70:73]
	v_mfma_f32_16x16x32_bf16 v[66:69], v[170:173], v[206:209], v[66:69]
	v_mfma_f32_16x16x32_bf16 v[118:121], v[166:169], v[186:189], v[118:121]
	v_mfma_f32_16x16x32_bf16 v[114:117], v[174:177], v[186:189], v[114:117]
	v_mfma_f32_16x16x32_bf16 v[102:105], v[166:169], v[194:197], v[102:105]
	v_mfma_f32_16x16x32_bf16 v[98:101], v[174:177], v[194:197], v[98:101]
	v_mfma_f32_16x16x32_bf16 v[86:89], v[166:169], v[202:205], v[86:89]
	v_mfma_f32_16x16x32_bf16 v[82:85], v[174:177], v[202:205], v[82:85]
	v_mfma_f32_16x16x32_bf16 v[70:73], v[166:169], v[210:213], v[70:73]
	v_mfma_f32_16x16x32_bf16 v[66:69], v[174:177], v[210:213], v[66:69]
	s_barrier
	s_mov_b32 m0, s42
	v_lshl_add_u64 v[214:215], s[22:23], 0, v[132:133]
	s_add_u32 s18, s22, 0x160000
	ds_read_b128 v[182:185], v146 offset:16384
	ds_read_b128 v[186:189], v146 offset:17408
	ds_read_b128 v[190:193], v146 offset:18432
	ds_read_b128 v[194:197], v146 offset:19456
	ds_read_b128 v[198:201], v146 offset:20480
	ds_read_b128 v[202:205], v146 offset:21504
	ds_read_b128 v[206:209], v146 offset:22528
	ds_read_b128 v[210:213], v146 offset:23552
	global_load_lds_dwordx4 v[214:215], off
	v_lshl_add_u64 v[216:217], s[22:23], 0, v[130:131]
	s_mov_b32 m0, s43
	s_addc_u32 s19, s23, 0
	global_load_lds_dwordx4 v[216:217], off
	v_lshl_add_u64 v[218:219], s[18:19], 0, v[132:133]
	s_mov_b32 m0, s44
	v_lshl_add_u64 v[220:221], s[24:25], 0, v[130:131]
	global_load_lds_dwordx4 v[218:219], off
	v_lshl_add_u64 v[218:219], s[18:19], 0, v[130:131]
	s_mov_b32 m0, s45
	s_nop 0
	global_load_lds_dwordx4 v[218:219], off
	v_lshl_add_u64 v[218:219], s[24:25], 0, v[132:133]
	s_mov_b32 m0, s28
	s_nop 0
	global_load_lds_dwordx4 v[218:219], off
	s_mov_b32 m0, s29
	s_nop 0
	global_load_lds_dwordx4 v[220:221], off
	s_waitcnt vmcnt(8)
	s_waitcnt lgkmcnt(0)
	s_barrier
	s_waitcnt lgkmcnt(0)
	v_mfma_f32_16x16x32_bf16 v[62:65], v[138:141], v[182:185], v[62:65]
	v_mfma_f32_16x16x32_bf16 v[58:61], v[154:157], v[182:185], v[58:61]
	v_mfma_f32_16x16x32_bf16 v[46:49], v[138:141], v[190:193], v[46:49]
	v_mfma_f32_16x16x32_bf16 v[42:45], v[154:157], v[190:193], v[42:45]
	v_mfma_f32_16x16x32_bf16 v[30:33], v[138:141], v[198:201], v[30:33]
	v_mfma_f32_16x16x32_bf16 v[26:29], v[154:157], v[198:201], v[26:29]
	v_mfma_f32_16x16x32_bf16 v[14:17], v[138:141], v[206:209], v[14:17]
	v_mfma_f32_16x16x32_bf16 v[10:13], v[154:157], v[206:209], v[10:13]
	v_mfma_f32_16x16x32_bf16 v[62:65], v[150:153], v[186:189], v[62:65]
	v_mfma_f32_16x16x32_bf16 v[58:61], v[158:161], v[186:189], v[58:61]
	v_mfma_f32_16x16x32_bf16 v[46:49], v[150:153], v[194:197], v[46:49]
	v_mfma_f32_16x16x32_bf16 v[42:45], v[158:161], v[194:197], v[42:45]
	v_mfma_f32_16x16x32_bf16 v[30:33], v[150:153], v[202:205], v[30:33]
	v_mfma_f32_16x16x32_bf16 v[26:29], v[158:161], v[202:205], v[26:29]
	v_mfma_f32_16x16x32_bf16 v[14:17], v[150:153], v[210:213], v[14:17]
	v_mfma_f32_16x16x32_bf16 v[10:13], v[158:161], v[210:213], v[10:13]
	v_mfma_f32_16x16x32_bf16 v[54:57], v[162:165], v[182:185], v[54:57]
	v_mfma_f32_16x16x32_bf16 v[50:53], v[170:173], v[182:185], v[50:53]
	v_mfma_f32_16x16x32_bf16 v[38:41], v[162:165], v[190:193], v[38:41]
	v_mfma_f32_16x16x32_bf16 v[34:37], v[170:173], v[190:193], v[34:37]
	v_mfma_f32_16x16x32_bf16 v[22:25], v[162:165], v[198:201], v[22:25]
	v_mfma_f32_16x16x32_bf16 v[18:21], v[170:173], v[198:201], v[18:21]
	v_mfma_f32_16x16x32_bf16 v[6:9], v[162:165], v[206:209], v[6:9]
	v_mfma_f32_16x16x32_bf16 v[2:5], v[170:173], v[206:209], v[2:5]
	v_mfma_f32_16x16x32_bf16 v[54:57], v[166:169], v[186:189], v[54:57]
	v_mfma_f32_16x16x32_bf16 v[50:53], v[174:177], v[186:189], v[50:53]
	v_mfma_f32_16x16x32_bf16 v[38:41], v[166:169], v[194:197], v[38:41]
	v_mfma_f32_16x16x32_bf16 v[34:37], v[174:177], v[194:197], v[34:37]
	v_mfma_f32_16x16x32_bf16 v[22:25], v[166:169], v[202:205], v[22:25]
	v_mfma_f32_16x16x32_bf16 v[18:21], v[174:177], v[202:205], v[18:21]
	v_mfma_f32_16x16x32_bf16 v[6:9], v[166:169], v[210:213], v[6:9]
	v_mfma_f32_16x16x32_bf16 v[2:5], v[174:177], v[210:213], v[2:5]
	s_barrier
	ds_read_b128 v[138:141], v147
	ds_read_b128 v[150:153], v147 offset:1024
	ds_read_b128 v[154:157], v147 offset:2048
	ds_read_b128 v[158:161], v147 offset:3072
	ds_read_b128 v[162:165], v148
	ds_read_b128 v[166:169], v148 offset:1024
	ds_read_b128 v[170:173], v148 offset:2048
	ds_read_b128 v[174:177], v148 offset:3072
	s_add_u32 s18, s24, 0x160000
	s_addc_u32 s19, s25, 0
	s_mov_b32 m0, s30
	v_lshl_add_u64 v[222:223], s[18:19], 0, v[132:133]
	ds_read_b128 v[182:185], v146 offset:32768
	ds_read_b128 v[186:189], v146 offset:33792
	ds_read_b128 v[190:193], v146 offset:34816
	ds_read_b128 v[194:197], v146 offset:35840
	ds_read_b128 v[198:201], v146 offset:36864
	ds_read_b128 v[202:205], v146 offset:37888
	ds_read_b128 v[206:209], v146 offset:38912
	ds_read_b128 v[210:213], v146 offset:39936
	global_load_lds_dwordx4 v[222:223], off
	v_lshl_add_u64 v[222:223], s[18:19], 0, v[130:131]
	s_mov_b32 m0, s31
	s_nop 0
	global_load_lds_dwordx4 v[222:223], off
	s_waitcnt vmcnt(8)
	s_waitcnt lgkmcnt(0)
	s_barrier
	s_waitcnt lgkmcnt(0)
	v_mfma_f32_16x16x32_bf16 v[126:129], v[138:141], v[182:185], v[126:129]
	v_mfma_f32_16x16x32_bf16 v[122:125], v[154:157], v[182:185], v[122:125]
	v_mfma_f32_16x16x32_bf16 v[110:113], v[138:141], v[190:193], v[110:113]
	v_mfma_f32_16x16x32_bf16 v[106:109], v[154:157], v[190:193], v[106:109]
	v_mfma_f32_16x16x32_bf16 v[94:97], v[138:141], v[198:201], v[94:97]
	v_mfma_f32_16x16x32_bf16 v[90:93], v[154:157], v[198:201], v[90:93]
	v_mfma_f32_16x16x32_bf16 v[78:81], v[138:141], v[206:209], v[78:81]
	v_mfma_f32_16x16x32_bf16 v[74:77], v[154:157], v[206:209], v[74:77]
	v_mfma_f32_16x16x32_bf16 v[126:129], v[150:153], v[186:189], v[126:129]
	v_mfma_f32_16x16x32_bf16 v[122:125], v[158:161], v[186:189], v[122:125]
	v_mfma_f32_16x16x32_bf16 v[110:113], v[150:153], v[194:197], v[110:113]
	v_mfma_f32_16x16x32_bf16 v[106:109], v[158:161], v[194:197], v[106:109]
	v_mfma_f32_16x16x32_bf16 v[94:97], v[150:153], v[202:205], v[94:97]
	v_mfma_f32_16x16x32_bf16 v[90:93], v[158:161], v[202:205], v[90:93]
	v_mfma_f32_16x16x32_bf16 v[78:81], v[150:153], v[210:213], v[78:81]
	v_mfma_f32_16x16x32_bf16 v[74:77], v[158:161], v[210:213], v[74:77]
	v_mfma_f32_16x16x32_bf16 v[118:121], v[162:165], v[182:185], v[118:121]
	v_mfma_f32_16x16x32_bf16 v[114:117], v[170:173], v[182:185], v[114:117]
	v_mfma_f32_16x16x32_bf16 v[102:105], v[162:165], v[190:193], v[102:105]
	v_mfma_f32_16x16x32_bf16 v[98:101], v[170:173], v[190:193], v[98:101]
	v_mfma_f32_16x16x32_bf16 v[86:89], v[162:165], v[198:201], v[86:89]
	v_mfma_f32_16x16x32_bf16 v[82:85], v[170:173], v[198:201], v[82:85]
	v_mfma_f32_16x16x32_bf16 v[70:73], v[162:165], v[206:209], v[70:73]
	v_mfma_f32_16x16x32_bf16 v[66:69], v[170:173], v[206:209], v[66:69]
	v_mfma_f32_16x16x32_bf16 v[118:121], v[166:169], v[186:189], v[118:121]
	v_mfma_f32_16x16x32_bf16 v[114:117], v[174:177], v[186:189], v[114:117]
	v_mfma_f32_16x16x32_bf16 v[102:105], v[166:169], v[194:197], v[102:105]
	v_mfma_f32_16x16x32_bf16 v[98:101], v[174:177], v[194:197], v[98:101]
	v_mfma_f32_16x16x32_bf16 v[86:89], v[166:169], v[202:205], v[86:89]
	v_mfma_f32_16x16x32_bf16 v[82:85], v[174:177], v[202:205], v[82:85]
	v_mfma_f32_16x16x32_bf16 v[70:73], v[166:169], v[210:213], v[70:73]
	v_mfma_f32_16x16x32_bf16 v[66:69], v[174:177], v[210:213], v[66:69]
	s_barrier
	s_mov_b32 m0, s46
	v_lshl_add_u64 v[214:215], v[214:215], 0, s[10:11]
	s_add_u32 s18, s22, 0x160080
	ds_read_b128 v[182:185], v146 offset:49152
	ds_read_b128 v[186:189], v146 offset:50176
	ds_read_b128 v[190:193], v146 offset:51200
	ds_read_b128 v[194:197], v146 offset:52224
	ds_read_b128 v[198:201], v146 offset:53248
	ds_read_b128 v[202:205], v146 offset:54272
	ds_read_b128 v[206:209], v146 offset:55296
	ds_read_b128 v[210:213], v146 offset:56320
	global_load_lds_dwordx4 v[214:215], off
	v_lshl_add_u64 v[214:215], v[216:217], 0, s[10:11]
	s_mov_b32 m0, s47
	s_addc_u32 s19, s23, 0
	global_load_lds_dwordx4 v[214:215], off
	v_lshl_add_u64 v[214:215], s[18:19], 0, v[132:133]
	s_mov_b32 m0, s48
	s_nop 0
	global_load_lds_dwordx4 v[214:215], off
	v_lshl_add_u64 v[214:215], s[18:19], 0, v[130:131]
	s_mov_b32 m0, s49
	s_nop 0
	global_load_lds_dwordx4 v[214:215], off
	v_lshl_add_u64 v[214:215], v[218:219], 0, s[10:11]
	s_mov_b32 m0, s36
	s_nop 0
	global_load_lds_dwordx4 v[214:215], off
	v_lshl_add_u64 v[214:215], v[220:221], 0, s[10:11]
	s_mov_b32 m0, s37
	s_nop 0
	global_load_lds_dwordx4 v[214:215], off
	s_waitcnt vmcnt(8)
	s_waitcnt lgkmcnt(0)
	s_barrier
	s_waitcnt lgkmcnt(0)
	v_mfma_f32_16x16x32_bf16 v[62:65], v[138:141], v[182:185], v[62:65]
	v_mfma_f32_16x16x32_bf16 v[58:61], v[154:157], v[182:185], v[58:61]
	v_mfma_f32_16x16x32_bf16 v[46:49], v[138:141], v[190:193], v[46:49]
	v_mfma_f32_16x16x32_bf16 v[42:45], v[154:157], v[190:193], v[42:45]
	v_mfma_f32_16x16x32_bf16 v[30:33], v[138:141], v[198:201], v[30:33]
	v_mfma_f32_16x16x32_bf16 v[26:29], v[154:157], v[198:201], v[26:29]
	v_mfma_f32_16x16x32_bf16 v[14:17], v[138:141], v[206:209], v[14:17]
	v_mfma_f32_16x16x32_bf16 v[10:13], v[154:157], v[206:209], v[10:13]
	v_mfma_f32_16x16x32_bf16 v[62:65], v[150:153], v[186:189], v[62:65]
	v_mfma_f32_16x16x32_bf16 v[58:61], v[158:161], v[186:189], v[58:61]
	v_mfma_f32_16x16x32_bf16 v[46:49], v[150:153], v[194:197], v[46:49]
	v_mfma_f32_16x16x32_bf16 v[42:45], v[158:161], v[194:197], v[42:45]
	v_mfma_f32_16x16x32_bf16 v[30:33], v[150:153], v[202:205], v[30:33]
	v_mfma_f32_16x16x32_bf16 v[26:29], v[158:161], v[202:205], v[26:29]
	v_mfma_f32_16x16x32_bf16 v[14:17], v[150:153], v[210:213], v[14:17]
	v_mfma_f32_16x16x32_bf16 v[10:13], v[158:161], v[210:213], v[10:13]
	v_mfma_f32_16x16x32_bf16 v[54:57], v[162:165], v[182:185], v[54:57]
	v_mfma_f32_16x16x32_bf16 v[50:53], v[170:173], v[182:185], v[50:53]
	v_mfma_f32_16x16x32_bf16 v[38:41], v[162:165], v[190:193], v[38:41]
	v_mfma_f32_16x16x32_bf16 v[34:37], v[170:173], v[190:193], v[34:37]
	v_mfma_f32_16x16x32_bf16 v[22:25], v[162:165], v[198:201], v[22:25]
	v_mfma_f32_16x16x32_bf16 v[18:21], v[170:173], v[198:201], v[18:21]
	v_mfma_f32_16x16x32_bf16 v[6:9], v[162:165], v[206:209], v[6:9]
	v_mfma_f32_16x16x32_bf16 v[2:5], v[170:173], v[206:209], v[2:5]
	v_mfma_f32_16x16x32_bf16 v[54:57], v[166:169], v[186:189], v[54:57]
	v_mfma_f32_16x16x32_bf16 v[50:53], v[174:177], v[186:189], v[50:53]
	v_mfma_f32_16x16x32_bf16 v[38:41], v[166:169], v[194:197], v[38:41]
	v_mfma_f32_16x16x32_bf16 v[34:37], v[174:177], v[194:197], v[34:37]
	v_mfma_f32_16x16x32_bf16 v[22:25], v[166:169], v[202:205], v[22:25]
	v_mfma_f32_16x16x32_bf16 v[18:21], v[174:177], v[202:205], v[18:21]
	v_mfma_f32_16x16x32_bf16 v[6:9], v[166:169], v[210:213], v[6:9]
	v_mfma_f32_16x16x32_bf16 v[2:5], v[174:177], v[210:213], v[2:5]
	s_barrier
	s_add_i32 s53, s53, 2
	s_cmpk_gt_u32 s53, 0x55
	s_mov_b64 s[18:19], s[20:21]
	s_cbranch_scc0 .LBB0_2644
	s_and_b64 vcc, exec, s[12:13]
	s_cbranch_vccz .LBB0_2647
	s_barrier

.LBB0_3114:
	ds_read_b128 v[142:145], v148
	ds_read_b128 v[152:155], v148 offset:1024
	ds_read_b128 v[156:159], v148 offset:2048
	ds_read_b128 v[160:163], v148 offset:3072
	ds_read_b128 v[164:167], v149
	ds_read_b128 v[168:171], v149 offset:1024
	ds_read_b128 v[172:175], v149 offset:2048
	ds_read_b128 v[176:179], v149 offset:3072
	s_add_u32 s26, s24, 0x100
	s_addc_u32 s27, s25, 0
	s_cmp_eq_u32 s55, 28
	s_cselect_b32 s31, s19, s27
	s_cselect_b32 s30, s51, s26
	s_cselect_b32 s29, s17, s54
	s_cselect_b32 s28, s52, s53
	v_lshl_add_u64 v[212:213], s[24:25], 0, v[134:135]
	s_add_i32 m0, s5, 0xc000
	ds_read_b128 v[180:183], v150
	ds_read_b128 v[184:187], v150 offset:1024
	ds_read_b128 v[188:191], v150 offset:2048
	ds_read_b128 v[192:195], v150 offset:3072
	ds_read_b128 v[196:199], v150 offset:4096
	ds_read_b128 v[200:203], v150 offset:5120
	ds_read_b128 v[204:207], v150 offset:6144
	ds_read_b128 v[208:211], v150 offset:7168
	global_load_lds_dwordx4 v[212:213], off
	v_lshl_add_u64 v[212:213], s[24:25], 0, v[136:137]
	s_add_i32 m0, s5, 0xe000
	s_nop 0
	global_load_lds_dwordx4 v[212:213], off
	s_waitcnt vmcnt(8)
	s_waitcnt lgkmcnt(0)
	s_barrier
	s_waitcnt lgkmcnt(0)
	v_mfma_f32_16x16x32_bf16 v[126:129], v[142:145], v[180:183], v[126:129]
	v_mfma_f32_16x16x32_bf16 v[122:125], v[156:159], v[180:183], v[122:125]
	v_mfma_f32_16x16x32_bf16 v[110:113], v[142:145], v[188:191], v[110:113]
	v_mfma_f32_16x16x32_bf16 v[106:109], v[156:159], v[188:191], v[106:109]
	v_mfma_f32_16x16x32_bf16 v[94:97], v[142:145], v[196:199], v[94:97]
	v_mfma_f32_16x16x32_bf16 v[90:93], v[156:159], v[196:199], v[90:93]
	v_mfma_f32_16x16x32_bf16 v[78:81], v[142:145], v[204:207], v[78:81]
	v_mfma_f32_16x16x32_bf16 v[74:77], v[156:159], v[204:207], v[74:77]
	v_mfma_f32_16x16x32_bf16 v[126:129], v[152:155], v[184:187], v[126:129]
	v_mfma_f32_16x16x32_bf16 v[122:125], v[160:163], v[184:187], v[122:125]
	v_mfma_f32_16x16x32_bf16 v[110:113], v[152:155], v[192:195], v[110:113]
	v_mfma_f32_16x16x32_bf16 v[106:109], v[160:163], v[192:195], v[106:109]
	v_mfma_f32_16x16x32_bf16 v[94:97], v[152:155], v[200:203], v[94:97]
	v_mfma_f32_16x16x32_bf16 v[90:93], v[160:163], v[200:203], v[90:93]
	v_mfma_f32_16x16x32_bf16 v[78:81], v[152:155], v[208:211], v[78:81]
	v_mfma_f32_16x16x32_bf16 v[74:77], v[160:163], v[208:211], v[74:77]
	v_mfma_f32_16x16x32_bf16 v[118:121], v[164:167], v[180:183], v[118:121]
	v_mfma_f32_16x16x32_bf16 v[114:117], v[172:175], v[180:183], v[114:117]
	v_mfma_f32_16x16x32_bf16 v[102:105], v[164:167], v[188:191], v[102:105]
	v_mfma_f32_16x16x32_bf16 v[98:101], v[172:175], v[188:191], v[98:101]
	v_mfma_f32_16x16x32_bf16 v[86:89], v[164:167], v[196:199], v[86:89]
	v_mfma_f32_16x16x32_bf16 v[82:85], v[172:175], v[196:199], v[82:85]
	v_mfma_f32_16x16x32_bf16 v[70:73], v[164:167], v[204:207], v[70:73]
	v_mfma_f32_16x16x32_bf16 v[66:69], v[172:175], v[204:207], v[66:69]
	v_mfma_f32_16x16x32_bf16 v[118:121], v[168:171], v[184:187], v[118:121]
	v_mfma_f32_16x16x32_bf16 v[114:117], v[176:179], v[184:187], v[114:117]
	v_mfma_f32_16x16x32_bf16 v[102:105], v[168:171], v[192:195], v[102:105]
	v_mfma_f32_16x16x32_bf16 v[98:101], v[176:179], v[192:195], v[98:101]
	v_mfma_f32_16x16x32_bf16 v[86:89], v[168:171], v[200:203], v[86:89]
	v_mfma_f32_16x16x32_bf16 v[82:85], v[176:179], v[200:203], v[82:85]
	v_mfma_f32_16x16x32_bf16 v[70:73], v[168:171], v[208:211], v[70:73]
	v_mfma_f32_16x16x32_bf16 v[66:69], v[176:179], v[208:211], v[66:69]
	s_barrier
	s_add_i32 s24, s48, s37
	v_lshl_add_u64 v[212:213], s[28:29], 0, v[130:131]
	s_mov_b32 m0, s24
	ds_read_b128 v[180:183], v150 offset:16384
	ds_read_b128 v[184:187], v150 offset:17408
	ds_read_b128 v[188:191], v150 offset:18432
	ds_read_b128 v[192:195], v150 offset:19456
	ds_read_b128 v[196:199], v150 offset:20480
	ds_read_b128 v[200:203], v150 offset:21504
	ds_read_b128 v[204:207], v150 offset:22528
	ds_read_b128 v[208:211], v150 offset:23552
	global_load_lds_dwordx4 v[212:213], off
	s_add_i32 m0, s24, 0x2000
	s_add_u32 s24, s28, 0x80000
	v_lshl_add_u64 v[214:215], s[28:29], 0, v[132:133]
	s_addc_u32 s25, s29, 0
	s_add_i32 s56, s49, s37
	global_load_lds_dwordx4 v[214:215], off
	v_lshl_add_u64 v[216:217], s[24:25], 0, v[130:131]
	s_mov_b32 m0, s56
	v_lshl_add_u64 v[218:219], s[30:31], 0, v[132:133]
	global_load_lds_dwordx4 v[216:217], off
	v_lshl_add_u64 v[216:217], s[24:25], 0, v[132:133]
	s_add_i32 m0, s56, 0x2000
	s_nop 0
	global_load_lds_dwordx4 v[216:217], off
	v_lshl_add_u64 v[216:217], s[30:31], 0, v[130:131]
	s_mov_b32 m0, s5
	s_nop 0
	global_load_lds_dwordx4 v[216:217], off
	s_mov_b32 m0, s38
	s_nop 0
	global_load_lds_dwordx4 v[218:219], off
	s_waitcnt vmcnt(8)
	s_waitcnt lgkmcnt(0)
	s_barrier
	s_waitcnt lgkmcnt(0)
	v_mfma_f32_16x16x32_bf16 v[62:65], v[142:145], v[180:183], v[62:65]
	v_mfma_f32_16x16x32_bf16 v[58:61], v[156:159], v[180:183], v[58:61]
	v_mfma_f32_16x16x32_bf16 v[46:49], v[142:145], v[188:191], v[46:49]
	v_mfma_f32_16x16x32_bf16 v[42:45], v[156:159], v[188:191], v[42:45]
	v_mfma_f32_16x16x32_bf16 v[30:33], v[142:145], v[196:199], v[30:33]
	v_mfma_f32_16x16x32_bf16 v[26:29], v[156:159], v[196:199], v[26:29]
	v_mfma_f32_16x16x32_bf16 v[14:17], v[142:145], v[204:207], v[14:17]
	v_mfma_f32_16x16x32_bf16 v[10:13], v[156:159], v[204:207], v[10:13]
	v_mfma_f32_16x16x32_bf16 v[62:65], v[152:155], v[184:187], v[62:65]
	v_mfma_f32_16x16x32_bf16 v[58:61], v[160:163], v[184:187], v[58:61]
	v_mfma_f32_16x16x32_bf16 v[46:49], v[152:155], v[192:195], v[46:49]
	v_mfma_f32_16x16x32_bf16 v[42:45], v[160:163], v[192:195], v[42:45]
	v_mfma_f32_16x16x32_bf16 v[30:33], v[152:155], v[200:203], v[30:33]
	v_mfma_f32_16x16x32_bf16 v[26:29], v[160:163], v[200:203], v[26:29]
	v_mfma_f32_16x16x32_bf16 v[14:17], v[152:155], v[208:211], v[14:17]
	v_mfma_f32_16x16x32_bf16 v[10:13], v[160:163], v[208:211], v[10:13]
	v_mfma_f32_16x16x32_bf16 v[54:57], v[164:167], v[180:183], v[54:57]
	v_mfma_f32_16x16x32_bf16 v[50:53], v[172:175], v[180:183], v[50:53]
	v_mfma_f32_16x16x32_bf16 v[38:41], v[164:167], v[188:191], v[38:41]
	v_mfma_f32_16x16x32_bf16 v[34:37], v[172:175], v[188:191], v[34:37]
	v_mfma_f32_16x16x32_bf16 v[22:25], v[164:167], v[196:199], v[22:25]
	v_mfma_f32_16x16x32_bf16 v[18:21], v[172:175], v[196:199], v[18:21]
	v_mfma_f32_16x16x32_bf16 v[6:9], v[164:167], v[204:207], v[6:9]
	v_mfma_f32_16x16x32_bf16 v[2:5], v[172:175], v[204:207], v[2:5]
	v_mfma_f32_16x16x32_bf16 v[54:57], v[168:171], v[184:187], v[54:57]
	v_mfma_f32_16x16x32_bf16 v[50:53], v[176:179], v[184:187], v[50:53]
	v_mfma_f32_16x16x32_bf16 v[38:41], v[168:171], v[192:195], v[38:41]
	v_mfma_f32_16x16x32_bf16 v[34:37], v[176:179], v[192:195], v[34:37]
	v_mfma_f32_16x16x32_bf16 v[22:25], v[168:171], v[200:203], v[22:25]
	v_mfma_f32_16x16x32_bf16 v[18:21], v[176:179], v[200:203], v[18:21]
	v_mfma_f32_16x16x32_bf16 v[6:9], v[168:171], v[208:211], v[6:9]
	v_mfma_f32_16x16x32_bf16 v[2:5], v[176:179], v[208:211], v[2:5]
	s_barrier
	s_add_i32 s56, 0, 0x18000
	s_add_i32 s57, 0, 0x1c000
	v_add_u32_e32 v160, s56, v147
	v_add_u32_e32 v176, s57, v147
	ds_read_b128 v[142:145], v160
	ds_read_b128 v[152:155], v160 offset:1024
	ds_read_b128 v[156:159], v160 offset:2048
	ds_read_b128 v[160:163], v160 offset:3072
	ds_read_b128 v[164:167], v176
	ds_read_b128 v[168:171], v176 offset:1024
	ds_read_b128 v[172:175], v176 offset:2048
	ds_read_b128 v[176:179], v176 offset:3072
	s_add_u32 s24, s30, 0x80000
	s_addc_u32 s25, s31, 0
	s_mov_b32 m0, s39
	v_lshl_add_u64 v[220:221], s[24:25], 0, v[130:131]
	ds_read_b128 v[180:183], v150 offset:32768
	ds_read_b128 v[184:187], v150 offset:33792
	ds_read_b128 v[188:191], v150 offset:34816
	ds_read_b128 v[192:195], v150 offset:35840
	ds_read_b128 v[196:199], v150 offset:36864
	ds_read_b128 v[200:203], v150 offset:37888
	ds_read_b128 v[204:207], v150 offset:38912
	ds_read_b128 v[208:211], v150 offset:39936
	global_load_lds_dwordx4 v[220:221], off
	v_lshl_add_u64 v[220:221], s[24:25], 0, v[132:133]
	s_mov_b32 m0, s40
	s_nop 0
	global_load_lds_dwordx4 v[220:221], off
	s_waitcnt vmcnt(8)
	s_waitcnt lgkmcnt(0)
	s_barrier
	s_waitcnt lgkmcnt(0)
	v_mfma_f32_16x16x32_bf16 v[126:129], v[142:145], v[180:183], v[126:129]
	v_mfma_f32_16x16x32_bf16 v[122:125], v[156:159], v[180:183], v[122:125]
	v_mfma_f32_16x16x32_bf16 v[110:113], v[142:145], v[188:191], v[110:113]
	v_mfma_f32_16x16x32_bf16 v[106:109], v[156:159], v[188:191], v[106:109]
	v_mfma_f32_16x16x32_bf16 v[94:97], v[142:145], v[196:199], v[94:97]
	v_mfma_f32_16x16x32_bf16 v[90:93], v[156:159], v[196:199], v[90:93]
	v_mfma_f32_16x16x32_bf16 v[78:81], v[142:145], v[204:207], v[78:81]
	v_mfma_f32_16x16x32_bf16 v[74:77], v[156:159], v[204:207], v[74:77]
	v_mfma_f32_16x16x32_bf16 v[126:129], v[152:155], v[184:187], v[126:129]
	v_mfma_f32_16x16x32_bf16 v[122:125], v[160:163], v[184:187], v[122:125]
	v_mfma_f32_16x16x32_bf16 v[110:113], v[152:155], v[192:195], v[110:113]
	v_mfma_f32_16x16x32_bf16 v[106:109], v[160:163], v[192:195], v[106:109]
	v_mfma_f32_16x16x32_bf16 v[94:97], v[152:155], v[200:203], v[94:97]
	v_mfma_f32_16x16x32_bf16 v[90:93], v[160:163], v[200:203], v[90:93]
	v_mfma_f32_16x16x32_bf16 v[78:81], v[152:155], v[208:211], v[78:81]
	v_mfma_f32_16x16x32_bf16 v[74:77], v[160:163], v[208:211], v[74:77]
	v_mfma_f32_16x16x32_bf16 v[118:121], v[164:167], v[180:183], v[118:121]
	v_mfma_f32_16x16x32_bf16 v[114:117], v[172:175], v[180:183], v[114:117]
	v_mfma_f32_16x16x32_bf16 v[102:105], v[164:167], v[188:191], v[102:105]
	v_mfma_f32_16x16x32_bf16 v[98:101], v[172:175], v[188:191], v[98:101]
	v_mfma_f32_16x16x32_bf16 v[86:89], v[164:167], v[196:199], v[86:89]
	v_mfma_f32_16x16x32_bf16 v[82:85], v[172:175], v[196:199], v[82:85]
	v_mfma_f32_16x16x32_bf16 v[70:73], v[164:167], v[204:207], v[70:73]
	v_mfma_f32_16x16x32_bf16 v[66:69], v[172:175], v[204:207], v[66:69]
	v_mfma_f32_16x16x32_bf16 v[118:121], v[168:171], v[184:187], v[118:121]
	v_mfma_f32_16x16x32_bf16 v[114:117], v[176:179], v[184:187], v[114:117]
	v_mfma_f32_16x16x32_bf16 v[102:105], v[168:171], v[192:195], v[102:105]
	v_mfma_f32_16x16x32_bf16 v[98:101], v[176:179], v[192:195], v[98:101]
	v_mfma_f32_16x16x32_bf16 v[86:89], v[168:171], v[200:203], v[86:89]
	v_mfma_f32_16x16x32_bf16 v[82:85], v[176:179], v[200:203], v[82:85]
	v_mfma_f32_16x16x32_bf16 v[70:73], v[168:171], v[208:211], v[70:73]
	v_mfma_f32_16x16x32_bf16 v[66:69], v[176:179], v[208:211], v[66:69]
	s_barrier
	s_add_i32 s24, s56, s37
	v_lshl_add_u64 v[212:213], v[212:213], 0, s[12:13]
	s_mov_b32 m0, s24
	ds_read_b128 v[180:183], v150 offset:49152
	ds_read_b128 v[184:187], v150 offset:50176
	ds_read_b128 v[188:191], v150 offset:51200
	ds_read_b128 v[192:195], v150 offset:52224
	ds_read_b128 v[196:199], v150 offset:53248
	ds_read_b128 v[200:203], v150 offset:54272
	ds_read_b128 v[204:207], v150 offset:55296
	ds_read_b128 v[208:211], v150 offset:56320
	global_load_lds_dwordx4 v[212:213], off
	s_add_i32 m0, s24, 0x2000
	s_add_u32 s24, s28, 0x80080
	v_lshl_add_u64 v[212:213], v[214:215], 0, s[12:13]
	s_addc_u32 s25, s29, 0
	s_add_i32 s28, s57, s37
	global_load_lds_dwordx4 v[212:213], off
	v_lshl_add_u64 v[212:213], s[24:25], 0, v[130:131]
	s_mov_b32 m0, s28
	s_nop 0
	global_load_lds_dwordx4 v[212:213], off
	v_lshl_add_u64 v[212:213], s[24:25], 0, v[132:133]
	s_add_i32 m0, s28, 0x2000
	s_nop 0
	global_load_lds_dwordx4 v[212:213], off
	v_lshl_add_u64 v[212:213], v[216:217], 0, s[12:13]
	s_mov_b32 m0, s44
	s_nop 0
	global_load_lds_dwordx4 v[212:213], off
	v_lshl_add_u64 v[212:213], v[218:219], 0, s[12:13]
	s_mov_b32 m0, s45
	s_nop 0
	global_load_lds_dwordx4 v[212:213], off
	s_waitcnt vmcnt(8)
	s_waitcnt lgkmcnt(0)
	s_barrier
	s_waitcnt lgkmcnt(0)
	v_mfma_f32_16x16x32_bf16 v[62:65], v[142:145], v[180:183], v[62:65]
	v_mfma_f32_16x16x32_bf16 v[58:61], v[156:159], v[180:183], v[58:61]
	v_mfma_f32_16x16x32_bf16 v[46:49], v[142:145], v[188:191], v[46:49]
	v_mfma_f32_16x16x32_bf16 v[42:45], v[156:159], v[188:191], v[42:45]
	v_mfma_f32_16x16x32_bf16 v[30:33], v[142:145], v[196:199], v[30:33]
	v_mfma_f32_16x16x32_bf16 v[26:29], v[156:159], v[196:199], v[26:29]
	v_mfma_f32_16x16x32_bf16 v[14:17], v[142:145], v[204:207], v[14:17]
	v_mfma_f32_16x16x32_bf16 v[10:13], v[156:159], v[204:207], v[10:13]
	v_mfma_f32_16x16x32_bf16 v[62:65], v[152:155], v[184:187], v[62:65]
	v_mfma_f32_16x16x32_bf16 v[58:61], v[160:163], v[184:187], v[58:61]
	v_mfma_f32_16x16x32_bf16 v[46:49], v[152:155], v[192:195], v[46:49]
	v_mfma_f32_16x16x32_bf16 v[42:45], v[160:163], v[192:195], v[42:45]
	v_mfma_f32_16x16x32_bf16 v[30:33], v[152:155], v[200:203], v[30:33]
	v_mfma_f32_16x16x32_bf16 v[26:29], v[160:163], v[200:203], v[26:29]
	v_mfma_f32_16x16x32_bf16 v[14:17], v[152:155], v[208:211], v[14:17]
	v_mfma_f32_16x16x32_bf16 v[10:13], v[160:163], v[208:211], v[10:13]
	v_mfma_f32_16x16x32_bf16 v[54:57], v[164:167], v[180:183], v[54:57]
	v_mfma_f32_16x16x32_bf16 v[50:53], v[172:175], v[180:183], v[50:53]
	v_mfma_f32_16x16x32_bf16 v[38:41], v[164:167], v[188:191], v[38:41]
	v_mfma_f32_16x16x32_bf16 v[34:37], v[172:175], v[188:191], v[34:37]
	v_mfma_f32_16x16x32_bf16 v[22:25], v[164:167], v[196:199], v[22:25]
	v_mfma_f32_16x16x32_bf16 v[18:21], v[172:175], v[196:199], v[18:21]
	v_mfma_f32_16x16x32_bf16 v[6:9], v[164:167], v[204:207], v[6:9]
	v_mfma_f32_16x16x32_bf16 v[2:5], v[172:175], v[204:207], v[2:5]
	v_mfma_f32_16x16x32_bf16 v[54:57], v[168:171], v[184:187], v[54:57]
	v_mfma_f32_16x16x32_bf16 v[50:53], v[176:179], v[184:187], v[50:53]
	v_mfma_f32_16x16x32_bf16 v[38:41], v[168:171], v[192:195], v[38:41]
	v_mfma_f32_16x16x32_bf16 v[34:37], v[176:179], v[192:195], v[34:37]
	v_mfma_f32_16x16x32_bf16 v[22:25], v[168:171], v[200:203], v[22:25]
	v_mfma_f32_16x16x32_bf16 v[18:21], v[176:179], v[200:203], v[18:21]
	v_mfma_f32_16x16x32_bf16 v[6:9], v[168:171], v[208:211], v[6:9]
	v_mfma_f32_16x16x32_bf16 v[2:5], v[176:179], v[208:211], v[2:5]
	s_barrier
	s_add_i32 s55, s55, 2
	s_add_u32 s53, s53, 0x100
	s_addc_u32 s54, s54, 0
	s_cmp_gt_u32 s55, 29
	s_mov_b64 s[24:25], s[26:27]
	s_cbranch_scc0 .LBB0_3114
	s_and_b64 vcc, exec, s[14:15]
	s_cbranch_vccz .LBB0_3117
	s_barrier

.LBB0_3201:
	s_waitcnt lgkmcnt(0)
	s_add_u32 s40, s8, 0xfff80080
	s_addc_u32 s41, s9, -1
	s_cmp_eq_u32 s66, 28
	s_cselect_b32 s43, s7, s41
	s_cselect_b32 s42, s35, s40
	s_cselect_b32 s41, s31, s65
	s_cselect_b32 s40, s63, s64
	v_lshl_add_u64 v[216:217], s[8:9], 0, v[138:139]
	s_add_i32 m0, s46, 0xc000
	s_nop 0
	global_load_lds_dwordx4 v[216:217], off
	v_lshl_add_u64 v[216:217], s[8:9], 0, v[140:141]
	s_add_i32 m0, s46, 0xe000
	s_nop 0
	global_load_lds_dwordx4 v[216:217], off
	ds_read_b128 v[146:149], v164
	ds_read_b128 v[150:153], v164 offset:1024
	ds_read_b128 v[154:157], v164 offset:2048
	ds_read_b128 v[158:161], v164 offset:3072
	ds_read_b128 v[168:171], v165
	ds_read_b128 v[172:175], v165 offset:1024
	ds_read_b128 v[176:179], v165 offset:2048
	ds_read_b128 v[180:183], v165 offset:3072
	ds_read_b128 v[184:187], v166
	ds_read_b128 v[188:191], v166 offset:1024
	ds_read_b128 v[192:195], v166 offset:2048
	ds_read_b128 v[196:199], v166 offset:3072
	ds_read_b128 v[200:203], v166 offset:4096
	ds_read_b128 v[204:207], v166 offset:5120
	ds_read_b128 v[208:211], v166 offset:6144
	ds_read_b128 v[212:215], v166 offset:7168
	s_waitcnt vmcnt(8)
	s_waitcnt lgkmcnt(0)
	s_barrier
	s_waitcnt lgkmcnt(0)
	v_mfma_f32_16x16x32_bf16 v[126:129], v[146:149], v[184:187], v[126:129]
	v_mfma_f32_16x16x32_bf16 v[122:125], v[154:157], v[184:187], v[122:125]
	v_mfma_f32_16x16x32_bf16 v[118:121], v[146:149], v[192:195], v[118:121]
	v_mfma_f32_16x16x32_bf16 v[110:113], v[154:157], v[192:195], v[110:113]
	v_mfma_f32_16x16x32_bf16 v[102:105], v[146:149], v[200:203], v[102:105]
	v_mfma_f32_16x16x32_bf16 v[94:97], v[154:157], v[200:203], v[94:97]
	v_mfma_f32_16x16x32_bf16 v[86:89], v[146:149], v[208:211], v[86:89]
	v_mfma_f32_16x16x32_bf16 v[78:81], v[154:157], v[208:211], v[78:81]
	v_mfma_f32_16x16x32_bf16 v[126:129], v[150:153], v[188:191], v[126:129]
	v_mfma_f32_16x16x32_bf16 v[122:125], v[158:161], v[188:191], v[122:125]
	v_mfma_f32_16x16x32_bf16 v[118:121], v[150:153], v[196:199], v[118:121]
	v_mfma_f32_16x16x32_bf16 v[110:113], v[158:161], v[196:199], v[110:113]
	v_mfma_f32_16x16x32_bf16 v[102:105], v[150:153], v[204:207], v[102:105]
	v_mfma_f32_16x16x32_bf16 v[94:97], v[158:161], v[204:207], v[94:97]
	v_mfma_f32_16x16x32_bf16 v[86:89], v[150:153], v[212:215], v[86:89]
	v_mfma_f32_16x16x32_bf16 v[78:81], v[158:161], v[212:215], v[78:81]
	v_mfma_f32_16x16x32_bf16 v[114:117], v[168:171], v[184:187], v[114:117]
	v_mfma_f32_16x16x32_bf16 v[106:109], v[176:179], v[184:187], v[106:109]
	v_mfma_f32_16x16x32_bf16 v[98:101], v[168:171], v[192:195], v[98:101]
	v_mfma_f32_16x16x32_bf16 v[90:93], v[176:179], v[192:195], v[90:93]
	v_mfma_f32_16x16x32_bf16 v[82:85], v[168:171], v[200:203], v[82:85]
	v_mfma_f32_16x16x32_bf16 v[74:77], v[176:179], v[200:203], v[74:77]
	v_mfma_f32_16x16x32_bf16 v[70:73], v[168:171], v[208:211], v[70:73]
	v_mfma_f32_16x16x32_bf16 v[66:69], v[176:179], v[208:211], v[66:69]
	v_mfma_f32_16x16x32_bf16 v[114:117], v[172:175], v[188:191], v[114:117]
	v_mfma_f32_16x16x32_bf16 v[106:109], v[180:183], v[188:191], v[106:109]
	v_mfma_f32_16x16x32_bf16 v[98:101], v[172:175], v[196:199], v[98:101]
	v_mfma_f32_16x16x32_bf16 v[90:93], v[180:183], v[196:199], v[90:93]
	v_mfma_f32_16x16x32_bf16 v[82:85], v[172:175], v[204:207], v[82:85]
	v_mfma_f32_16x16x32_bf16 v[74:77], v[180:183], v[204:207], v[74:77]
	v_mfma_f32_16x16x32_bf16 v[70:73], v[172:175], v[212:215], v[70:73]
	v_mfma_f32_16x16x32_bf16 v[66:69], v[180:183], v[212:215], v[66:69]
	s_barrier
	s_add_i32 s67, s56, s33
	v_lshl_add_u64 v[216:217], s[40:41], 0, v[134:135]
	s_mov_b32 m0, s67
	s_nop 0
	global_load_lds_dwordx4 v[216:217], off
	s_add_i32 m0, s67, 0x2000
	s_add_u32 s68, s40, 0x80000
	v_lshl_add_u64 v[218:219], s[40:41], 0, v[130:131]
	s_addc_u32 s69, s41, 0
	s_add_i32 s67, s57, s33
	global_load_lds_dwordx4 v[218:219], off
	v_lshl_add_u64 v[220:221], s[68:69], 0, v[134:135]
	s_mov_b32 m0, s67
	v_lshl_add_u64 v[222:223], s[42:43], 0, v[132:133]
	global_load_lds_dwordx4 v[220:221], off
	v_lshl_add_u64 v[220:221], s[68:69], 0, v[130:131]
	s_add_i32 m0, s67, 0x2000
	s_nop 0
	global_load_lds_dwordx4 v[220:221], off
	v_lshl_add_u64 v[220:221], s[42:43], 0, v[136:137]
	s_mov_b32 m0, s46
	s_nop 0
	global_load_lds_dwordx4 v[220:221], off
	s_mov_b32 m0, s47
	s_nop 0
	global_load_lds_dwordx4 v[222:223], off
	ds_read_b128 v[184:187], v166 offset:16384
	ds_read_b128 v[188:191], v166 offset:17408
	ds_read_b128 v[192:195], v166 offset:18432
	ds_read_b128 v[196:199], v166 offset:19456
	ds_read_b128 v[200:203], v166 offset:20480
	ds_read_b128 v[204:207], v166 offset:21504
	ds_read_b128 v[208:211], v166 offset:22528
	ds_read_b128 v[212:215], v166 offset:23552
	s_waitcnt vmcnt(8)
	s_waitcnt lgkmcnt(0)
	s_barrier
	s_waitcnt lgkmcnt(0)
	v_mfma_f32_16x16x32_bf16 v[62:65], v[146:149], v[184:187], v[62:65]
	v_mfma_f32_16x16x32_bf16 v[58:61], v[154:157], v[184:187], v[58:61]
	v_mfma_f32_16x16x32_bf16 v[54:57], v[146:149], v[192:195], v[54:57]
	v_mfma_f32_16x16x32_bf16 v[46:49], v[154:157], v[192:195], v[46:49]
	v_mfma_f32_16x16x32_bf16 v[38:41], v[146:149], v[200:203], v[38:41]
	v_mfma_f32_16x16x32_bf16 v[30:33], v[154:157], v[200:203], v[30:33]
	v_mfma_f32_16x16x32_bf16 v[22:25], v[146:149], v[208:211], v[22:25]
	v_mfma_f32_16x16x32_bf16 v[14:17], v[154:157], v[208:211], v[14:17]
	v_mfma_f32_16x16x32_bf16 v[62:65], v[150:153], v[188:191], v[62:65]
	v_mfma_f32_16x16x32_bf16 v[58:61], v[158:161], v[188:191], v[58:61]
	v_mfma_f32_16x16x32_bf16 v[54:57], v[150:153], v[196:199], v[54:57]
	v_mfma_f32_16x16x32_bf16 v[46:49], v[158:161], v[196:199], v[46:49]
	v_mfma_f32_16x16x32_bf16 v[38:41], v[150:153], v[204:207], v[38:41]
	v_mfma_f32_16x16x32_bf16 v[30:33], v[158:161], v[204:207], v[30:33]
	v_mfma_f32_16x16x32_bf16 v[22:25], v[150:153], v[212:215], v[22:25]
	v_mfma_f32_16x16x32_bf16 v[14:17], v[158:161], v[212:215], v[14:17]
	v_mfma_f32_16x16x32_bf16 v[50:53], v[168:171], v[184:187], v[50:53]
	v_mfma_f32_16x16x32_bf16 v[42:45], v[176:179], v[184:187], v[42:45]
	v_mfma_f32_16x16x32_bf16 v[34:37], v[168:171], v[192:195], v[34:37]
	v_mfma_f32_16x16x32_bf16 v[26:29], v[176:179], v[192:195], v[26:29]
	v_mfma_f32_16x16x32_bf16 v[18:21], v[168:171], v[200:203], v[18:21]
	v_mfma_f32_16x16x32_bf16 v[10:13], v[176:179], v[200:203], v[10:13]
	v_mfma_f32_16x16x32_bf16 v[6:9], v[168:171], v[208:211], v[6:9]
	v_mfma_f32_16x16x32_bf16 v[2:5], v[176:179], v[208:211], v[2:5]
	v_mfma_f32_16x16x32_bf16 v[50:53], v[172:175], v[188:191], v[50:53]
	v_mfma_f32_16x16x32_bf16 v[42:45], v[180:183], v[188:191], v[42:45]
	v_mfma_f32_16x16x32_bf16 v[34:37], v[172:175], v[196:199], v[34:37]
	v_mfma_f32_16x16x32_bf16 v[26:29], v[180:183], v[196:199], v[26:29]
	v_mfma_f32_16x16x32_bf16 v[18:21], v[172:175], v[204:207], v[18:21]
	v_mfma_f32_16x16x32_bf16 v[10:13], v[180:183], v[204:207], v[10:13]
	v_mfma_f32_16x16x32_bf16 v[6:9], v[172:175], v[212:215], v[6:9]
	v_mfma_f32_16x16x32_bf16 v[2:5], v[180:183], v[212:215], v[2:5]
	s_barrier
	s_add_i32 s67, 0, 0x18000
	s_add_i32 s68, 0, 0x1c000
	v_add_u32_e32 v158, s67, v163
	v_add_u32_e32 v180, s68, v163
	s_add_u32 s42, s42, 0x80000
	s_addc_u32 s43, s43, 0
	s_mov_b32 m0, s48
	v_lshl_add_u64 v[224:225], s[42:43], 0, v[136:137]
	global_load_lds_dwordx4 v[224:225], off
	v_lshl_add_u64 v[224:225], s[42:43], 0, v[132:133]
	s_mov_b32 m0, s49
	s_nop 0
	global_load_lds_dwordx4 v[224:225], off
	ds_read_b128 v[146:149], v158
	ds_read_b128 v[150:153], v158 offset:1024
	ds_read_b128 v[154:157], v158 offset:2048
	ds_read_b128 v[158:161], v158 offset:3072
	ds_read_b128 v[168:171], v180
	ds_read_b128 v[172:175], v180 offset:1024
	ds_read_b128 v[176:179], v180 offset:2048
	ds_read_b128 v[180:183], v180 offset:3072
	ds_read_b128 v[184:187], v166 offset:32768
	ds_read_b128 v[188:191], v166 offset:33792
	ds_read_b128 v[192:195], v166 offset:34816
	ds_read_b128 v[196:199], v166 offset:35840
	ds_read_b128 v[200:203], v166 offset:36864
	ds_read_b128 v[204:207], v166 offset:37888
	ds_read_b128 v[208:211], v166 offset:38912
	ds_read_b128 v[212:215], v166 offset:39936
	s_waitcnt vmcnt(8)
	s_waitcnt lgkmcnt(0)
	s_barrier
	s_waitcnt lgkmcnt(0)
	v_mfma_f32_16x16x32_bf16 v[126:129], v[146:149], v[184:187], v[126:129]
	v_mfma_f32_16x16x32_bf16 v[122:125], v[154:157], v[184:187], v[122:125]
	v_mfma_f32_16x16x32_bf16 v[118:121], v[146:149], v[192:195], v[118:121]
	v_mfma_f32_16x16x32_bf16 v[110:113], v[154:157], v[192:195], v[110:113]
	v_mfma_f32_16x16x32_bf16 v[102:105], v[146:149], v[200:203], v[102:105]
	v_mfma_f32_16x16x32_bf16 v[94:97], v[154:157], v[200:203], v[94:97]
	v_mfma_f32_16x16x32_bf16 v[86:89], v[146:149], v[208:211], v[86:89]
	v_mfma_f32_16x16x32_bf16 v[78:81], v[154:157], v[208:211], v[78:81]
	v_mfma_f32_16x16x32_bf16 v[126:129], v[150:153], v[188:191], v[126:129]
	v_mfma_f32_16x16x32_bf16 v[122:125], v[158:161], v[188:191], v[122:125]
	v_mfma_f32_16x16x32_bf16 v[118:121], v[150:153], v[196:199], v[118:121]
	v_mfma_f32_16x16x32_bf16 v[110:113], v[158:161], v[196:199], v[110:113]
	v_mfma_f32_16x16x32_bf16 v[102:105], v[150:153], v[204:207], v[102:105]
	v_mfma_f32_16x16x32_bf16 v[94:97], v[158:161], v[204:207], v[94:97]
	v_mfma_f32_16x16x32_bf16 v[86:89], v[150:153], v[212:215], v[86:89]
	v_mfma_f32_16x16x32_bf16 v[78:81], v[158:161], v[212:215], v[78:81]
	v_mfma_f32_16x16x32_bf16 v[114:117], v[168:171], v[184:187], v[114:117]
	v_mfma_f32_16x16x32_bf16 v[106:109], v[176:179], v[184:187], v[106:109]
	v_mfma_f32_16x16x32_bf16 v[98:101], v[168:171], v[192:195], v[98:101]
	v_mfma_f32_16x16x32_bf16 v[90:93], v[176:179], v[192:195], v[90:93]
	v_mfma_f32_16x16x32_bf16 v[82:85], v[168:171], v[200:203], v[82:85]
	v_mfma_f32_16x16x32_bf16 v[74:77], v[176:179], v[200:203], v[74:77]
	v_mfma_f32_16x16x32_bf16 v[70:73], v[168:171], v[208:211], v[70:73]
	v_mfma_f32_16x16x32_bf16 v[66:69], v[176:179], v[208:211], v[66:69]
	v_mfma_f32_16x16x32_bf16 v[114:117], v[172:175], v[188:191], v[114:117]
	v_mfma_f32_16x16x32_bf16 v[106:109], v[180:183], v[188:191], v[106:109]
	v_mfma_f32_16x16x32_bf16 v[98:101], v[172:175], v[196:199], v[98:101]
	v_mfma_f32_16x16x32_bf16 v[90:93], v[180:183], v[196:199], v[90:93]
	v_mfma_f32_16x16x32_bf16 v[82:85], v[172:175], v[204:207], v[82:85]
	v_mfma_f32_16x16x32_bf16 v[74:77], v[180:183], v[204:207], v[74:77]
	v_mfma_f32_16x16x32_bf16 v[70:73], v[172:175], v[212:215], v[70:73]
	v_mfma_f32_16x16x32_bf16 v[66:69], v[180:183], v[212:215], v[66:69]
	s_barrier
	s_add_i32 s42, s67, s33
	v_lshl_add_u64 v[216:217], v[216:217], 0, s[12:13]
	s_mov_b32 m0, s42
	s_nop 0
	global_load_lds_dwordx4 v[216:217], off
	s_add_i32 m0, s42, 0x2000
	s_add_u32 s40, s40, 0x80080
	v_lshl_add_u64 v[216:217], v[218:219], 0, s[12:13]
	s_addc_u32 s41, s41, 0
	s_add_i32 s42, s68, s33
	global_load_lds_dwordx4 v[216:217], off
	v_lshl_add_u64 v[216:217], s[40:41], 0, v[134:135]
	s_mov_b32 m0, s42
	s_nop 0
	global_load_lds_dwordx4 v[216:217], off
	v_lshl_add_u64 v[216:217], s[40:41], 0, v[130:131]
	s_add_i32 m0, s42, 0x2000
	s_nop 0
	global_load_lds_dwordx4 v[216:217], off
	v_lshl_add_u64 v[216:217], v[220:221], 0, s[12:13]
	s_mov_b32 m0, s53
	s_nop 0
	global_load_lds_dwordx4 v[216:217], off
	v_lshl_add_u64 v[216:217], v[222:223], 0, s[12:13]
	s_mov_b32 m0, s54
	s_nop 0
	global_load_lds_dwordx4 v[216:217], off
	ds_read_b128 v[184:187], v166 offset:49152
	ds_read_b128 v[188:191], v166 offset:50176
	ds_read_b128 v[192:195], v166 offset:51200
	ds_read_b128 v[196:199], v166 offset:52224
	ds_read_b128 v[200:203], v166 offset:53248
	ds_read_b128 v[204:207], v166 offset:54272
	ds_read_b128 v[208:211], v166 offset:55296
	ds_read_b128 v[212:215], v166 offset:56320
	s_waitcnt vmcnt(8)
	s_waitcnt lgkmcnt(0)
	s_barrier
	s_waitcnt lgkmcnt(0)
	v_mfma_f32_16x16x32_bf16 v[62:65], v[146:149], v[184:187], v[62:65]
	v_mfma_f32_16x16x32_bf16 v[58:61], v[154:157], v[184:187], v[58:61]
	v_mfma_f32_16x16x32_bf16 v[54:57], v[146:149], v[192:195], v[54:57]
	v_mfma_f32_16x16x32_bf16 v[46:49], v[154:157], v[192:195], v[46:49]
	v_mfma_f32_16x16x32_bf16 v[38:41], v[146:149], v[200:203], v[38:41]
	v_mfma_f32_16x16x32_bf16 v[30:33], v[154:157], v[200:203], v[30:33]
	v_mfma_f32_16x16x32_bf16 v[22:25], v[146:149], v[208:211], v[22:25]
	v_mfma_f32_16x16x32_bf16 v[14:17], v[154:157], v[208:211], v[14:17]
	v_mfma_f32_16x16x32_bf16 v[62:65], v[150:153], v[188:191], v[62:65]
	v_mfma_f32_16x16x32_bf16 v[58:61], v[158:161], v[188:191], v[58:61]
	v_mfma_f32_16x16x32_bf16 v[54:57], v[150:153], v[196:199], v[54:57]
	v_mfma_f32_16x16x32_bf16 v[46:49], v[158:161], v[196:199], v[46:49]
	v_mfma_f32_16x16x32_bf16 v[38:41], v[150:153], v[204:207], v[38:41]
	v_mfma_f32_16x16x32_bf16 v[30:33], v[158:161], v[204:207], v[30:33]
	v_mfma_f32_16x16x32_bf16 v[22:25], v[150:153], v[212:215], v[22:25]
	v_mfma_f32_16x16x32_bf16 v[14:17], v[158:161], v[212:215], v[14:17]
	v_mfma_f32_16x16x32_bf16 v[50:53], v[168:171], v[184:187], v[50:53]
	v_mfma_f32_16x16x32_bf16 v[42:45], v[176:179], v[184:187], v[42:45]
	v_mfma_f32_16x16x32_bf16 v[34:37], v[168:171], v[192:195], v[34:37]
	v_mfma_f32_16x16x32_bf16 v[26:29], v[176:179], v[192:195], v[26:29]
	v_mfma_f32_16x16x32_bf16 v[18:21], v[168:171], v[200:203], v[18:21]
	v_mfma_f32_16x16x32_bf16 v[10:13], v[176:179], v[200:203], v[10:13]
	v_mfma_f32_16x16x32_bf16 v[6:9], v[168:171], v[208:211], v[6:9]
	v_mfma_f32_16x16x32_bf16 v[2:5], v[176:179], v[208:211], v[2:5]
	v_mfma_f32_16x16x32_bf16 v[50:53], v[172:175], v[188:191], v[50:53]
	v_mfma_f32_16x16x32_bf16 v[42:45], v[180:183], v[188:191], v[42:45]
	v_mfma_f32_16x16x32_bf16 v[34:37], v[172:175], v[196:199], v[34:37]
	v_mfma_f32_16x16x32_bf16 v[26:29], v[180:183], v[196:199], v[26:29]
	v_mfma_f32_16x16x32_bf16 v[18:21], v[172:175], v[204:207], v[18:21]
	v_mfma_f32_16x16x32_bf16 v[10:13], v[180:183], v[204:207], v[10:13]
	v_mfma_f32_16x16x32_bf16 v[6:9], v[172:175], v[212:215], v[6:9]
	v_mfma_f32_16x16x32_bf16 v[2:5], v[180:183], v[212:215], v[2:5]
	s_barrier
	s_add_i32 s66, s66, 2
	s_add_u32 s8, s8, 0x100
	s_addc_u32 s9, s9, 0
	s_add_u32 s64, s64, 0x100
	s_addc_u32 s65, s65, 0
	s_cmp_gt_u32 s66, 29
	s_cbranch_scc0 .LBB0_3201
	s_and_b64 vcc, exec, s[14:15]
	s_cbranch_vccz .LBB0_3204
	s_barrier

.LBB0_3378:
	ds_read_b128 v[142:145], v148
	ds_read_b128 v[152:155], v148 offset:1024
	ds_read_b128 v[156:159], v148 offset:2048
	ds_read_b128 v[160:163], v148 offset:3072
	ds_read_b128 v[164:167], v149
	ds_read_b128 v[168:171], v149 offset:1024
	ds_read_b128 v[172:175], v149 offset:2048
	ds_read_b128 v[176:179], v149 offset:3072
	s_add_u32 s20, s18, 0x100
	s_addc_u32 s21, s19, 0
	s_cmpk_eq_i32 s49, 0x54
	s_cselect_b32 s25, s7, s21
	s_cselect_b32 s24, s6, s20
	s_cselect_b32 s23, s17, s48
	s_cselect_b32 s22, s16, s47
	v_lshl_add_u64 v[212:213], s[18:19], 0, v[134:135]
	s_add_i32 m0, s28, 0xc000
	ds_read_b128 v[180:183], v150
	ds_read_b128 v[184:187], v150 offset:1024
	ds_read_b128 v[188:191], v150 offset:2048
	ds_read_b128 v[192:195], v150 offset:3072
	ds_read_b128 v[196:199], v150 offset:4096
	ds_read_b128 v[200:203], v150 offset:5120
	ds_read_b128 v[204:207], v150 offset:6144
	ds_read_b128 v[208:211], v150 offset:7168
	global_load_lds_dwordx4 v[212:213], off
	v_lshl_add_u64 v[212:213], s[18:19], 0, v[136:137]
	s_add_i32 m0, s28, 0xe000
	s_nop 0
	global_load_lds_dwordx4 v[212:213], off
	s_waitcnt vmcnt(8)
	s_waitcnt lgkmcnt(0)
	s_barrier
	s_waitcnt lgkmcnt(0)
	v_mfma_f32_16x16x32_bf16 v[126:129], v[142:145], v[180:183], v[126:129]
	v_mfma_f32_16x16x32_bf16 v[122:125], v[156:159], v[180:183], v[122:125]
	v_mfma_f32_16x16x32_bf16 v[110:113], v[142:145], v[188:191], v[110:113]
	v_mfma_f32_16x16x32_bf16 v[106:109], v[156:159], v[188:191], v[106:109]
	v_mfma_f32_16x16x32_bf16 v[94:97], v[142:145], v[196:199], v[94:97]
	v_mfma_f32_16x16x32_bf16 v[90:93], v[156:159], v[196:199], v[90:93]
	v_mfma_f32_16x16x32_bf16 v[78:81], v[142:145], v[204:207], v[78:81]
	v_mfma_f32_16x16x32_bf16 v[74:77], v[156:159], v[204:207], v[74:77]
	v_mfma_f32_16x16x32_bf16 v[126:129], v[152:155], v[184:187], v[126:129]
	v_mfma_f32_16x16x32_bf16 v[122:125], v[160:163], v[184:187], v[122:125]
	v_mfma_f32_16x16x32_bf16 v[110:113], v[152:155], v[192:195], v[110:113]
	v_mfma_f32_16x16x32_bf16 v[106:109], v[160:163], v[192:195], v[106:109]
	v_mfma_f32_16x16x32_bf16 v[94:97], v[152:155], v[200:203], v[94:97]
	v_mfma_f32_16x16x32_bf16 v[90:93], v[160:163], v[200:203], v[90:93]
	v_mfma_f32_16x16x32_bf16 v[78:81], v[152:155], v[208:211], v[78:81]
	v_mfma_f32_16x16x32_bf16 v[74:77], v[160:163], v[208:211], v[74:77]
	v_mfma_f32_16x16x32_bf16 v[118:121], v[164:167], v[180:183], v[118:121]
	v_mfma_f32_16x16x32_bf16 v[114:117], v[172:175], v[180:183], v[114:117]
	v_mfma_f32_16x16x32_bf16 v[102:105], v[164:167], v[188:191], v[102:105]
	v_mfma_f32_16x16x32_bf16 v[98:101], v[172:175], v[188:191], v[98:101]
	v_mfma_f32_16x16x32_bf16 v[86:89], v[164:167], v[196:199], v[86:89]
	v_mfma_f32_16x16x32_bf16 v[82:85], v[172:175], v[196:199], v[82:85]
	v_mfma_f32_16x16x32_bf16 v[70:73], v[164:167], v[204:207], v[70:73]
	v_mfma_f32_16x16x32_bf16 v[66:69], v[172:175], v[204:207], v[66:69]
	v_mfma_f32_16x16x32_bf16 v[118:121], v[168:171], v[184:187], v[118:121]
	v_mfma_f32_16x16x32_bf16 v[114:117], v[176:179], v[184:187], v[114:117]
	v_mfma_f32_16x16x32_bf16 v[102:105], v[168:171], v[192:195], v[102:105]
	v_mfma_f32_16x16x32_bf16 v[98:101], v[176:179], v[192:195], v[98:101]
	v_mfma_f32_16x16x32_bf16 v[86:89], v[168:171], v[200:203], v[86:89]
	v_mfma_f32_16x16x32_bf16 v[82:85], v[176:179], v[200:203], v[82:85]
	v_mfma_f32_16x16x32_bf16 v[70:73], v[168:171], v[208:211], v[70:73]
	v_mfma_f32_16x16x32_bf16 v[66:69], v[176:179], v[208:211], v[66:69]
	s_barrier
	s_add_i32 s18, s41, s27
	v_lshl_add_u64 v[212:213], s[22:23], 0, v[130:131]
	s_mov_b32 m0, s18
	ds_read_b128 v[180:183], v150 offset:16384
	ds_read_b128 v[184:187], v150 offset:17408
	ds_read_b128 v[188:191], v150 offset:18432
	ds_read_b128 v[192:195], v150 offset:19456
	ds_read_b128 v[196:199], v150 offset:20480
	ds_read_b128 v[200:203], v150 offset:21504
	ds_read_b128 v[204:207], v150 offset:22528
	ds_read_b128 v[208:211], v150 offset:23552
	global_load_lds_dwordx4 v[212:213], off
	s_add_i32 m0, s18, 0x2000
	s_add_u32 s18, s22, 0x160000
	v_lshl_add_u64 v[214:215], s[22:23], 0, v[132:133]
	s_addc_u32 s19, s23, 0
	s_add_i32 s50, s42, s27
	global_load_lds_dwordx4 v[214:215], off
	v_lshl_add_u64 v[216:217], s[18:19], 0, v[130:131]
	s_mov_b32 m0, s50
	v_lshl_add_u64 v[218:219], s[24:25], 0, v[132:133]
	global_load_lds_dwordx4 v[216:217], off
	v_lshl_add_u64 v[216:217], s[18:19], 0, v[132:133]
	s_add_i32 m0, s50, 0x2000
	s_nop 0
	global_load_lds_dwordx4 v[216:217], off
	v_lshl_add_u64 v[216:217], s[24:25], 0, v[130:131]
	s_mov_b32 m0, s28
	s_nop 0
	global_load_lds_dwordx4 v[216:217], off
	s_mov_b32 m0, s29
	s_nop 0
	global_load_lds_dwordx4 v[218:219], off
	s_waitcnt vmcnt(8)
	s_waitcnt lgkmcnt(0)
	s_barrier
	s_waitcnt lgkmcnt(0)
	v_mfma_f32_16x16x32_bf16 v[62:65], v[142:145], v[180:183], v[62:65]
	v_mfma_f32_16x16x32_bf16 v[58:61], v[156:159], v[180:183], v[58:61]
	v_mfma_f32_16x16x32_bf16 v[46:49], v[142:145], v[188:191], v[46:49]
	v_mfma_f32_16x16x32_bf16 v[42:45], v[156:159], v[188:191], v[42:45]
	v_mfma_f32_16x16x32_bf16 v[30:33], v[142:145], v[196:199], v[30:33]
	v_mfma_f32_16x16x32_bf16 v[26:29], v[156:159], v[196:199], v[26:29]
	v_mfma_f32_16x16x32_bf16 v[14:17], v[142:145], v[204:207], v[14:17]
	v_mfma_f32_16x16x32_bf16 v[10:13], v[156:159], v[204:207], v[10:13]
	v_mfma_f32_16x16x32_bf16 v[62:65], v[152:155], v[184:187], v[62:65]
	v_mfma_f32_16x16x32_bf16 v[58:61], v[160:163], v[184:187], v[58:61]
	v_mfma_f32_16x16x32_bf16 v[46:49], v[152:155], v[192:195], v[46:49]
	v_mfma_f32_16x16x32_bf16 v[42:45], v[160:163], v[192:195], v[42:45]
	v_mfma_f32_16x16x32_bf16 v[30:33], v[152:155], v[200:203], v[30:33]
	v_mfma_f32_16x16x32_bf16 v[26:29], v[160:163], v[200:203], v[26:29]
	v_mfma_f32_16x16x32_bf16 v[14:17], v[152:155], v[208:211], v[14:17]
	v_mfma_f32_16x16x32_bf16 v[10:13], v[160:163], v[208:211], v[10:13]
	v_mfma_f32_16x16x32_bf16 v[54:57], v[164:167], v[180:183], v[54:57]
	v_mfma_f32_16x16x32_bf16 v[50:53], v[172:175], v[180:183], v[50:53]
	v_mfma_f32_16x16x32_bf16 v[38:41], v[164:167], v[188:191], v[38:41]
	v_mfma_f32_16x16x32_bf16 v[34:37], v[172:175], v[188:191], v[34:37]
	v_mfma_f32_16x16x32_bf16 v[22:25], v[164:167], v[196:199], v[22:25]
	v_mfma_f32_16x16x32_bf16 v[18:21], v[172:175], v[196:199], v[18:21]
	v_mfma_f32_16x16x32_bf16 v[6:9], v[164:167], v[204:207], v[6:9]
	v_mfma_f32_16x16x32_bf16 v[2:5], v[172:175], v[204:207], v[2:5]
	v_mfma_f32_16x16x32_bf16 v[54:57], v[168:171], v[184:187], v[54:57]
	v_mfma_f32_16x16x32_bf16 v[50:53], v[176:179], v[184:187], v[50:53]
	v_mfma_f32_16x16x32_bf16 v[38:41], v[168:171], v[192:195], v[38:41]
	v_mfma_f32_16x16x32_bf16 v[34:37], v[176:179], v[192:195], v[34:37]
	v_mfma_f32_16x16x32_bf16 v[22:25], v[168:171], v[200:203], v[22:25]
	v_mfma_f32_16x16x32_bf16 v[18:21], v[176:179], v[200:203], v[18:21]
	v_mfma_f32_16x16x32_bf16 v[6:9], v[168:171], v[208:211], v[6:9]
	v_mfma_f32_16x16x32_bf16 v[2:5], v[176:179], v[208:211], v[2:5]
	s_barrier
	s_add_i32 s50, 0, 0x18000
	s_add_i32 s51, 0, 0x1c000
	v_add_u32_e32 v160, s50, v147
	v_add_u32_e32 v176, s51, v147
	ds_read_b128 v[142:145], v160
	ds_read_b128 v[152:155], v160 offset:1024
	ds_read_b128 v[156:159], v160 offset:2048
	ds_read_b128 v[160:163], v160 offset:3072
	ds_read_b128 v[164:167], v176
	ds_read_b128 v[168:171], v176 offset:1024
	ds_read_b128 v[172:175], v176 offset:2048
	ds_read_b128 v[176:179], v176 offset:3072
	s_add_u32 s18, s24, 0x160000
	s_addc_u32 s19, s25, 0
	s_mov_b32 m0, s30
	v_lshl_add_u64 v[220:221], s[18:19], 0, v[130:131]
	ds_read_b128 v[180:183], v150 offset:32768
	ds_read_b128 v[184:187], v150 offset:33792
	ds_read_b128 v[188:191], v150 offset:34816
	ds_read_b128 v[192:195], v150 offset:35840
	ds_read_b128 v[196:199], v150 offset:36864
	ds_read_b128 v[200:203], v150 offset:37888
	ds_read_b128 v[204:207], v150 offset:38912
	ds_read_b128 v[208:211], v150 offset:39936
	global_load_lds_dwordx4 v[220:221], off
	v_lshl_add_u64 v[220:221], s[18:19], 0, v[132:133]
	s_mov_b32 m0, s31
	s_nop 0
	global_load_lds_dwordx4 v[220:221], off
	s_waitcnt vmcnt(8)
	s_waitcnt lgkmcnt(0)
	s_barrier
	s_waitcnt lgkmcnt(0)
	v_mfma_f32_16x16x32_bf16 v[126:129], v[142:145], v[180:183], v[126:129]
	v_mfma_f32_16x16x32_bf16 v[122:125], v[156:159], v[180:183], v[122:125]
	v_mfma_f32_16x16x32_bf16 v[110:113], v[142:145], v[188:191], v[110:113]
	v_mfma_f32_16x16x32_bf16 v[106:109], v[156:159], v[188:191], v[106:109]
	v_mfma_f32_16x16x32_bf16 v[94:97], v[142:145], v[196:199], v[94:97]
	v_mfma_f32_16x16x32_bf16 v[90:93], v[156:159], v[196:199], v[90:93]
	v_mfma_f32_16x16x32_bf16 v[78:81], v[142:145], v[204:207], v[78:81]
	v_mfma_f32_16x16x32_bf16 v[74:77], v[156:159], v[204:207], v[74:77]
	v_mfma_f32_16x16x32_bf16 v[126:129], v[152:155], v[184:187], v[126:129]
	v_mfma_f32_16x16x32_bf16 v[122:125], v[160:163], v[184:187], v[122:125]
	v_mfma_f32_16x16x32_bf16 v[110:113], v[152:155], v[192:195], v[110:113]
	v_mfma_f32_16x16x32_bf16 v[106:109], v[160:163], v[192:195], v[106:109]
	v_mfma_f32_16x16x32_bf16 v[94:97], v[152:155], v[200:203], v[94:97]
	v_mfma_f32_16x16x32_bf16 v[90:93], v[160:163], v[200:203], v[90:93]
	v_mfma_f32_16x16x32_bf16 v[78:81], v[152:155], v[208:211], v[78:81]
	v_mfma_f32_16x16x32_bf16 v[74:77], v[160:163], v[208:211], v[74:77]
	v_mfma_f32_16x16x32_bf16 v[118:121], v[164:167], v[180:183], v[118:121]
	v_mfma_f32_16x16x32_bf16 v[114:117], v[172:175], v[180:183], v[114:117]
	v_mfma_f32_16x16x32_bf16 v[102:105], v[164:167], v[188:191], v[102:105]
	v_mfma_f32_16x16x32_bf16 v[98:101], v[172:175], v[188:191], v[98:101]
	v_mfma_f32_16x16x32_bf16 v[86:89], v[164:167], v[196:199], v[86:89]
	v_mfma_f32_16x16x32_bf16 v[82:85], v[172:175], v[196:199], v[82:85]
	v_mfma_f32_16x16x32_bf16 v[70:73], v[164:167], v[204:207], v[70:73]
	v_mfma_f32_16x16x32_bf16 v[66:69], v[172:175], v[204:207], v[66:69]
	v_mfma_f32_16x16x32_bf16 v[118:121], v[168:171], v[184:187], v[118:121]
	v_mfma_f32_16x16x32_bf16 v[114:117], v[176:179], v[184:187], v[114:117]
	v_mfma_f32_16x16x32_bf16 v[102:105], v[168:171], v[192:195], v[102:105]
	v_mfma_f32_16x16x32_bf16 v[98:101], v[176:179], v[192:195], v[98:101]
	v_mfma_f32_16x16x32_bf16 v[86:89], v[168:171], v[200:203], v[86:89]
	v_mfma_f32_16x16x32_bf16 v[82:85], v[176:179], v[200:203], v[82:85]
	v_mfma_f32_16x16x32_bf16 v[70:73], v[168:171], v[208:211], v[70:73]
	v_mfma_f32_16x16x32_bf16 v[66:69], v[176:179], v[208:211], v[66:69]
	s_barrier
	s_add_i32 s18, s50, s27
	v_lshl_add_u64 v[212:213], v[212:213], 0, s[12:13]
	s_mov_b32 m0, s18
	ds_read_b128 v[180:183], v150 offset:49152
	ds_read_b128 v[184:187], v150 offset:50176
	ds_read_b128 v[188:191], v150 offset:51200
	ds_read_b128 v[192:195], v150 offset:52224
	ds_read_b128 v[196:199], v150 offset:53248
	ds_read_b128 v[200:203], v150 offset:54272
	ds_read_b128 v[204:207], v150 offset:55296
	ds_read_b128 v[208:211], v150 offset:56320
	global_load_lds_dwordx4 v[212:213], off
	s_add_i32 m0, s18, 0x2000
	s_add_u32 s18, s22, 0x160080
	v_lshl_add_u64 v[212:213], v[214:215], 0, s[12:13]
	s_addc_u32 s19, s23, 0
	s_add_i32 s22, s51, s27
	global_load_lds_dwordx4 v[212:213], off
	v_lshl_add_u64 v[212:213], s[18:19], 0, v[130:131]
	s_mov_b32 m0, s22
	s_nop 0
	global_load_lds_dwordx4 v[212:213], off
	v_lshl_add_u64 v[212:213], s[18:19], 0, v[132:133]
	s_add_i32 m0, s22, 0x2000
	s_nop 0
	global_load_lds_dwordx4 v[212:213], off
	v_lshl_add_u64 v[212:213], v[216:217], 0, s[12:13]
	s_mov_b32 m0, s37
	s_nop 0
	global_load_lds_dwordx4 v[212:213], off
	v_lshl_add_u64 v[212:213], v[218:219], 0, s[12:13]
	s_mov_b32 m0, s38
	s_nop 0
	global_load_lds_dwordx4 v[212:213], off
	s_waitcnt vmcnt(8)
	s_waitcnt lgkmcnt(0)
	s_barrier
	s_waitcnt lgkmcnt(0)
	v_mfma_f32_16x16x32_bf16 v[62:65], v[142:145], v[180:183], v[62:65]
	v_mfma_f32_16x16x32_bf16 v[58:61], v[156:159], v[180:183], v[58:61]
	v_mfma_f32_16x16x32_bf16 v[46:49], v[142:145], v[188:191], v[46:49]
	v_mfma_f32_16x16x32_bf16 v[42:45], v[156:159], v[188:191], v[42:45]
	v_mfma_f32_16x16x32_bf16 v[30:33], v[142:145], v[196:199], v[30:33]
	v_mfma_f32_16x16x32_bf16 v[26:29], v[156:159], v[196:199], v[26:29]
	v_mfma_f32_16x16x32_bf16 v[14:17], v[142:145], v[204:207], v[14:17]
	v_mfma_f32_16x16x32_bf16 v[10:13], v[156:159], v[204:207], v[10:13]
	v_mfma_f32_16x16x32_bf16 v[62:65], v[152:155], v[184:187], v[62:65]
	v_mfma_f32_16x16x32_bf16 v[58:61], v[160:163], v[184:187], v[58:61]
	v_mfma_f32_16x16x32_bf16 v[46:49], v[152:155], v[192:195], v[46:49]
	v_mfma_f32_16x16x32_bf16 v[42:45], v[160:163], v[192:195], v[42:45]
	v_mfma_f32_16x16x32_bf16 v[30:33], v[152:155], v[200:203], v[30:33]
	v_mfma_f32_16x16x32_bf16 v[26:29], v[160:163], v[200:203], v[26:29]
	v_mfma_f32_16x16x32_bf16 v[14:17], v[152:155], v[208:211], v[14:17]
	v_mfma_f32_16x16x32_bf16 v[10:13], v[160:163], v[208:211], v[10:13]
	v_mfma_f32_16x16x32_bf16 v[54:57], v[164:167], v[180:183], v[54:57]
	v_mfma_f32_16x16x32_bf16 v[50:53], v[172:175], v[180:183], v[50:53]
	v_mfma_f32_16x16x32_bf16 v[38:41], v[164:167], v[188:191], v[38:41]
	v_mfma_f32_16x16x32_bf16 v[34:37], v[172:175], v[188:191], v[34:37]
	v_mfma_f32_16x16x32_bf16 v[22:25], v[164:167], v[196:199], v[22:25]
	v_mfma_f32_16x16x32_bf16 v[18:21], v[172:175], v[196:199], v[18:21]
	v_mfma_f32_16x16x32_bf16 v[6:9], v[164:167], v[204:207], v[6:9]
	v_mfma_f32_16x16x32_bf16 v[2:5], v[172:175], v[204:207], v[2:5]
	v_mfma_f32_16x16x32_bf16 v[54:57], v[168:171], v[184:187], v[54:57]
	v_mfma_f32_16x16x32_bf16 v[50:53], v[176:179], v[184:187], v[50:53]
	v_mfma_f32_16x16x32_bf16 v[38:41], v[168:171], v[192:195], v[38:41]
	v_mfma_f32_16x16x32_bf16 v[34:37], v[176:179], v[192:195], v[34:37]
	v_mfma_f32_16x16x32_bf16 v[22:25], v[168:171], v[200:203], v[22:25]
	v_mfma_f32_16x16x32_bf16 v[18:21], v[176:179], v[200:203], v[18:21]
	v_mfma_f32_16x16x32_bf16 v[6:9], v[168:171], v[208:211], v[6:9]
	v_mfma_f32_16x16x32_bf16 v[2:5], v[176:179], v[208:211], v[2:5]
	s_barrier
	s_add_i32 s49, s49, 2
	s_add_u32 s47, s47, 0x100
	s_addc_u32 s48, s48, 0
	s_cmpk_gt_u32 s49, 0x55
	s_mov_b64 s[18:19], s[20:21]
	s_cbranch_scc0 .LBB0_3378
	s_and_b64 vcc, exec, s[14:15]
	s_cbranch_vccz .LBB0_3381
	s_barrier

.LBB0_3426:
	ds_read_b128 v[140:143], v181
	ds_read_b128 v[144:147], v181 offset:1024
	ds_read_b128 v[148:151], v181 offset:2048
	ds_read_b128 v[152:155], v181 offset:3072
	ds_read_b128 v[156:159], v182
	ds_read_b128 v[160:163], v182 offset:1024
	ds_read_b128 v[164:167], v182 offset:2048
	ds_read_b128 v[168:171], v182 offset:3072
	s_add_u32 s6, s40, 0x100
	s_addc_u32 s7, s41, 0
	s_cmpk_eq_i32 s68, 0x54
	s_cselect_b32 s45, s37, s7
	s_cselect_b32 s44, s36, s6
	s_cselect_b32 s43, s39, s67
	s_cselect_b32 s42, s38, s66
	v_lshl_add_u64 v[176:177], s[40:41], 0, v[132:133]
	s_add_i32 m0, s23, 0xc000
	ds_read_b128 v[172:175], v183
	ds_read_b128 v[186:189], v183 offset:1024
	ds_read_b128 v[190:193], v183 offset:2048
	ds_read_b128 v[194:197], v183 offset:3072
	ds_read_b128 v[198:201], v183 offset:4096
	ds_read_b128 v[202:205], v183 offset:5120
	ds_read_b128 v[206:209], v183 offset:6144
	ds_read_b128 v[210:213], v183 offset:7168
	global_load_lds_dwordx4 v[176:177], off
	v_lshl_add_u64 v[176:177], s[40:41], 0, v[134:135]
	s_add_i32 m0, s23, 0xe000
	s_nop 0
	global_load_lds_dwordx4 v[176:177], off
	s_waitcnt vmcnt(8)
	s_waitcnt lgkmcnt(0)
	s_barrier
	s_waitcnt lgkmcnt(0)
	v_mfma_f32_16x16x32_bf16 v[124:127], v[140:143], v[172:175], v[124:127]
	v_mfma_f32_16x16x32_bf16 v[120:123], v[148:151], v[172:175], v[120:123]
	v_mfma_f32_16x16x32_bf16 v[108:111], v[140:143], v[190:193], v[108:111]
	v_mfma_f32_16x16x32_bf16 v[104:107], v[148:151], v[190:193], v[104:107]
	v_mfma_f32_16x16x32_bf16 v[92:95], v[140:143], v[198:201], v[92:95]
	v_mfma_f32_16x16x32_bf16 v[88:91], v[148:151], v[198:201], v[88:91]
	v_mfma_f32_16x16x32_bf16 v[76:79], v[140:143], v[206:209], v[76:79]
	v_mfma_f32_16x16x32_bf16 v[72:75], v[148:151], v[206:209], v[72:75]
	v_mfma_f32_16x16x32_bf16 v[124:127], v[144:147], v[186:189], v[124:127]
	v_mfma_f32_16x16x32_bf16 v[120:123], v[152:155], v[186:189], v[120:123]
	v_mfma_f32_16x16x32_bf16 v[108:111], v[144:147], v[194:197], v[108:111]
	v_mfma_f32_16x16x32_bf16 v[104:107], v[152:155], v[194:197], v[104:107]
	v_mfma_f32_16x16x32_bf16 v[92:95], v[144:147], v[202:205], v[92:95]
	v_mfma_f32_16x16x32_bf16 v[88:91], v[152:155], v[202:205], v[88:91]
	v_mfma_f32_16x16x32_bf16 v[76:79], v[144:147], v[210:213], v[76:79]
	v_mfma_f32_16x16x32_bf16 v[72:75], v[152:155], v[210:213], v[72:75]
	v_mfma_f32_16x16x32_bf16 v[116:119], v[156:159], v[172:175], v[116:119]
	v_mfma_f32_16x16x32_bf16 v[112:115], v[164:167], v[172:175], v[112:115]
	v_mfma_f32_16x16x32_bf16 v[100:103], v[156:159], v[190:193], v[100:103]
	v_mfma_f32_16x16x32_bf16 v[96:99], v[164:167], v[190:193], v[96:99]
	v_mfma_f32_16x16x32_bf16 v[84:87], v[156:159], v[198:201], v[84:87]
	v_mfma_f32_16x16x32_bf16 v[80:83], v[164:167], v[198:201], v[80:83]
	v_mfma_f32_16x16x32_bf16 v[68:71], v[156:159], v[206:209], v[68:71]
	v_mfma_f32_16x16x32_bf16 v[64:67], v[164:167], v[206:209], v[64:67]
	v_mfma_f32_16x16x32_bf16 v[116:119], v[160:163], v[186:189], v[116:119]
	v_mfma_f32_16x16x32_bf16 v[112:115], v[168:171], v[186:189], v[112:115]
	v_mfma_f32_16x16x32_bf16 v[100:103], v[160:163], v[194:197], v[100:103]
	v_mfma_f32_16x16x32_bf16 v[96:99], v[168:171], v[194:197], v[96:99]
	v_mfma_f32_16x16x32_bf16 v[84:87], v[160:163], v[202:205], v[84:87]
	v_mfma_f32_16x16x32_bf16 v[80:83], v[168:171], v[202:205], v[80:83]
	v_mfma_f32_16x16x32_bf16 v[68:71], v[160:163], v[210:213], v[68:71]
	v_mfma_f32_16x16x32_bf16 v[64:67], v[168:171], v[210:213], v[64:67]
	s_barrier
	s_add_i32 s40, s59, s21
	v_lshl_add_u64 v[176:177], s[42:43], 0, v[128:129]
	s_mov_b32 m0, s40
	ds_read_b128 v[172:175], v183 offset:16384
	ds_read_b128 v[186:189], v183 offset:17408
	ds_read_b128 v[190:193], v183 offset:18432
	ds_read_b128 v[194:197], v183 offset:19456
	ds_read_b128 v[198:201], v183 offset:20480
	ds_read_b128 v[202:205], v183 offset:21504
	ds_read_b128 v[206:209], v183 offset:22528
	ds_read_b128 v[210:213], v183 offset:23552
	global_load_lds_dwordx4 v[176:177], off
	s_add_i32 m0, s40, 0x2000
	s_add_u32 s40, s42, 0x160000
	v_lshl_add_u64 v[214:215], s[42:43], 0, v[130:131]
	s_addc_u32 s41, s43, 0
	s_add_i32 s69, s60, s21
	global_load_lds_dwordx4 v[214:215], off
	v_lshl_add_u64 v[216:217], s[40:41], 0, v[128:129]
	s_mov_b32 m0, s69
	v_lshl_add_u64 v[218:219], s[44:45], 0, v[130:131]
	global_load_lds_dwordx4 v[216:217], off
	v_lshl_add_u64 v[216:217], s[40:41], 0, v[130:131]
	s_add_i32 m0, s69, 0x2000
	s_nop 0
	global_load_lds_dwordx4 v[216:217], off
	v_lshl_add_u64 v[216:217], s[44:45], 0, v[128:129]
	s_mov_b32 m0, s23
	s_nop 0
	global_load_lds_dwordx4 v[216:217], off
	s_mov_b32 m0, s47
	s_nop 0
	global_load_lds_dwordx4 v[218:219], off
	s_waitcnt vmcnt(8)
	s_waitcnt lgkmcnt(0)
	s_barrier
	s_waitcnt lgkmcnt(0)
	v_mfma_f32_16x16x32_bf16 v[60:63], v[140:143], v[172:175], v[60:63]
	v_mfma_f32_16x16x32_bf16 v[56:59], v[148:151], v[172:175], v[56:59]
	v_mfma_f32_16x16x32_bf16 v[44:47], v[140:143], v[190:193], v[44:47]
	v_mfma_f32_16x16x32_bf16 v[40:43], v[148:151], v[190:193], v[40:43]
	v_mfma_f32_16x16x32_bf16 v[28:31], v[140:143], v[198:201], v[28:31]
	v_mfma_f32_16x16x32_bf16 v[24:27], v[148:151], v[198:201], v[24:27]
	v_mfma_f32_16x16x32_bf16 v[12:15], v[140:143], v[206:209], v[12:15]
	v_mfma_f32_16x16x32_bf16 v[8:11], v[148:151], v[206:209], v[8:11]
	v_mfma_f32_16x16x32_bf16 v[60:63], v[144:147], v[186:189], v[60:63]
	v_mfma_f32_16x16x32_bf16 v[56:59], v[152:155], v[186:189], v[56:59]
	v_mfma_f32_16x16x32_bf16 v[44:47], v[144:147], v[194:197], v[44:47]
	v_mfma_f32_16x16x32_bf16 v[40:43], v[152:155], v[194:197], v[40:43]
	v_mfma_f32_16x16x32_bf16 v[28:31], v[144:147], v[202:205], v[28:31]
	v_mfma_f32_16x16x32_bf16 v[24:27], v[152:155], v[202:205], v[24:27]
	v_mfma_f32_16x16x32_bf16 v[12:15], v[144:147], v[210:213], v[12:15]
	v_mfma_f32_16x16x32_bf16 v[8:11], v[152:155], v[210:213], v[8:11]
	v_mfma_f32_16x16x32_bf16 v[52:55], v[156:159], v[172:175], v[52:55]
	v_mfma_f32_16x16x32_bf16 v[48:51], v[164:167], v[172:175], v[48:51]
	v_mfma_f32_16x16x32_bf16 v[36:39], v[156:159], v[190:193], v[36:39]
	v_mfma_f32_16x16x32_bf16 v[32:35], v[164:167], v[190:193], v[32:35]
	v_mfma_f32_16x16x32_bf16 v[20:23], v[156:159], v[198:201], v[20:23]
	v_mfma_f32_16x16x32_bf16 v[16:19], v[164:167], v[198:201], v[16:19]
	v_mfma_f32_16x16x32_bf16 v[4:7], v[156:159], v[206:209], v[4:7]
	v_mfma_f32_16x16x32_bf16 v[0:3], v[164:167], v[206:209], v[0:3]
	v_mfma_f32_16x16x32_bf16 v[52:55], v[160:163], v[186:189], v[52:55]
	v_mfma_f32_16x16x32_bf16 v[48:51], v[168:171], v[186:189], v[48:51]
	v_mfma_f32_16x16x32_bf16 v[36:39], v[160:163], v[194:197], v[36:39]
	v_mfma_f32_16x16x32_bf16 v[32:35], v[168:171], v[194:197], v[32:35]
	v_mfma_f32_16x16x32_bf16 v[20:23], v[160:163], v[202:205], v[20:23]
	v_mfma_f32_16x16x32_bf16 v[16:19], v[168:171], v[202:205], v[16:19]
	v_mfma_f32_16x16x32_bf16 v[4:7], v[160:163], v[210:213], v[4:7]
	v_mfma_f32_16x16x32_bf16 v[0:3], v[168:171], v[210:213], v[0:3]
	s_barrier
	s_add_i32 s69, 0, 0x18000
	s_add_i32 s70, 0, 0x1c000
	v_add_u32_e32 v152, s69, v180
	v_add_u32_e32 v168, s70, v180
	ds_read_b128 v[140:143], v152
	ds_read_b128 v[144:147], v152 offset:1024
	ds_read_b128 v[148:151], v152 offset:2048
	ds_read_b128 v[152:155], v152 offset:3072
	ds_read_b128 v[156:159], v168
	ds_read_b128 v[160:163], v168 offset:1024
	ds_read_b128 v[164:167], v168 offset:2048
	ds_read_b128 v[168:171], v168 offset:3072
	s_add_u32 s40, s44, 0x160000
	s_addc_u32 s41, s45, 0
	s_mov_b32 m0, s48
	v_lshl_add_u64 v[220:221], s[40:41], 0, v[128:129]
	ds_read_b128 v[172:175], v183 offset:32768
	ds_read_b128 v[186:189], v183 offset:33792
	ds_read_b128 v[190:193], v183 offset:34816
	ds_read_b128 v[194:197], v183 offset:35840
	ds_read_b128 v[198:201], v183 offset:36864
	ds_read_b128 v[202:205], v183 offset:37888
	ds_read_b128 v[206:209], v183 offset:38912
	ds_read_b128 v[210:213], v183 offset:39936
	global_load_lds_dwordx4 v[220:221], off
	v_lshl_add_u64 v[220:221], s[40:41], 0, v[130:131]
	s_mov_b32 m0, s49
	s_nop 0
	global_load_lds_dwordx4 v[220:221], off
	s_waitcnt vmcnt(8)
	s_waitcnt lgkmcnt(0)
	s_barrier
	s_waitcnt lgkmcnt(0)
	v_mfma_f32_16x16x32_bf16 v[124:127], v[140:143], v[172:175], v[124:127]
	v_mfma_f32_16x16x32_bf16 v[120:123], v[148:151], v[172:175], v[120:123]
	v_mfma_f32_16x16x32_bf16 v[108:111], v[140:143], v[190:193], v[108:111]
	v_mfma_f32_16x16x32_bf16 v[104:107], v[148:151], v[190:193], v[104:107]
	v_mfma_f32_16x16x32_bf16 v[92:95], v[140:143], v[198:201], v[92:95]
	v_mfma_f32_16x16x32_bf16 v[88:91], v[148:151], v[198:201], v[88:91]
	v_mfma_f32_16x16x32_bf16 v[76:79], v[140:143], v[206:209], v[76:79]
	v_mfma_f32_16x16x32_bf16 v[72:75], v[148:151], v[206:209], v[72:75]
	v_mfma_f32_16x16x32_bf16 v[124:127], v[144:147], v[186:189], v[124:127]
	v_mfma_f32_16x16x32_bf16 v[120:123], v[152:155], v[186:189], v[120:123]
	v_mfma_f32_16x16x32_bf16 v[108:111], v[144:147], v[194:197], v[108:111]
	v_mfma_f32_16x16x32_bf16 v[104:107], v[152:155], v[194:197], v[104:107]
	v_mfma_f32_16x16x32_bf16 v[92:95], v[144:147], v[202:205], v[92:95]
	v_mfma_f32_16x16x32_bf16 v[88:91], v[152:155], v[202:205], v[88:91]
	v_mfma_f32_16x16x32_bf16 v[76:79], v[144:147], v[210:213], v[76:79]
	v_mfma_f32_16x16x32_bf16 v[72:75], v[152:155], v[210:213], v[72:75]
	v_mfma_f32_16x16x32_bf16 v[116:119], v[156:159], v[172:175], v[116:119]
	v_mfma_f32_16x16x32_bf16 v[112:115], v[164:167], v[172:175], v[112:115]
	v_mfma_f32_16x16x32_bf16 v[100:103], v[156:159], v[190:193], v[100:103]
	v_mfma_f32_16x16x32_bf16 v[96:99], v[164:167], v[190:193], v[96:99]
	v_mfma_f32_16x16x32_bf16 v[84:87], v[156:159], v[198:201], v[84:87]
	v_mfma_f32_16x16x32_bf16 v[80:83], v[164:167], v[198:201], v[80:83]
	v_mfma_f32_16x16x32_bf16 v[68:71], v[156:159], v[206:209], v[68:71]
	v_mfma_f32_16x16x32_bf16 v[64:67], v[164:167], v[206:209], v[64:67]
	v_mfma_f32_16x16x32_bf16 v[116:119], v[160:163], v[186:189], v[116:119]
	v_mfma_f32_16x16x32_bf16 v[112:115], v[168:171], v[186:189], v[112:115]
	v_mfma_f32_16x16x32_bf16 v[100:103], v[160:163], v[194:197], v[100:103]
	v_mfma_f32_16x16x32_bf16 v[96:99], v[168:171], v[194:197], v[96:99]
	v_mfma_f32_16x16x32_bf16 v[84:87], v[160:163], v[202:205], v[84:87]
	v_mfma_f32_16x16x32_bf16 v[80:83], v[168:171], v[202:205], v[80:83]
	v_mfma_f32_16x16x32_bf16 v[68:71], v[160:163], v[210:213], v[68:71]
	v_mfma_f32_16x16x32_bf16 v[64:67], v[168:171], v[210:213], v[64:67]
	s_barrier
	s_add_i32 s40, s69, s21
	v_lshl_add_u64 v[176:177], v[176:177], 0, s[14:15]
	s_mov_b32 m0, s40
	ds_read_b128 v[172:175], v183 offset:49152
	ds_read_b128 v[186:189], v183 offset:50176
	ds_read_b128 v[190:193], v183 offset:51200
	ds_read_b128 v[194:197], v183 offset:52224
	ds_read_b128 v[198:201], v183 offset:53248
	ds_read_b128 v[202:205], v183 offset:54272
	ds_read_b128 v[206:209], v183 offset:55296
	ds_read_b128 v[210:213], v183 offset:56320
	global_load_lds_dwordx4 v[176:177], off
	s_add_i32 m0, s40, 0x2000
	s_add_u32 s40, s42, 0x160080
	v_lshl_add_u64 v[176:177], v[214:215], 0, s[14:15]
	s_addc_u32 s41, s43, 0
	s_add_i32 s42, s70, s21
	global_load_lds_dwordx4 v[176:177], off
	v_lshl_add_u64 v[176:177], s[40:41], 0, v[128:129]
	s_mov_b32 m0, s42
	s_nop 0
	global_load_lds_dwordx4 v[176:177], off
	v_lshl_add_u64 v[176:177], s[40:41], 0, v[130:131]
	s_add_i32 m0, s42, 0x2000
	s_nop 0
	global_load_lds_dwordx4 v[176:177], off
	v_lshl_add_u64 v[176:177], v[216:217], 0, s[14:15]
	s_mov_b32 m0, s56
	s_nop 0
	global_load_lds_dwordx4 v[176:177], off
	v_lshl_add_u64 v[176:177], v[218:219], 0, s[14:15]
	s_mov_b32 m0, s57
	s_nop 0
	global_load_lds_dwordx4 v[176:177], off
	s_waitcnt vmcnt(8)
	s_waitcnt lgkmcnt(0)
	s_barrier
	s_waitcnt lgkmcnt(0)
	v_mfma_f32_16x16x32_bf16 v[60:63], v[140:143], v[172:175], v[60:63]
	v_mfma_f32_16x16x32_bf16 v[56:59], v[148:151], v[172:175], v[56:59]
	v_mfma_f32_16x16x32_bf16 v[44:47], v[140:143], v[190:193], v[44:47]
	v_mfma_f32_16x16x32_bf16 v[40:43], v[148:151], v[190:193], v[40:43]
	v_mfma_f32_16x16x32_bf16 v[28:31], v[140:143], v[198:201], v[28:31]
	v_mfma_f32_16x16x32_bf16 v[24:27], v[148:151], v[198:201], v[24:27]
	v_mfma_f32_16x16x32_bf16 v[12:15], v[140:143], v[206:209], v[12:15]
	v_mfma_f32_16x16x32_bf16 v[8:11], v[148:151], v[206:209], v[8:11]
	v_mfma_f32_16x16x32_bf16 v[60:63], v[144:147], v[186:189], v[60:63]
	v_mfma_f32_16x16x32_bf16 v[56:59], v[152:155], v[186:189], v[56:59]
	v_mfma_f32_16x16x32_bf16 v[44:47], v[144:147], v[194:197], v[44:47]
	v_mfma_f32_16x16x32_bf16 v[40:43], v[152:155], v[194:197], v[40:43]
	v_mfma_f32_16x16x32_bf16 v[28:31], v[144:147], v[202:205], v[28:31]
	v_mfma_f32_16x16x32_bf16 v[24:27], v[152:155], v[202:205], v[24:27]
	v_mfma_f32_16x16x32_bf16 v[12:15], v[144:147], v[210:213], v[12:15]
	v_mfma_f32_16x16x32_bf16 v[8:11], v[152:155], v[210:213], v[8:11]
	v_mfma_f32_16x16x32_bf16 v[52:55], v[156:159], v[172:175], v[52:55]
	v_mfma_f32_16x16x32_bf16 v[48:51], v[164:167], v[172:175], v[48:51]
	v_mfma_f32_16x16x32_bf16 v[36:39], v[156:159], v[190:193], v[36:39]
	v_mfma_f32_16x16x32_bf16 v[32:35], v[164:167], v[190:193], v[32:35]
	v_mfma_f32_16x16x32_bf16 v[20:23], v[156:159], v[198:201], v[20:23]
	v_mfma_f32_16x16x32_bf16 v[16:19], v[164:167], v[198:201], v[16:19]
	v_mfma_f32_16x16x32_bf16 v[4:7], v[156:159], v[206:209], v[4:7]
	v_mfma_f32_16x16x32_bf16 v[0:3], v[164:167], v[206:209], v[0:3]
	v_mfma_f32_16x16x32_bf16 v[52:55], v[160:163], v[186:189], v[52:55]
	v_mfma_f32_16x16x32_bf16 v[48:51], v[168:171], v[186:189], v[48:51]
	v_mfma_f32_16x16x32_bf16 v[36:39], v[160:163], v[194:197], v[36:39]
	v_mfma_f32_16x16x32_bf16 v[32:35], v[168:171], v[194:197], v[32:35]
	v_mfma_f32_16x16x32_bf16 v[20:23], v[160:163], v[202:205], v[20:23]
	v_mfma_f32_16x16x32_bf16 v[16:19], v[168:171], v[202:205], v[16:19]
	v_mfma_f32_16x16x32_bf16 v[4:7], v[160:163], v[210:213], v[4:7]
	v_mfma_f32_16x16x32_bf16 v[0:3], v[168:171], v[210:213], v[0:3]
	s_barrier
	s_add_i32 s68, s68, 2
	s_add_u32 s66, s66, 0x100
	s_addc_u32 s67, s67, 0
	s_cmpk_gt_u32 s68, 0x55
	s_mov_b64 s[40:41], s[6:7]
	s_cbranch_scc0 .LBB0_3426
	s_and_b64 vcc, exec, s[18:19]
	s_cbranch_vccz .LBB0_3429
	s_barrier
